# combination on top of m7: hoisted LDS fragment bases, peeled first K-iteration (no accumulator zeroing), one-deep ds_read pipelining of serialized ds_read-wait-mfma chains in the mixer phase, counted
# speedup vs baseline: 1.0159x; 1.0116x over previous
; #define PG8_STAGE(bufoff, gbase, voff) do { _Pragma("unroll") for (int _i = 0; _i < 2; ++_i) \
;         __builtin_amdgcn_global_load_lds((const unsigned*)((const char*)(gbase) + (voff)[_i]), (LAS unsigned*)(lds + (bufoff) + ldsw + _i * 8192), 16, 0, 0); } while (0)
; #define PG8_LDA(dst, b, h) do { _Pragma("unroll") for (int m = 0; m < 4; ++m) _Pragma("unroll") for (int k = 0; k < 2; ++k) dst[m][k] = *(const LAS bf16x8*)(lds + PG8_SA(b, h) + aoff + m * 2048 + k * 1024); } while (0)
; #define PG8_LDB(dst, b, h) do { _Pragma("unroll") for (int n = 0; n < 2; ++n) _Pragma("unroll") for (int k = 0; k < 2; ++k) dst[n][k] = *(const LAS bf16x8*)(lds + PG8_SB(b, h) + boff + n * 2048 + k * 1024); } while (0)
; #define PG8_MMA(ai, bj, At, Bt) do { __builtin_amdgcn_s_setprio(1); _Pragma("unroll") for (int m = 0; m < 4; ++m) _Pragma("unroll") for (int n = 0; n < 2; ++n) _Pragma("unroll") for (int k = 0; k < 2; ++k) \
;         acc[ai][bj][m][n] = __builtin_amdgcn_mfma_f32_16x16x32_bf16(Bt[n][k], At[m][k], acc[ai][bj][m][n], 0, 0, 0); __builtin_amdgcn_s_setprio(0); } while (0)
; #define PG8_WAIT_V(n) asm volatile("s_waitcnt vmcnt(" #n ")" ::: "memory")
; #define PG8_WAIT_L(n) asm volatile("s_waitcnt lgkmcnt(" #n ")" ::: "memory")
; #define PG8_BAR __builtin_amdgcn_s_barrier()
; #define PG8_SCHED __builtin_amdgcn_sched_barrier(0)
; __device__ __forceinline__ void gemm_phase(LAS unsigned char* lds, const GP p, const int tid) {
;     ...
;     f32x4 acc[2][2][4][2];
; #pragma unroll
;     for (int a = 0; a < 2; ++a)
; #pragma unroll
;         for (int b = 0; b < 2; ++b)
; #pragma unroll
;             for (int m = 0; m < 4; ++m)
; #pragma unroll
;                 for (int n = 0; n < 2; ++n) acc[a][b][m][n] = (f32x4){0.f, 0.f, 0.f, 0.f};
;     ...
;             PG8_LDB(B0, 0, 0); PG8_LDB(B1, 0, 1); PG8_SCHED; PG8_LDA(At, 0, 0); PG8_STAGE(PG8_SA(1, 1), a1 + hstep, voffA);
;             PG8_WAIT_V(8); PG8_WAIT_L(0); PG8_BAR; PG8_MMA(0, 0, At, B0); PG8_MMA(0, 1, At, B1); PG8_BAR; PG8_SCHED;
;             PG8_LDA(At, 0, 1); PG8_STAGE(PG8_SB(0, 0), b2, voffB); PG8_STAGE(PG8_SB(0, 1), b2 + hstep, voffB); PG8_STAGE(PG8_SA(0, 0), a2, voffA);
;             PG8_WAIT_V(8); PG8_WAIT_L(0); PG8_BAR; PG8_MMA(1, 0, At, B0); PG8_MMA(1, 1, At, B1); PG8_BAR; PG8_SCHED;
.Lpeel_body:
	s_add_i32 s98, s98, 2
	s_add_u32 s43, s82, 0x80
	s_addc_u32 s99, s83, 0
	s_and_b64 s[86:87], s[84:85], exec
	s_cselect_b32 s87, s77, s99
	s_cselect_b32 s86, s76, s43
	s_add_i32 s43, 0, 0x10000
	s_and_b64 s[84:85], s[84:85], exec
	s_cselect_b32 s85, s79, s91
	s_cselect_b32 s84, s78, s81
	s_add_i32 s99, 0, 0x14000
	ds_read_b128 v[130:133], v238
	ds_read_b128 v[134:137], v238 offset:1024
	ds_read_b128 v[138:141], v238 offset:2048
	ds_read_b128 v[180:183], v238 offset:3072
	ds_read_b128 v[184:187], v239
	ds_read_b128 v[188:191], v239 offset:1024
	ds_read_b128 v[192:195], v239 offset:2048
	ds_read_b128 v[196:199], v239 offset:3072
	s_add_i32 m0, s53, 0xc000
	ds_read_b128 v[200:203], v167
	ds_read_b128 v[204:207], v167 offset:1024
	ds_read_b128 v[208:211], v167 offset:2048
	ds_read_b128 v[218:221], v167 offset:3072
	ds_read_b128 v[222:225], v167 offset:4096
	ds_read_b128 v[226:229], v167 offset:5120
	ds_read_b128 v[230:233], v167 offset:6144
	ds_read_b128 v[234:237], v167 offset:7168
	global_load_lds_dwordx4 v160, s[82:83]
	s_add_i32 m0, s53, 0xe000
	s_nop 0
	global_load_lds_dwordx4 v162, s[82:83]
	s_waitcnt vmcnt(8)
	s_waitcnt lgkmcnt(0)
	s_barrier
	s_setprio 1
	s_waitcnt lgkmcnt(0)
	v_mfma_f32_16x16x32_bf16 v[124:127], v[130:133], v[200:203], 0
	v_mfma_f32_16x16x32_bf16 v[120:123], v[138:141], v[200:203], 0
	v_mfma_f32_16x16x32_bf16 v[108:111], v[130:133], v[208:211], 0
	v_mfma_f32_16x16x32_bf16 v[104:107], v[138:141], v[208:211], 0
	v_mfma_f32_16x16x32_bf16 v[92:95], v[130:133], v[222:225], 0
	v_mfma_f32_16x16x32_bf16 v[88:91], v[138:141], v[222:225], 0
	v_mfma_f32_16x16x32_bf16 v[76:79], v[130:133], v[230:233], 0
	v_mfma_f32_16x16x32_bf16 v[72:75], v[138:141], v[230:233], 0
	v_mfma_f32_16x16x32_bf16 v[124:127], v[134:137], v[204:207], v[124:127]
	v_mfma_f32_16x16x32_bf16 v[120:123], v[180:183], v[204:207], v[120:123]
	v_mfma_f32_16x16x32_bf16 v[108:111], v[134:137], v[218:221], v[108:111]
	v_mfma_f32_16x16x32_bf16 v[104:107], v[180:183], v[218:221], v[104:107]
	v_mfma_f32_16x16x32_bf16 v[92:95], v[134:137], v[226:229], v[92:95]
	v_mfma_f32_16x16x32_bf16 v[88:91], v[180:183], v[226:229], v[88:91]
	v_mfma_f32_16x16x32_bf16 v[76:79], v[134:137], v[234:237], v[76:79]
	v_mfma_f32_16x16x32_bf16 v[72:75], v[180:183], v[234:237], v[72:75]
	s_setprio 0
	s_setprio 1
	v_mfma_f32_16x16x32_bf16 v[116:119], v[184:187], v[200:203], 0
	v_mfma_f32_16x16x32_bf16 v[112:115], v[192:195], v[200:203], 0
	v_mfma_f32_16x16x32_bf16 v[100:103], v[184:187], v[208:211], 0
	v_mfma_f32_16x16x32_bf16 v[96:99], v[192:195], v[208:211], 0
	v_mfma_f32_16x16x32_bf16 v[84:87], v[184:187], v[222:225], 0
	v_mfma_f32_16x16x32_bf16 v[80:83], v[192:195], v[222:225], 0
	v_mfma_f32_16x16x32_bf16 v[68:71], v[184:187], v[230:233], 0
	v_mfma_f32_16x16x32_bf16 v[64:67], v[192:195], v[230:233], 0
	v_mfma_f32_16x16x32_bf16 v[116:119], v[188:191], v[204:207], v[116:119]
	v_mfma_f32_16x16x32_bf16 v[112:115], v[196:199], v[204:207], v[112:115]
	v_mfma_f32_16x16x32_bf16 v[100:103], v[188:191], v[218:221], v[100:103]
	v_mfma_f32_16x16x32_bf16 v[96:99], v[196:199], v[218:221], v[96:99]
	v_mfma_f32_16x16x32_bf16 v[84:87], v[188:191], v[226:229], v[84:87]
	v_mfma_f32_16x16x32_bf16 v[80:83], v[196:199], v[226:229], v[80:83]
	v_mfma_f32_16x16x32_bf16 v[68:71], v[188:191], v[234:237], v[68:71]
	v_mfma_f32_16x16x32_bf16 v[64:67], v[196:199], v[234:237], v[64:67]
	s_setprio 0
	s_barrier
	s_add_i32 s43, s43, s52
	s_mov_b64 s[100:101], s[84:85]
	s_mov_b32 m0, s43
	ds_read_b128 v[200:203], v167 offset:16384
	ds_read_b128 v[204:207], v167 offset:17408
	ds_read_b128 v[208:211], v167 offset:18432
	ds_read_b128 v[218:221], v167 offset:19456
	ds_read_b128 v[222:225], v167 offset:20480
	ds_read_b128 v[226:229], v167 offset:21504
	ds_read_b128 v[230:233], v167 offset:22528
	ds_read_b128 v[234:237], v167 offset:23552
	global_load_lds_dwordx4 v148, s[84:85]
	s_add_i32 m0, s43, 0x2000
	s_add_i32 s43, s99, s52
	global_load_lds_dwordx4 v152, s[84:85]
	s_add_u32 s84, s84, s74
	s_addc_u32 s85, s85, 0
	s_mov_b32 m0, s43
	s_nop 0
	global_load_lds_dwordx4 v148, s[84:85]
	s_add_i32 m0, s43, 0x2000
	s_nop 0
	global_load_lds_dwordx4 v152, s[84:85]
	s_mov_b32 m0, s53
	s_nop 0
	global_load_lds_dwordx4 v146, s[86:87]
	s_mov_b32 m0, s54
	s_nop 0
	global_load_lds_dwordx4 v150, s[86:87]
	s_waitcnt vmcnt(8)
	s_waitcnt lgkmcnt(0)
	s_barrier
	s_setprio 1
	s_waitcnt lgkmcnt(0)
	v_mfma_f32_16x16x32_bf16 v[60:63], v[130:133], v[200:203], 0
	v_mfma_f32_16x16x32_bf16 v[56:59], v[138:141], v[200:203], 0
	v_mfma_f32_16x16x32_bf16 v[44:47], v[130:133], v[208:211], 0
	v_mfma_f32_16x16x32_bf16 v[40:43], v[138:141], v[208:211], 0
	v_mfma_f32_16x16x32_bf16 v[28:31], v[130:133], v[222:225], 0
	v_mfma_f32_16x16x32_bf16 v[24:27], v[138:141], v[222:225], 0
	v_mfma_f32_16x16x32_bf16 v[12:15], v[130:133], v[230:233], 0
	v_mfma_f32_16x16x32_bf16 v[8:11], v[138:141], v[230:233], 0
	v_mfma_f32_16x16x32_bf16 v[60:63], v[134:137], v[204:207], v[60:63]
	v_mfma_f32_16x16x32_bf16 v[56:59], v[180:183], v[204:207], v[56:59]
	v_mfma_f32_16x16x32_bf16 v[44:47], v[134:137], v[218:221], v[44:47]
	v_mfma_f32_16x16x32_bf16 v[40:43], v[180:183], v[218:221], v[40:43]
	v_mfma_f32_16x16x32_bf16 v[28:31], v[134:137], v[226:229], v[28:31]
	v_mfma_f32_16x16x32_bf16 v[24:27], v[180:183], v[226:229], v[24:27]
	v_mfma_f32_16x16x32_bf16 v[12:15], v[134:137], v[234:237], v[12:15]
	v_mfma_f32_16x16x32_bf16 v[8:11], v[180:183], v[234:237], v[8:11]
	s_setprio 0
	s_setprio 1
	v_mfma_f32_16x16x32_bf16 v[52:55], v[184:187], v[200:203], 0
	v_mfma_f32_16x16x32_bf16 v[48:51], v[192:195], v[200:203], 0
	v_mfma_f32_16x16x32_bf16 v[36:39], v[184:187], v[208:211], 0
	v_mfma_f32_16x16x32_bf16 v[32:35], v[192:195], v[208:211], 0
	v_mfma_f32_16x16x32_bf16 v[20:23], v[184:187], v[222:225], 0
	v_mfma_f32_16x16x32_bf16 v[16:19], v[192:195], v[222:225], 0
	v_mfma_f32_16x16x32_bf16 v[4:7], v[184:187], v[230:233], 0
	v_mfma_f32_16x16x32_bf16 v[0:3], v[192:195], v[230:233], 0
	v_mfma_f32_16x16x32_bf16 v[52:55], v[188:191], v[204:207], v[52:55]
	v_mfma_f32_16x16x32_bf16 v[48:51], v[196:199], v[204:207], v[48:51]
	v_mfma_f32_16x16x32_bf16 v[36:39], v[188:191], v[218:221], v[36:39]
	v_mfma_f32_16x16x32_bf16 v[32:35], v[196:199], v[218:221], v[32:35]
	v_mfma_f32_16x16x32_bf16 v[20:23], v[188:191], v[226:229], v[20:23]
	v_mfma_f32_16x16x32_bf16 v[16:19], v[196:199], v[226:229], v[16:19]
	v_mfma_f32_16x16x32_bf16 v[4:7], v[188:191], v[234:237], v[4:7]
	v_mfma_f32_16x16x32_bf16 v[0:3], v[196:199], v[234:237], v[0:3]
	s_setprio 0
	s_barrier
; #define PG8_STAGE(bufoff, gbase, voff) do { _Pragma("unroll") for (int _i = 0; _i < 2; ++_i) \
;         __builtin_amdgcn_global_load_lds((const unsigned*)((const char*)(gbase) + (voff)[_i]), (LAS unsigned*)(lds + (bufoff) + ldsw + _i * 8192), 16, 0, 0); } while (0)
; #define PG8_LDA(dst, b, h) do { _Pragma("unroll") for (int m = 0; m < 4; ++m) _Pragma("unroll") for (int k = 0; k < 2; ++k) dst[m][k] = *(const LAS bf16x8*)(lds + PG8_SA(b, h) + aoff + m * 2048 + k * 1024); } while (0)
; #define PG8_LDB(dst, b, h) do { _Pragma("unroll") for (int n = 0; n < 2; ++n) _Pragma("unroll") for (int k = 0; k < 2; ++k) dst[n][k] = *(const LAS bf16x8*)(lds + PG8_SB(b, h) + boff + n * 2048 + k * 1024); } while (0)
; #define PG8_MMA(ai, bj, At, Bt) do { __builtin_amdgcn_s_setprio(1); _Pragma("unroll") for (int m = 0; m < 4; ++m) _Pragma("unroll") for (int n = 0; n < 2; ++n) _Pragma("unroll") for (int k = 0; k < 2; ++k) \
;         acc[ai][bj][m][n] = __builtin_amdgcn_mfma_f32_16x16x32_bf16(Bt[n][k], At[m][k], acc[ai][bj][m][n], 0, 0, 0); __builtin_amdgcn_s_setprio(0); } while (0)
; #define PG8_WAIT_V(n) asm volatile("s_waitcnt vmcnt(" #n ")" ::: "memory")
; #define PG8_WAIT_L(n) asm volatile("s_waitcnt lgkmcnt(" #n ")" ::: "memory")
; #define PG8_BAR __builtin_amdgcn_s_barrier()
; #define PG8_SCHED __builtin_amdgcn_sched_barrier(0)
; __device__ __forceinline__ void gemm_phase(LAS unsigned char* lds, const GP p, const int tid) {
;     ...
;             PG8_LDB(B0, 1, 0); PG8_LDB(B1, 1, 1); PG8_SCHED; PG8_LDA(At, 1, 0); PG8_STAGE(PG8_SA(0, 1), a2 + hstep, voffA);
;             PG8_WAIT_V(8); PG8_WAIT_L(0); PG8_BAR; PG8_MMA(0, 0, At, B0); PG8_MMA(0, 1, At, B1); PG8_BAR; PG8_SCHED;
;             PG8_LDA(At, 1, 1); PG8_STAGE(PG8_SB(1, 0), b3, voffB); PG8_STAGE(PG8_SB(1, 1), b3 + hstep, voffB); PG8_STAGE(PG8_SA(1, 0), a3, voffA);
;             PG8_WAIT_V(8); PG8_WAIT_L(0); PG8_BAR; PG8_MMA(1, 0, At, B0); PG8_MMA(1, 1, At, B1); PG8_BAR; PG8_SCHED;
	s_add_i32 s43, 0, 0x18000
	s_add_i32 s99, 0, 0x1c000
	ds_read_b128 v[130:133], v240
	ds_read_b128 v[134:137], v240 offset:1024
	ds_read_b128 v[138:141], v240 offset:2048
	ds_read_b128 v[180:183], v240 offset:3072
	ds_read_b128 v[184:187], v241
	ds_read_b128 v[188:191], v241 offset:1024
	ds_read_b128 v[192:195], v241 offset:2048
	ds_read_b128 v[196:199], v241 offset:3072
	s_add_u32 s84, s86, s74
	s_addc_u32 s85, s87, 0
	s_mov_b32 m0, s55
	ds_read_b128 v[200:203], v167 offset:32768
	ds_read_b128 v[204:207], v167 offset:33792
	ds_read_b128 v[208:211], v167 offset:34816
	ds_read_b128 v[218:221], v167 offset:35840
	ds_read_b128 v[222:225], v167 offset:36864
	ds_read_b128 v[226:229], v167 offset:37888
	ds_read_b128 v[230:233], v167 offset:38912
	ds_read_b128 v[234:237], v167 offset:39936
	global_load_lds_dwordx4 v146, s[84:85]
	s_mov_b32 m0, s56
	s_nop 0
	global_load_lds_dwordx4 v150, s[84:85]
	s_waitcnt vmcnt(8)
	s_waitcnt lgkmcnt(0)
	s_barrier
	s_setprio 1
	s_waitcnt lgkmcnt(0)
	v_mfma_f32_16x16x32_bf16 v[124:127], v[130:133], v[200:203], v[124:127]
	v_mfma_f32_16x16x32_bf16 v[120:123], v[138:141], v[200:203], v[120:123]
	v_mfma_f32_16x16x32_bf16 v[108:111], v[130:133], v[208:211], v[108:111]
	v_mfma_f32_16x16x32_bf16 v[104:107], v[138:141], v[208:211], v[104:107]
	v_mfma_f32_16x16x32_bf16 v[92:95], v[130:133], v[222:225], v[92:95]
	v_mfma_f32_16x16x32_bf16 v[88:91], v[138:141], v[222:225], v[88:91]
	v_mfma_f32_16x16x32_bf16 v[76:79], v[130:133], v[230:233], v[76:79]
	v_mfma_f32_16x16x32_bf16 v[72:75], v[138:141], v[230:233], v[72:75]
	v_mfma_f32_16x16x32_bf16 v[124:127], v[134:137], v[204:207], v[124:127]
	v_mfma_f32_16x16x32_bf16 v[120:123], v[180:183], v[204:207], v[120:123]
	v_mfma_f32_16x16x32_bf16 v[108:111], v[134:137], v[218:221], v[108:111]
	v_mfma_f32_16x16x32_bf16 v[104:107], v[180:183], v[218:221], v[104:107]
	v_mfma_f32_16x16x32_bf16 v[92:95], v[134:137], v[226:229], v[92:95]
	v_mfma_f32_16x16x32_bf16 v[88:91], v[180:183], v[226:229], v[88:91]
	v_mfma_f32_16x16x32_bf16 v[76:79], v[134:137], v[234:237], v[76:79]
	v_mfma_f32_16x16x32_bf16 v[72:75], v[180:183], v[234:237], v[72:75]
	s_setprio 0
	s_setprio 1
	v_mfma_f32_16x16x32_bf16 v[116:119], v[184:187], v[200:203], v[116:119]
	v_mfma_f32_16x16x32_bf16 v[112:115], v[192:195], v[200:203], v[112:115]
	v_mfma_f32_16x16x32_bf16 v[100:103], v[184:187], v[208:211], v[100:103]
	v_mfma_f32_16x16x32_bf16 v[96:99], v[192:195], v[208:211], v[96:99]
	v_mfma_f32_16x16x32_bf16 v[84:87], v[184:187], v[222:225], v[84:87]
	v_mfma_f32_16x16x32_bf16 v[80:83], v[192:195], v[222:225], v[80:83]
	v_mfma_f32_16x16x32_bf16 v[68:71], v[184:187], v[230:233], v[68:71]
	v_mfma_f32_16x16x32_bf16 v[64:67], v[192:195], v[230:233], v[64:67]
	v_mfma_f32_16x16x32_bf16 v[116:119], v[188:191], v[204:207], v[116:119]
	v_mfma_f32_16x16x32_bf16 v[112:115], v[196:199], v[204:207], v[112:115]
	v_mfma_f32_16x16x32_bf16 v[100:103], v[188:191], v[218:221], v[100:103]
	v_mfma_f32_16x16x32_bf16 v[96:99], v[196:199], v[218:221], v[96:99]
	v_mfma_f32_16x16x32_bf16 v[84:87], v[188:191], v[226:229], v[84:87]
	v_mfma_f32_16x16x32_bf16 v[80:83], v[196:199], v[226:229], v[80:83]
	v_mfma_f32_16x16x32_bf16 v[68:71], v[188:191], v[234:237], v[68:71]
	v_mfma_f32_16x16x32_bf16 v[64:67], v[196:199], v[234:237], v[64:67]
	s_setprio 0
	s_barrier
	s_add_i32 s43, s43, s52
	s_add_u32 s100, s100, 0x80
	s_addc_u32 s101, s101, 0
	s_mov_b32 m0, s43
	ds_read_b128 v[200:203], v167 offset:49152
	ds_read_b128 v[204:207], v167 offset:50176
	ds_read_b128 v[208:211], v167 offset:51200
	ds_read_b128 v[218:221], v167 offset:52224
	ds_read_b128 v[222:225], v167 offset:53248
	ds_read_b128 v[226:229], v167 offset:54272
	ds_read_b128 v[230:233], v167 offset:55296
	ds_read_b128 v[234:237], v167 offset:56320
	global_load_lds_dwordx4 v148, s[100:101]
	s_add_i32 m0, s43, 0x2000
	s_add_i32 s43, s99, s52
	global_load_lds_dwordx4 v152, s[100:101]
	s_add_u32 s100, s100, s74
	s_addc_u32 s101, s101, 0
	s_mov_b32 m0, s43
	s_nop 0
	global_load_lds_dwordx4 v148, s[100:101]
	s_add_u32 s86, s86, 0x80
	s_addc_u32 s87, s87, 0
	s_add_i32 m0, s43, 0x2000
	s_nop 0
	global_load_lds_dwordx4 v152, s[100:101]
	s_mov_b32 m0, s57
	s_nop 0
	global_load_lds_dwordx4 v146, s[86:87]
	s_mov_b32 m0, s58
	s_nop 0
	global_load_lds_dwordx4 v150, s[86:87]
	s_waitcnt vmcnt(8)
	s_waitcnt lgkmcnt(0)
	s_barrier
	s_setprio 1
	s_waitcnt lgkmcnt(0)
	v_mfma_f32_16x16x32_bf16 v[60:63], v[130:133], v[200:203], v[60:63]
	v_mfma_f32_16x16x32_bf16 v[56:59], v[138:141], v[200:203], v[56:59]
	v_mfma_f32_16x16x32_bf16 v[44:47], v[130:133], v[208:211], v[44:47]
	v_mfma_f32_16x16x32_bf16 v[40:43], v[138:141], v[208:211], v[40:43]
	v_mfma_f32_16x16x32_bf16 v[28:31], v[130:133], v[222:225], v[28:31]
	v_mfma_f32_16x16x32_bf16 v[24:27], v[138:141], v[222:225], v[24:27]
	v_mfma_f32_16x16x32_bf16 v[12:15], v[130:133], v[230:233], v[12:15]
	v_mfma_f32_16x16x32_bf16 v[8:11], v[138:141], v[230:233], v[8:11]
	v_mfma_f32_16x16x32_bf16 v[60:63], v[134:137], v[204:207], v[60:63]
	v_mfma_f32_16x16x32_bf16 v[56:59], v[180:183], v[204:207], v[56:59]
	v_mfma_f32_16x16x32_bf16 v[44:47], v[134:137], v[218:221], v[44:47]
	v_mfma_f32_16x16x32_bf16 v[40:43], v[180:183], v[218:221], v[40:43]
	v_mfma_f32_16x16x32_bf16 v[28:31], v[134:137], v[226:229], v[28:31]
	v_mfma_f32_16x16x32_bf16 v[24:27], v[180:183], v[226:229], v[24:27]
	v_mfma_f32_16x16x32_bf16 v[12:15], v[134:137], v[234:237], v[12:15]
	v_mfma_f32_16x16x32_bf16 v[8:11], v[180:183], v[234:237], v[8:11]
	s_setprio 0
	s_setprio 1
	v_mfma_f32_16x16x32_bf16 v[52:55], v[184:187], v[200:203], v[52:55]
	v_mfma_f32_16x16x32_bf16 v[48:51], v[192:195], v[200:203], v[48:51]
	v_mfma_f32_16x16x32_bf16 v[36:39], v[184:187], v[208:211], v[36:39]
	v_mfma_f32_16x16x32_bf16 v[32:35], v[192:195], v[208:211], v[32:35]
	v_mfma_f32_16x16x32_bf16 v[20:23], v[184:187], v[222:225], v[20:23]
	v_mfma_f32_16x16x32_bf16 v[16:19], v[192:195], v[222:225], v[16:19]
	v_mfma_f32_16x16x32_bf16 v[4:7], v[184:187], v[230:233], v[4:7]
	v_mfma_f32_16x16x32_bf16 v[0:3], v[192:195], v[230:233], v[0:3]
	v_mfma_f32_16x16x32_bf16 v[52:55], v[188:191], v[204:207], v[52:55]
	v_mfma_f32_16x16x32_bf16 v[48:51], v[196:199], v[204:207], v[48:51]
	v_mfma_f32_16x16x32_bf16 v[36:39], v[188:191], v[218:221], v[36:39]
	v_mfma_f32_16x16x32_bf16 v[32:35], v[196:199], v[218:221], v[32:35]
	v_mfma_f32_16x16x32_bf16 v[20:23], v[188:191], v[226:229], v[20:23]
	v_mfma_f32_16x16x32_bf16 v[16:19], v[196:199], v[226:229], v[16:19]
	v_mfma_f32_16x16x32_bf16 v[4:7], v[188:191], v[234:237], v[4:7]
	v_mfma_f32_16x16x32_bf16 v[0:3], v[196:199], v[234:237], v[0:3]
	s_setprio 0
	s_barrier
	s_add_u32 s82, s82, 0x100
	s_addc_u32 s83, s83, 0
	s_add_u32 s81, s81, 0x100
	s_addc_u32 s91, s91, 0
	s_cmp_ge_u32 s98, s60
	s_cbranch_scc1 .LBB0_107
	s_branch .LBB0_105
; #define PG8_STAGE(bufoff, gbase, voff) do { _Pragma("unroll") for (int _i = 0; _i < 2; ++_i) \
;         __builtin_amdgcn_global_load_lds((const unsigned*)((const char*)(gbase) + (voff)[_i]), (LAS unsigned*)(lds + (bufoff) + ldsw + _i * 8192), 16, 0, 0); } while (0)
; #define PG8_LDA(dst, b, h) do { _Pragma("unroll") for (int m = 0; m < 4; ++m) _Pragma("unroll") for (int k = 0; k < 2; ++k) dst[m][k] = *(const LAS bf16x8*)(lds + PG8_SA(b, h) + aoff + m * 2048 + k * 1024); } while (0)
; #define PG8_LDB(dst, b, h) do { _Pragma("unroll") for (int n = 0; n < 2; ++n) _Pragma("unroll") for (int k = 0; k < 2; ++k) dst[n][k] = *(const LAS bf16x8*)(lds + PG8_SB(b, h) + boff + n * 2048 + k * 1024); } while (0)
; #define PG8_MMA(ai, bj, At, Bt) do { __builtin_amdgcn_s_setprio(1); _Pragma("unroll") for (int m = 0; m < 4; ++m) _Pragma("unroll") for (int n = 0; n < 2; ++n) _Pragma("unroll") for (int k = 0; k < 2; ++k) \
;         acc[ai][bj][m][n] = __builtin_amdgcn_mfma_f32_16x16x32_bf16(Bt[n][k], At[m][k], acc[ai][bj][m][n], 0, 0, 0); __builtin_amdgcn_s_setprio(0); } while (0)
; #define PG8_WAIT_V(n) asm volatile("s_waitcnt vmcnt(" #n ")" ::: "memory")
; #define PG8_WAIT_L(n) asm volatile("s_waitcnt lgkmcnt(" #n ")" ::: "memory")
; #define PG8_BAR __builtin_amdgcn_s_barrier()
; #define PG8_SCHED __builtin_amdgcn_sched_barrier(0)
; __device__ __forceinline__ void gemm_phase(LAS unsigned char* lds, const GP p, const int tid) {
;     ...
;             PG8_LDB(B0, 0, 0); PG8_LDB(B1, 0, 1); PG8_SCHED; PG8_LDA(At, 0, 0); PG8_STAGE(PG8_SA(1, 1), a1 + hstep, voffA);
;             PG8_WAIT_V(8); PG8_WAIT_L(0); PG8_BAR; PG8_MMA(0, 0, At, B0); PG8_MMA(0, 1, At, B1); PG8_BAR; PG8_SCHED;
;             PG8_LDA(At, 0, 1); PG8_STAGE(PG8_SB(0, 0), b2, voffB); PG8_STAGE(PG8_SB(0, 1), b2 + hstep, voffB); PG8_STAGE(PG8_SA(0, 0), a2, voffA);
;             PG8_WAIT_V(8); PG8_WAIT_L(0); PG8_BAR; PG8_MMA(1, 0, At, B0); PG8_MMA(1, 1, At, B1); PG8_BAR; PG8_SCHED;
.LBB0_104:
	s_cmp_eq_u32 s98, 0
	s_cbranch_scc1 .Lpeel_body
	s_add_i32 s98, s98, 2
	s_add_u32 s43, s82, 0x80
	s_addc_u32 s99, s83, 0
	s_and_b64 s[86:87], s[84:85], exec
	s_cselect_b32 s87, s77, s99
	s_cselect_b32 s86, s76, s43
	s_add_i32 s43, 0, 0x10000
	s_and_b64 s[84:85], s[84:85], exec
	s_cselect_b32 s85, s79, s91
	s_cselect_b32 s84, s78, s81
	s_add_i32 s99, 0, 0x14000
	ds_read_b128 v[130:133], v238
	ds_read_b128 v[134:137], v238 offset:1024
	ds_read_b128 v[138:141], v238 offset:2048
	ds_read_b128 v[180:183], v238 offset:3072
	ds_read_b128 v[184:187], v239
	ds_read_b128 v[188:191], v239 offset:1024
	ds_read_b128 v[192:195], v239 offset:2048
	ds_read_b128 v[196:199], v239 offset:3072
	s_add_i32 m0, s53, 0xc000
	ds_read_b128 v[200:203], v167
	ds_read_b128 v[204:207], v167 offset:1024
	ds_read_b128 v[208:211], v167 offset:2048
	ds_read_b128 v[218:221], v167 offset:3072
	ds_read_b128 v[222:225], v167 offset:4096
	ds_read_b128 v[226:229], v167 offset:5120
	ds_read_b128 v[230:233], v167 offset:6144
	ds_read_b128 v[234:237], v167 offset:7168
	global_load_lds_dwordx4 v160, s[82:83]
	s_add_i32 m0, s53, 0xe000
	s_nop 0
	global_load_lds_dwordx4 v162, s[82:83]
	s_waitcnt vmcnt(8)
	s_waitcnt lgkmcnt(0)
	s_barrier
	s_setprio 1
	s_waitcnt lgkmcnt(0)
	v_mfma_f32_16x16x32_bf16 v[124:127], v[130:133], v[200:203], v[124:127]
	v_mfma_f32_16x16x32_bf16 v[120:123], v[138:141], v[200:203], v[120:123]
	v_mfma_f32_16x16x32_bf16 v[108:111], v[130:133], v[208:211], v[108:111]
	v_mfma_f32_16x16x32_bf16 v[104:107], v[138:141], v[208:211], v[104:107]
	v_mfma_f32_16x16x32_bf16 v[92:95], v[130:133], v[222:225], v[92:95]
	v_mfma_f32_16x16x32_bf16 v[88:91], v[138:141], v[222:225], v[88:91]
	v_mfma_f32_16x16x32_bf16 v[76:79], v[130:133], v[230:233], v[76:79]
	v_mfma_f32_16x16x32_bf16 v[72:75], v[138:141], v[230:233], v[72:75]
	v_mfma_f32_16x16x32_bf16 v[124:127], v[134:137], v[204:207], v[124:127]
	v_mfma_f32_16x16x32_bf16 v[120:123], v[180:183], v[204:207], v[120:123]
	v_mfma_f32_16x16x32_bf16 v[108:111], v[134:137], v[218:221], v[108:111]
	v_mfma_f32_16x16x32_bf16 v[104:107], v[180:183], v[218:221], v[104:107]
	v_mfma_f32_16x16x32_bf16 v[92:95], v[134:137], v[226:229], v[92:95]
	v_mfma_f32_16x16x32_bf16 v[88:91], v[180:183], v[226:229], v[88:91]
	v_mfma_f32_16x16x32_bf16 v[76:79], v[134:137], v[234:237], v[76:79]
	v_mfma_f32_16x16x32_bf16 v[72:75], v[180:183], v[234:237], v[72:75]
	s_setprio 0
	s_setprio 1
	v_mfma_f32_16x16x32_bf16 v[116:119], v[184:187], v[200:203], v[116:119]
	v_mfma_f32_16x16x32_bf16 v[112:115], v[192:195], v[200:203], v[112:115]
	v_mfma_f32_16x16x32_bf16 v[100:103], v[184:187], v[208:211], v[100:103]
	v_mfma_f32_16x16x32_bf16 v[96:99], v[192:195], v[208:211], v[96:99]
	v_mfma_f32_16x16x32_bf16 v[84:87], v[184:187], v[222:225], v[84:87]
	v_mfma_f32_16x16x32_bf16 v[80:83], v[192:195], v[222:225], v[80:83]
	v_mfma_f32_16x16x32_bf16 v[68:71], v[184:187], v[230:233], v[68:71]
	v_mfma_f32_16x16x32_bf16 v[64:67], v[192:195], v[230:233], v[64:67]
	v_mfma_f32_16x16x32_bf16 v[116:119], v[188:191], v[204:207], v[116:119]
	v_mfma_f32_16x16x32_bf16 v[112:115], v[196:199], v[204:207], v[112:115]
	v_mfma_f32_16x16x32_bf16 v[100:103], v[188:191], v[218:221], v[100:103]
	v_mfma_f32_16x16x32_bf16 v[96:99], v[196:199], v[218:221], v[96:99]
	v_mfma_f32_16x16x32_bf16 v[84:87], v[188:191], v[226:229], v[84:87]
	v_mfma_f32_16x16x32_bf16 v[80:83], v[196:199], v[226:229], v[80:83]
	v_mfma_f32_16x16x32_bf16 v[68:71], v[188:191], v[234:237], v[68:71]
	v_mfma_f32_16x16x32_bf16 v[64:67], v[196:199], v[234:237], v[64:67]
	s_setprio 0
	s_barrier
	s_add_i32 s43, s43, s52
	s_mov_b64 s[100:101], s[84:85]
	s_mov_b32 m0, s43
	ds_read_b128 v[200:203], v167 offset:16384
	ds_read_b128 v[204:207], v167 offset:17408
	ds_read_b128 v[208:211], v167 offset:18432
	ds_read_b128 v[218:221], v167 offset:19456
	ds_read_b128 v[222:225], v167 offset:20480
	ds_read_b128 v[226:229], v167 offset:21504
	ds_read_b128 v[230:233], v167 offset:22528
	ds_read_b128 v[234:237], v167 offset:23552
	global_load_lds_dwordx4 v148, s[84:85]
	s_add_i32 m0, s43, 0x2000
	s_add_i32 s43, s99, s52
	global_load_lds_dwordx4 v152, s[84:85]
	s_add_u32 s84, s84, s74
	s_addc_u32 s85, s85, 0
	s_mov_b32 m0, s43
	s_nop 0
	global_load_lds_dwordx4 v148, s[84:85]
	s_add_i32 m0, s43, 0x2000
	s_nop 0
	global_load_lds_dwordx4 v152, s[84:85]
	s_mov_b32 m0, s53
	s_nop 0
	global_load_lds_dwordx4 v146, s[86:87]
	s_mov_b32 m0, s54
	s_nop 0
	global_load_lds_dwordx4 v150, s[86:87]
	s_waitcnt vmcnt(8)
	s_waitcnt lgkmcnt(0)
	s_barrier
; #define PG8_STAGE(bufoff, gbase, voff) do { _Pragma("unroll") for (int _i = 0; _i < 2; ++_i) \
;         __builtin_amdgcn_global_load_lds((const unsigned*)((const char*)(gbase) + (voff)[_i]), (LAS unsigned*)(lds + (bufoff) + ldsw + _i * 8192), 16, 0, 0); } while (0)
; #define PG8_LDA(dst, b, h) do { _Pragma("unroll") for (int m = 0; m < 4; ++m) _Pragma("unroll") for (int k = 0; k < 2; ++k) dst[m][k] = *(const LAS bf16x8*)(lds + PG8_SA(b, h) + aoff + m * 2048 + k * 1024); } while (0)
; #define PG8_LDB(dst, b, h) do { _Pragma("unroll") for (int n = 0; n < 2; ++n) _Pragma("unroll") for (int k = 0; k < 2; ++k) dst[n][k] = *(const LAS bf16x8*)(lds + PG8_SB(b, h) + boff + n * 2048 + k * 1024); } while (0)
; #define PG8_MMA(ai, bj, At, Bt) do { __builtin_amdgcn_s_setprio(1); _Pragma("unroll") for (int m = 0; m < 4; ++m) _Pragma("unroll") for (int n = 0; n < 2; ++n) _Pragma("unroll") for (int k = 0; k < 2; ++k) \
;         acc[ai][bj][m][n] = __builtin_amdgcn_mfma_f32_16x16x32_bf16(Bt[n][k], At[m][k], acc[ai][bj][m][n], 0, 0, 0); __builtin_amdgcn_s_setprio(0); } while (0)
; #define PG8_WAIT_V(n) asm volatile("s_waitcnt vmcnt(" #n ")" ::: "memory")
; #define PG8_WAIT_L(n) asm volatile("s_waitcnt lgkmcnt(" #n ")" ::: "memory")
; #define PG8_BAR __builtin_amdgcn_s_barrier()
; #define PG8_SCHED __builtin_amdgcn_sched_barrier(0)
; __device__ __forceinline__ void gemm_phase(LAS unsigned char* lds, const GP p, const int tid) {
;     ...
;             PG8_WAIT_V(8); PG8_WAIT_L(0); PG8_BAR; PG8_MMA(1, 0, At, B0); PG8_MMA(1, 1, At, B1); PG8_BAR; PG8_SCHED;
;             PG8_LDB(B0, 1, 0); PG8_LDB(B1, 1, 1); PG8_SCHED; PG8_LDA(At, 1, 0); PG8_STAGE(PG8_SA(0, 1), a2 + hstep, voffA);
;             PG8_WAIT_V(8); PG8_WAIT_L(0); PG8_BAR; PG8_MMA(0, 0, At, B0); PG8_MMA(0, 1, At, B1); PG8_BAR; PG8_SCHED;
	s_setprio 1
	s_waitcnt lgkmcnt(0)
	v_mfma_f32_16x16x32_bf16 v[60:63], v[130:133], v[200:203], v[60:63]
	v_mfma_f32_16x16x32_bf16 v[56:59], v[138:141], v[200:203], v[56:59]
	v_mfma_f32_16x16x32_bf16 v[44:47], v[130:133], v[208:211], v[44:47]
	v_mfma_f32_16x16x32_bf16 v[40:43], v[138:141], v[208:211], v[40:43]
	v_mfma_f32_16x16x32_bf16 v[28:31], v[130:133], v[222:225], v[28:31]
	v_mfma_f32_16x16x32_bf16 v[24:27], v[138:141], v[222:225], v[24:27]
	v_mfma_f32_16x16x32_bf16 v[12:15], v[130:133], v[230:233], v[12:15]
	v_mfma_f32_16x16x32_bf16 v[8:11], v[138:141], v[230:233], v[8:11]
	v_mfma_f32_16x16x32_bf16 v[60:63], v[134:137], v[204:207], v[60:63]
	v_mfma_f32_16x16x32_bf16 v[56:59], v[180:183], v[204:207], v[56:59]
	v_mfma_f32_16x16x32_bf16 v[44:47], v[134:137], v[218:221], v[44:47]
	v_mfma_f32_16x16x32_bf16 v[40:43], v[180:183], v[218:221], v[40:43]
	v_mfma_f32_16x16x32_bf16 v[28:31], v[134:137], v[226:229], v[28:31]
	v_mfma_f32_16x16x32_bf16 v[24:27], v[180:183], v[226:229], v[24:27]
	v_mfma_f32_16x16x32_bf16 v[12:15], v[134:137], v[234:237], v[12:15]
	v_mfma_f32_16x16x32_bf16 v[8:11], v[180:183], v[234:237], v[8:11]
	s_setprio 0
	s_setprio 1
	v_mfma_f32_16x16x32_bf16 v[52:55], v[184:187], v[200:203], v[52:55]
	v_mfma_f32_16x16x32_bf16 v[48:51], v[192:195], v[200:203], v[48:51]
	v_mfma_f32_16x16x32_bf16 v[36:39], v[184:187], v[208:211], v[36:39]
	v_mfma_f32_16x16x32_bf16 v[32:35], v[192:195], v[208:211], v[32:35]
	v_mfma_f32_16x16x32_bf16 v[20:23], v[184:187], v[222:225], v[20:23]
	v_mfma_f32_16x16x32_bf16 v[16:19], v[192:195], v[222:225], v[16:19]
	v_mfma_f32_16x16x32_bf16 v[4:7], v[184:187], v[230:233], v[4:7]
	v_mfma_f32_16x16x32_bf16 v[0:3], v[192:195], v[230:233], v[0:3]
	v_mfma_f32_16x16x32_bf16 v[52:55], v[188:191], v[204:207], v[52:55]
	v_mfma_f32_16x16x32_bf16 v[48:51], v[196:199], v[204:207], v[48:51]
	v_mfma_f32_16x16x32_bf16 v[36:39], v[188:191], v[218:221], v[36:39]
	v_mfma_f32_16x16x32_bf16 v[32:35], v[196:199], v[218:221], v[32:35]
	v_mfma_f32_16x16x32_bf16 v[20:23], v[188:191], v[226:229], v[20:23]
	v_mfma_f32_16x16x32_bf16 v[16:19], v[196:199], v[226:229], v[16:19]
	v_mfma_f32_16x16x32_bf16 v[4:7], v[188:191], v[234:237], v[4:7]
	v_mfma_f32_16x16x32_bf16 v[0:3], v[196:199], v[234:237], v[0:3]
	s_setprio 0
	s_barrier
	s_add_i32 s43, 0, 0x18000
	s_add_i32 s99, 0, 0x1c000
	ds_read_b128 v[130:133], v240
	ds_read_b128 v[134:137], v240 offset:1024
	ds_read_b128 v[138:141], v240 offset:2048
	ds_read_b128 v[180:183], v240 offset:3072
	ds_read_b128 v[184:187], v241
	ds_read_b128 v[188:191], v241 offset:1024
	ds_read_b128 v[192:195], v241 offset:2048
	ds_read_b128 v[196:199], v241 offset:3072
	s_add_u32 s84, s86, s74
	s_addc_u32 s85, s87, 0
	s_mov_b32 m0, s55
	ds_read_b128 v[200:203], v167 offset:32768
	ds_read_b128 v[204:207], v167 offset:33792
	ds_read_b128 v[208:211], v167 offset:34816
	ds_read_b128 v[218:221], v167 offset:35840
	ds_read_b128 v[222:225], v167 offset:36864
	ds_read_b128 v[226:229], v167 offset:37888
	ds_read_b128 v[230:233], v167 offset:38912
	ds_read_b128 v[234:237], v167 offset:39936
	global_load_lds_dwordx4 v146, s[84:85]
	s_mov_b32 m0, s56
	s_nop 0
	global_load_lds_dwordx4 v150, s[84:85]
	s_waitcnt vmcnt(8)
	s_waitcnt lgkmcnt(0)
	s_barrier
	s_setprio 1
	s_waitcnt lgkmcnt(0)
	v_mfma_f32_16x16x32_bf16 v[124:127], v[130:133], v[200:203], v[124:127]
	v_mfma_f32_16x16x32_bf16 v[120:123], v[138:141], v[200:203], v[120:123]
	v_mfma_f32_16x16x32_bf16 v[108:111], v[130:133], v[208:211], v[108:111]
	v_mfma_f32_16x16x32_bf16 v[104:107], v[138:141], v[208:211], v[104:107]
	v_mfma_f32_16x16x32_bf16 v[92:95], v[130:133], v[222:225], v[92:95]
	v_mfma_f32_16x16x32_bf16 v[88:91], v[138:141], v[222:225], v[88:91]
	v_mfma_f32_16x16x32_bf16 v[76:79], v[130:133], v[230:233], v[76:79]
	v_mfma_f32_16x16x32_bf16 v[72:75], v[138:141], v[230:233], v[72:75]
	v_mfma_f32_16x16x32_bf16 v[124:127], v[134:137], v[204:207], v[124:127]
	v_mfma_f32_16x16x32_bf16 v[120:123], v[180:183], v[204:207], v[120:123]
	v_mfma_f32_16x16x32_bf16 v[108:111], v[134:137], v[218:221], v[108:111]
	v_mfma_f32_16x16x32_bf16 v[104:107], v[180:183], v[218:221], v[104:107]
	v_mfma_f32_16x16x32_bf16 v[92:95], v[134:137], v[226:229], v[92:95]
	v_mfma_f32_16x16x32_bf16 v[88:91], v[180:183], v[226:229], v[88:91]
	v_mfma_f32_16x16x32_bf16 v[76:79], v[134:137], v[234:237], v[76:79]
	v_mfma_f32_16x16x32_bf16 v[72:75], v[180:183], v[234:237], v[72:75]
	s_setprio 0
	s_setprio 1
	v_mfma_f32_16x16x32_bf16 v[116:119], v[184:187], v[200:203], v[116:119]
	v_mfma_f32_16x16x32_bf16 v[112:115], v[192:195], v[200:203], v[112:115]
	v_mfma_f32_16x16x32_bf16 v[100:103], v[184:187], v[208:211], v[100:103]
	v_mfma_f32_16x16x32_bf16 v[96:99], v[192:195], v[208:211], v[96:99]
	v_mfma_f32_16x16x32_bf16 v[84:87], v[184:187], v[222:225], v[84:87]
	v_mfma_f32_16x16x32_bf16 v[80:83], v[192:195], v[222:225], v[80:83]
	v_mfma_f32_16x16x32_bf16 v[68:71], v[184:187], v[230:233], v[68:71]
	v_mfma_f32_16x16x32_bf16 v[64:67], v[192:195], v[230:233], v[64:67]
	v_mfma_f32_16x16x32_bf16 v[116:119], v[188:191], v[204:207], v[116:119]
	v_mfma_f32_16x16x32_bf16 v[112:115], v[196:199], v[204:207], v[112:115]
	v_mfma_f32_16x16x32_bf16 v[100:103], v[188:191], v[218:221], v[100:103]
	v_mfma_f32_16x16x32_bf16 v[96:99], v[196:199], v[218:221], v[96:99]
	v_mfma_f32_16x16x32_bf16 v[84:87], v[188:191], v[226:229], v[84:87]
	v_mfma_f32_16x16x32_bf16 v[80:83], v[196:199], v[226:229], v[80:83]
	v_mfma_f32_16x16x32_bf16 v[68:71], v[188:191], v[234:237], v[68:71]
	v_mfma_f32_16x16x32_bf16 v[64:67], v[196:199], v[234:237], v[64:67]
	s_setprio 0
	s_barrier
; #define PG8_STAGE(bufoff, gbase, voff) do { _Pragma("unroll") for (int _i = 0; _i < 2; ++_i) \
;         __builtin_amdgcn_global_load_lds((const unsigned*)((const char*)(gbase) + (voff)[_i]), (LAS unsigned*)(lds + (bufoff) + ldsw + _i * 8192), 16, 0, 0); } while (0)
; #define PG8_LDA(dst, b, h) do { _Pragma("unroll") for (int m = 0; m < 4; ++m) _Pragma("unroll") for (int k = 0; k < 2; ++k) dst[m][k] = *(const LAS bf16x8*)(lds + PG8_SA(b, h) + aoff + m * 2048 + k * 1024); } while (0)
; #define PG8_MMA(ai, bj, At, Bt) do { __builtin_amdgcn_s_setprio(1); _Pragma("unroll") for (int m = 0; m < 4; ++m) _Pragma("unroll") for (int n = 0; n < 2; ++n) _Pragma("unroll") for (int k = 0; k < 2; ++k) \
;         acc[ai][bj][m][n] = __builtin_amdgcn_mfma_f32_16x16x32_bf16(Bt[n][k], At[m][k], acc[ai][bj][m][n], 0, 0, 0); __builtin_amdgcn_s_setprio(0); } while (0)
; #define PG8_WAIT_V(n) asm volatile("s_waitcnt vmcnt(" #n ")" ::: "memory")
; #define PG8_WAIT_L(n) asm volatile("s_waitcnt lgkmcnt(" #n ")" ::: "memory")
; #define PG8_BAR __builtin_amdgcn_s_barrier()
; #define PG8_SCHED __builtin_amdgcn_sched_barrier(0)
; __device__ __forceinline__ void gemm_phase(LAS unsigned char* lds, const GP p, const int tid) {
;     ...
;             PG8_LDA(At, 1, 1); PG8_STAGE(PG8_SB(1, 0), b3, voffB); PG8_STAGE(PG8_SB(1, 1), b3 + hstep, voffB); PG8_STAGE(PG8_SA(1, 0), a3, voffA);
;             PG8_WAIT_V(8); PG8_WAIT_L(0); PG8_BAR; PG8_MMA(1, 0, At, B0); PG8_MMA(1, 1, At, B1); PG8_BAR; PG8_SCHED;
;         }
	s_add_i32 s43, s43, s52
	s_add_u32 s100, s100, 0x80
	s_addc_u32 s101, s101, 0
	s_mov_b32 m0, s43
	ds_read_b128 v[200:203], v167 offset:49152
	ds_read_b128 v[204:207], v167 offset:50176
	ds_read_b128 v[208:211], v167 offset:51200
	ds_read_b128 v[218:221], v167 offset:52224
	ds_read_b128 v[222:225], v167 offset:53248
	ds_read_b128 v[226:229], v167 offset:54272
	ds_read_b128 v[230:233], v167 offset:55296
	ds_read_b128 v[234:237], v167 offset:56320
	global_load_lds_dwordx4 v148, s[100:101]
	s_add_i32 m0, s43, 0x2000
	s_add_i32 s43, s99, s52
	global_load_lds_dwordx4 v152, s[100:101]
	s_add_u32 s100, s100, s74
	s_addc_u32 s101, s101, 0
	s_mov_b32 m0, s43
	s_nop 0
	global_load_lds_dwordx4 v148, s[100:101]
	s_add_u32 s86, s86, 0x80
	s_addc_u32 s87, s87, 0
	s_add_i32 m0, s43, 0x2000
	s_nop 0
	global_load_lds_dwordx4 v152, s[100:101]
	s_mov_b32 m0, s57
	s_nop 0
	global_load_lds_dwordx4 v146, s[86:87]
	s_mov_b32 m0, s58
	s_nop 0
	global_load_lds_dwordx4 v150, s[86:87]
	s_waitcnt vmcnt(8)
	s_waitcnt lgkmcnt(0)
	s_barrier
	s_setprio 1
	s_waitcnt lgkmcnt(0)
	v_mfma_f32_16x16x32_bf16 v[60:63], v[130:133], v[200:203], v[60:63]
	v_mfma_f32_16x16x32_bf16 v[56:59], v[138:141], v[200:203], v[56:59]
	v_mfma_f32_16x16x32_bf16 v[44:47], v[130:133], v[208:211], v[44:47]
	v_mfma_f32_16x16x32_bf16 v[40:43], v[138:141], v[208:211], v[40:43]
	v_mfma_f32_16x16x32_bf16 v[28:31], v[130:133], v[222:225], v[28:31]
	v_mfma_f32_16x16x32_bf16 v[24:27], v[138:141], v[222:225], v[24:27]
	v_mfma_f32_16x16x32_bf16 v[12:15], v[130:133], v[230:233], v[12:15]
	v_mfma_f32_16x16x32_bf16 v[8:11], v[138:141], v[230:233], v[8:11]
	v_mfma_f32_16x16x32_bf16 v[60:63], v[134:137], v[204:207], v[60:63]
	v_mfma_f32_16x16x32_bf16 v[56:59], v[180:183], v[204:207], v[56:59]
	v_mfma_f32_16x16x32_bf16 v[44:47], v[134:137], v[218:221], v[44:47]
	v_mfma_f32_16x16x32_bf16 v[40:43], v[180:183], v[218:221], v[40:43]
	v_mfma_f32_16x16x32_bf16 v[28:31], v[134:137], v[226:229], v[28:31]
	v_mfma_f32_16x16x32_bf16 v[24:27], v[180:183], v[226:229], v[24:27]
	v_mfma_f32_16x16x32_bf16 v[12:15], v[134:137], v[234:237], v[12:15]
	v_mfma_f32_16x16x32_bf16 v[8:11], v[180:183], v[234:237], v[8:11]
	s_setprio 0
	s_setprio 1
	v_mfma_f32_16x16x32_bf16 v[52:55], v[184:187], v[200:203], v[52:55]
	v_mfma_f32_16x16x32_bf16 v[48:51], v[192:195], v[200:203], v[48:51]
	v_mfma_f32_16x16x32_bf16 v[36:39], v[184:187], v[208:211], v[36:39]
	v_mfma_f32_16x16x32_bf16 v[32:35], v[192:195], v[208:211], v[32:35]
	v_mfma_f32_16x16x32_bf16 v[20:23], v[184:187], v[222:225], v[20:23]
	v_mfma_f32_16x16x32_bf16 v[16:19], v[192:195], v[222:225], v[16:19]
	v_mfma_f32_16x16x32_bf16 v[4:7], v[184:187], v[230:233], v[4:7]
	v_mfma_f32_16x16x32_bf16 v[0:3], v[192:195], v[230:233], v[0:3]
	v_mfma_f32_16x16x32_bf16 v[52:55], v[188:191], v[204:207], v[52:55]
	v_mfma_f32_16x16x32_bf16 v[48:51], v[196:199], v[204:207], v[48:51]
	v_mfma_f32_16x16x32_bf16 v[36:39], v[188:191], v[218:221], v[36:39]
	v_mfma_f32_16x16x32_bf16 v[32:35], v[196:199], v[218:221], v[32:35]
	v_mfma_f32_16x16x32_bf16 v[20:23], v[188:191], v[226:229], v[20:23]
	v_mfma_f32_16x16x32_bf16 v[16:19], v[196:199], v[226:229], v[16:19]
	v_mfma_f32_16x16x32_bf16 v[4:7], v[188:191], v[234:237], v[4:7]
	v_mfma_f32_16x16x32_bf16 v[0:3], v[196:199], v[234:237], v[0:3]
	s_setprio 0
	s_barrier
	s_add_u32 s82, s82, 0x100
	s_addc_u32 s83, s83, 0
	s_add_u32 s81, s81, 0x100
	s_addc_u32 s91, s91, 0
	s_cmp_ge_u32 s98, s60
	s_cbranch_scc1 .LBB0_107

; #define PG8_BAR __builtin_amdgcn_s_barrier()
; __device__ __forceinline__ void gemm_phase(LAS unsigned char* lds, const GP p, const int tid) {
;     ...
;         if (wr == 0) PG8_BAR;
;         epilogue(acc, cur, wr, wc, fr, fq, p.mode, p.out, p.ld, p.proj, p.vt, p.km, p.vmt, p.rs, rsv);
.LBB0_120:
	s_and_b64 vcc, exec, s[90:91]
	s_cbranch_vccnz .Lep_w0
	s_waitcnt vmcnt(8)
	s_branch .Lep_wd

;     __device__ __forceinline__ f32x4 xf(f32x4 v) const {
;         v = v * sc;
;         if (act) { v.x = gelu_tanh(v.x); v.y = gelu_tanh(v.y); v.z = gelu_tanh(v.z); v.w = gelu_tanh(v.w); }
; __device__ __forceinline__ void epilogue(const f32x4 (&acc)[2][2][4][2], const Unit& u, int wr, int wc, int fr, int fq, int mode, bf16_t* out, int ld, bf16_t* proj, bf16_t* vt, bf16_t* km, bf16_t* vmt, const float* rs, const float (&rsv)[2][4]) {
;     ...
;                 const float r = rowsc ? rsv[ai][m] : 1.0f;
; #pragma unroll
;                 for (int bj = 0; bj < 2; ++bj)
;                     o.st8(row0 + ai * HALF + m * 16, u.pn * BM + bj * HALF + cb, acc[ai][bj][m][0] * c0[bj] * r, acc[ai][bj][m][1] * c1[bj] * r);
.Lep_wd:
	v_cndmask_b32_e64 v186, 1.0, v164, s[84:85]
	v_pk_mul_f32 v[184:185], v[126:127], v[142:143]
	v_pk_mul_f32 v[188:189], v[124:125], v[140:141]
	s_xor_b64 s[80:81], s[80:81], -1
	v_pk_mul_f32 v[184:185], v[186:187], v[184:185] op_sel_hi:[0,1]
	v_pk_mul_f32 v[190:191], v[186:187], v[188:189] op_sel_hi:[0,1]
	v_cndmask_b32_e64 v144, 0, 1, s[80:81]
	v_pk_mul_f32 v[188:189], v[182:183], v[184:185]
	v_cmp_ne_u32_e64 s[42:43], 1, v144
	s_andn2_b64 vcc, exec, s[80:81]
	v_pk_mul_f32 v[190:191], v[180:181], v[190:191]
	s_cbranch_vccnz .LBB0_122
	v_mul_f32_e32 v144, 0x3d372713, v190
	v_fma_f32 v144, v190, v144, 1.0
	v_mul_f32_e32 v144, v190, v144
	v_mul_f32_e32 v144, 0xc0135761, v144
	v_exp_f32_e32 v144, v144
	v_mul_f32_e32 v171, 0x3d372713, v191
	v_fma_f32 v171, v191, v171, 1.0
	v_mul_f32_e32 v171, v191, v171
	v_add_f32_e32 v144, 1.0, v144
	v_rcp_f32_e32 v184, v144
	v_mul_f32_e32 v144, 0xc0135761, v171
	v_mul_f32_e32 v171, 0x3d372713, v188
	v_fma_f32 v171, v188, v171, 1.0
	v_mul_f32_e32 v173, 0x3d372713, v189
	v_mul_f32_e32 v171, v188, v171
	v_fma_f32 v173, v189, v173, 1.0
	v_mul_f32_e32 v171, 0xc0135761, v171
	v_mul_f32_e32 v173, v189, v173
	v_exp_f32_e32 v171, v171
	v_mul_f32_e32 v173, 0xc0135761, v173
	v_exp_f32_e32 v144, v144
	v_exp_f32_e32 v173, v173
	v_add_f32_e32 v171, 1.0, v171
	v_rcp_f32_e32 v192, v171
	v_add_f32_e32 v144, 1.0, v144
	v_add_f32_e32 v171, 1.0, v173
	v_rcp_f32_e32 v193, v171
	v_rcp_f32_e32 v185, v144
	v_pk_mul_f32 v[188:189], v[188:189], v[192:193]
	v_pk_mul_f32 v[190:191], v[190:191], v[184:185]

; __device__ __forceinline__ unsigned pk2(float lo, float hi) { unsigned r; asm("v_cvt_pk_bf16_f32 %0, %1, %2" : "=v"(r) : "v"(lo), "v"(hi)); return r; }
; __device__ __forceinline__ float silu_mul(float g, float u) { return g * frcp(1.0f + fexp2(g * (-LOG2E))) * u; }
; __device__ __forceinline__ void epilogue(const f32x4 (&acc)[2][2][4][2], const Unit& u, int wr, int wc, int fr, int fq, int mode, bf16_t* out, int ld, bf16_t* proj, bf16_t* vt, bf16_t* km, bf16_t* vmt, const float* rs, const float (&rsv)[2][4]) {
;     ...
;                 const float r = rsv[ai][m];
;                 const f32x4 g0 = acc[ai][0][m][0] * r, g1 = acc[ai][0][m][1] * r, u0 = acc[ai][1][m][0] * r, u1 = acc[ai][1][m][1] * r;
;                 u32x4 w;
;                 w.x = pk2(silu_mul(g0.x, u0.x), silu_mul(g0.y, u0.y)); w.y = pk2(silu_mul(g0.z, u0.z), silu_mul(g0.w, u0.w));
;                 w.z = pk2(silu_mul(g1.x, u1.x), silu_mul(g1.y, u1.y)); w.w = pk2(silu_mul(g1.z, u1.z), silu_mul(g1.w, u1.w));
;                 *(u32x4*)(out + (size_t)(row0 + ai * HALF + m * 16) * DFF + u.pn * 128 + cb) = w;
.LBB0_185:
	s_waitcnt vmcnt(8)
	v_pk_mul_f32 v[124:125], v[164:165], v[124:125] op_sel_hi:[0,1]
	v_pk_mul_f32 v[128:129], v[164:165], v[114:115] op_sel_hi:[0,1]
	v_mul_f32_e32 v114, 0xbfb8aa3b, v124
	v_mul_f32_e32 v115, 0xbfb8aa3b, v125
	v_exp_f32_e32 v114, v114
	v_exp_f32_e32 v115, v115
	v_pk_mul_f32 v[116:117], v[164:165], v[116:117] op_sel_hi:[0,1]
	v_pk_mul_f32 v[126:127], v[164:165], v[126:127] op_sel_hi:[0,1]
	v_add_f32_e32 v114, 1.0, v114
	v_add_f32_e32 v115, 1.0, v115
	v_rcp_f32_e32 v114, v114
	v_rcp_f32_e32 v115, v115
	v_pk_mul_f32 v[118:119], v[164:165], v[118:119] op_sel_hi:[0,1]
	v_pk_mul_f32 v[120:121], v[164:165], v[120:121] op_sel_hi:[0,1]
	v_mul_f32_e32 v114, v124, v114
	v_mul_f32_e32 v115, v125, v115
	v_mul_f32_e32 v114, v114, v116
	v_mul_f32_e32 v115, v115, v117
	v_cvt_pk_bf16_f32 v114, v114, v115
	v_mul_f32_e32 v115, 0xbfb8aa3b, v126
	v_mul_f32_e32 v116, 0xbfb8aa3b, v127
	v_exp_f32_e32 v115, v115
	v_exp_f32_e32 v116, v116
	v_pk_mul_f32 v[112:113], v[164:165], v[112:113] op_sel_hi:[0,1]
	v_pk_mul_f32 v[122:123], v[164:165], v[122:123] op_sel_hi:[0,1]
	v_add_f32_e32 v115, 1.0, v115
	v_add_f32_e32 v116, 1.0, v116
	v_rcp_f32_e32 v115, v115
	v_rcp_f32_e32 v116, v116
	v_lshlrev_b32_e32 v144, 1, v156
	v_pk_mul_f32 v[108:109], v[166:167], v[108:109] op_sel_hi:[0,1]
	v_mul_f32_e32 v115, v126, v115
	v_mul_f32_e32 v116, v127, v116
	v_mul_f32_e32 v115, v115, v118
	v_mul_f32_e32 v116, v116, v119
	v_cvt_pk_bf16_f32 v115, v115, v116
	v_mul_f32_e32 v116, 0xbfb8aa3b, v120
	v_exp_f32_e32 v116, v116
	v_pk_mul_f32 v[100:101], v[166:167], v[100:101] op_sel_hi:[0,1]
	v_pk_mul_f32 v[110:111], v[166:167], v[110:111] op_sel_hi:[0,1]
	v_pk_mul_f32 v[102:103], v[166:167], v[102:103] op_sel_hi:[0,1]
	v_add_f32_e32 v116, 1.0, v116
	v_rcp_f32_e32 v116, v116
	v_pk_mul_f32 v[104:105], v[166:167], v[104:105] op_sel_hi:[0,1]
	v_pk_mul_f32 v[106:107], v[166:167], v[106:107] op_sel_hi:[0,1]
	v_pk_mul_f32 v[92:93], v[168:169], v[92:93] op_sel_hi:[0,1]
	v_mul_f32_e32 v116, v120, v116
	v_mul_f32_e32 v112, v116, v112
	v_mul_f32_e32 v116, 0xbfb8aa3b, v121
	v_exp_f32_e32 v116, v116
	v_pk_mul_f32 v[84:85], v[168:169], v[84:85] op_sel_hi:[0,1]
	v_pk_mul_f32 v[94:95], v[168:169], v[94:95] op_sel_hi:[0,1]
	v_pk_mul_f32 v[86:87], v[168:169], v[86:87] op_sel_hi:[0,1]
	v_add_f32_e32 v116, 1.0, v116
	v_rcp_f32_e32 v116, v116
	v_pk_mul_f32 v[88:89], v[168:169], v[88:89] op_sel_hi:[0,1]
	v_pk_mul_f32 v[90:91], v[168:169], v[90:91] op_sel_hi:[0,1]
	v_pk_mul_f32 v[76:77], v[170:171], v[76:77] op_sel_hi:[0,1]
	v_mul_f32_e32 v116, v121, v116
	v_mul_f32_e32 v113, v116, v113
	v_cvt_pk_bf16_f32 v116, v112, v113
	v_mul_f32_e32 v112, 0xbfb8aa3b, v122
	v_mul_f32_e32 v113, 0xbfb8aa3b, v123
	v_exp_f32_e32 v112, v112
	v_exp_f32_e32 v113, v113
	v_pk_mul_f32 v[68:69], v[170:171], v[68:69] op_sel_hi:[0,1]
	v_pk_mul_f32 v[78:79], v[170:171], v[78:79] op_sel_hi:[0,1]
	v_add_f32_e32 v112, 1.0, v112
	v_add_f32_e32 v113, 1.0, v113
	v_rcp_f32_e32 v112, v112
	v_rcp_f32_e32 v113, v113
	v_pk_mul_f32 v[70:71], v[170:171], v[70:71] op_sel_hi:[0,1]
	v_pk_mul_f32 v[72:73], v[170:171], v[72:73] op_sel_hi:[0,1]
	v_mul_f32_e32 v112, v122, v112
	v_mul_f32_e32 v113, v123, v113
	v_mul_f32_e32 v112, v112, v128
	v_mul_f32_e32 v113, v113, v129
	v_cvt_pk_bf16_f32 v117, v112, v113
	v_mov_b64_e32 v[112:113], s[92:93]
	v_mad_i64_i32 v[118:119], s[42:43], v169, s44, v[112:113]
	s_lshl_b32 s42, s89, 7
	s_ashr_i32 s43, s42, 31
	s_lshl_b64 s[42:43], s[42:43], 1
	v_lshl_add_u64 v[118:119], v[118:119], 0, s[42:43]
	v_lshl_add_u64 v[118:119], v[118:119], 0, v[144:145]
	global_store_dwordx4 v[118:119], v[114:117], off
	v_pk_mul_f32 v[74:75], v[170:171], v[74:75] op_sel_hi:[0,1]
	v_pk_mul_f32 v[60:61], v[172:173], v[60:61] op_sel_hi:[0,1]
	v_pk_mul_f32 v[114:115], v[166:167], v[98:99] op_sel_hi:[0,1]
	v_pk_mul_f32 v[98:99], v[166:167], v[96:97] op_sel_hi:[0,1]
	v_mul_f32_e32 v96, 0xbfb8aa3b, v108
	v_mul_f32_e32 v97, 0xbfb8aa3b, v109
	v_exp_f32_e32 v96, v96
	v_exp_f32_e32 v97, v97
	v_pk_mul_f32 v[52:53], v[172:173], v[52:53] op_sel_hi:[0,1]
	v_pk_mul_f32 v[62:63], v[172:173], v[62:63] op_sel_hi:[0,1]
	v_add_f32_e32 v96, 1.0, v96
	v_add_f32_e32 v97, 1.0, v97
	v_rcp_f32_e32 v96, v96
	v_rcp_f32_e32 v97, v97
	v_pk_mul_f32 v[54:55], v[172:173], v[54:55] op_sel_hi:[0,1]
	v_pk_mul_f32 v[56:57], v[172:173], v[56:57] op_sel_hi:[0,1]
	v_mul_f32_e32 v96, v108, v96
	v_mul_f32_e32 v97, v109, v97
	v_mul_f32_e32 v96, v96, v100
	v_mul_f32_e32 v97, v97, v101
	v_cvt_pk_bf16_f32 v96, v96, v97
	v_mul_f32_e32 v97, 0xbfb8aa3b, v110
	v_mul_f32_e32 v100, 0xbfb8aa3b, v111
	v_exp_f32_e32 v97, v97
	v_exp_f32_e32 v100, v100
	v_pk_mul_f32 v[58:59], v[172:173], v[58:59] op_sel_hi:[0,1]
	v_pk_mul_f32 v[44:45], v[174:175], v[44:45] op_sel_hi:[0,1]
	v_add_f32_e32 v97, 1.0, v97
	v_add_f32_e32 v100, 1.0, v100
	v_rcp_f32_e32 v97, v97
	v_rcp_f32_e32 v100, v100
	v_pk_mul_f32 v[36:37], v[174:175], v[36:37] op_sel_hi:[0,1]
	v_pk_mul_f32 v[46:47], v[174:175], v[46:47] op_sel_hi:[0,1]
	v_mul_f32_e32 v97, v110, v97
	v_mul_f32_e32 v100, v111, v100
	v_mul_f32_e32 v97, v97, v102
	v_mul_f32_e32 v100, v100, v103
	v_cvt_pk_bf16_f32 v97, v97, v100
	v_mul_f32_e32 v100, 0xbfb8aa3b, v104
	v_exp_f32_e32 v100, v100
	v_pk_mul_f32 v[38:39], v[174:175], v[38:39] op_sel_hi:[0,1]
	v_pk_mul_f32 v[40:41], v[174:175], v[40:41] op_sel_hi:[0,1]
	v_pk_mul_f32 v[42:43], v[174:175], v[42:43] op_sel_hi:[0,1]
	v_add_f32_e32 v100, 1.0, v100
	v_rcp_f32_e32 v100, v100
	v_pk_mul_f32 v[28:29], v[176:177], v[28:29] op_sel_hi:[0,1]
	v_pk_mul_f32 v[20:21], v[176:177], v[20:21] op_sel_hi:[0,1]
	v_pk_mul_f32 v[30:31], v[176:177], v[30:31] op_sel_hi:[0,1]
	v_mul_f32_e32 v100, v104, v100
; __device__ __forceinline__ unsigned pk2(float lo, float hi) { unsigned r; asm("v_cvt_pk_bf16_f32 %0, %1, %2" : "=v"(r) : "v"(lo), "v"(hi)); return r; }
; __device__ __forceinline__ float silu_mul(float g, float u) { return g * frcp(1.0f + fexp2(g * (-LOG2E))) * u; }
; __device__ __forceinline__ void epilogue(const f32x4 (&acc)[2][2][4][2], const Unit& u, int wr, int wc, int fr, int fq, int mode, bf16_t* out, int ld, bf16_t* proj, bf16_t* vt, bf16_t* km, bf16_t* vmt, const float* rs, const float (&rsv)[2][4]) {
;     ...
;                 const float r = rsv[ai][m];
;                 const f32x4 g0 = acc[ai][0][m][0] * r, g1 = acc[ai][0][m][1] * r, u0 = acc[ai][1][m][0] * r, u1 = acc[ai][1][m][1] * r;
;                 u32x4 w;
;                 w.x = pk2(silu_mul(g0.x, u0.x), silu_mul(g0.y, u0.y)); w.y = pk2(silu_mul(g0.z, u0.z), silu_mul(g0.w, u0.w));
;                 w.z = pk2(silu_mul(g1.x, u1.x), silu_mul(g1.y, u1.y)); w.w = pk2(silu_mul(g1.z, u1.z), silu_mul(g1.w, u1.w));
;                 *(u32x4*)(out + (size_t)(row0 + ai * HALF + m * 16) * DFF + u.pn * 128 + cb) = w;
	v_mul_f32_e32 v98, v100, v98
	v_mul_f32_e32 v100, 0xbfb8aa3b, v105
	v_exp_f32_e32 v100, v100
	v_pk_mul_f32 v[22:23], v[176:177], v[22:23] op_sel_hi:[0,1]
	v_pk_mul_f32 v[24:25], v[176:177], v[24:25] op_sel_hi:[0,1]
	v_pk_mul_f32 v[26:27], v[176:177], v[26:27] op_sel_hi:[0,1]
	v_add_f32_e32 v100, 1.0, v100
	v_rcp_f32_e32 v100, v100
	v_pk_mul_f32 v[12:13], v[178:179], v[12:13] op_sel_hi:[0,1]
	v_pk_mul_f32 v[4:5], v[178:179], v[4:5] op_sel_hi:[0,1]
	v_pk_mul_f32 v[14:15], v[178:179], v[14:15] op_sel_hi:[0,1]
	v_mul_f32_e32 v100, v105, v100
	v_mul_f32_e32 v99, v100, v99
	v_cvt_pk_bf16_f32 v98, v98, v99
	v_mul_f32_e32 v99, 0xbfb8aa3b, v106
	v_mul_f32_e32 v100, 0xbfb8aa3b, v107
	v_exp_f32_e32 v99, v99
	v_exp_f32_e32 v100, v100
	v_pk_mul_f32 v[6:7], v[178:179], v[6:7] op_sel_hi:[0,1]
	v_pk_mul_f32 v[8:9], v[178:179], v[8:9] op_sel_hi:[0,1]
	v_add_f32_e32 v99, 1.0, v99
	v_add_f32_e32 v100, 1.0, v100
	v_rcp_f32_e32 v99, v99
	v_rcp_f32_e32 v100, v100
	v_pk_mul_f32 v[10:11], v[178:179], v[10:11] op_sel_hi:[0,1]
	v_mul_f32_e32 v99, v106, v99
	v_mul_f32_e32 v100, v107, v100
	v_mul_f32_e32 v99, v99, v114
	v_mul_f32_e32 v100, v100, v115
	v_cvt_pk_bf16_f32 v99, v99, v100
	v_or_b32_e32 v100, 16, v169
	v_mad_i64_i32 v[100:101], s[80:81], v100, s44, v[112:113]
	v_lshl_add_u64 v[100:101], v[100:101], 0, s[42:43]
	v_lshl_add_u64 v[100:101], v[100:101], 0, v[144:145]
	global_store_dwordx4 v[100:101], v[96:99], off
	s_nop 1
	v_pk_mul_f32 v[96:97], v[168:169], v[82:83] op_sel_hi:[0,1]
	v_pk_mul_f32 v[82:83], v[168:169], v[80:81] op_sel_hi:[0,1]
	v_mul_f32_e32 v80, 0xbfb8aa3b, v92
	v_mul_f32_e32 v81, 0xbfb8aa3b, v93
	v_exp_f32_e32 v80, v80
	v_exp_f32_e32 v81, v81
	v_add_f32_e32 v80, 1.0, v80
	v_add_f32_e32 v81, 1.0, v81
	v_rcp_f32_e32 v80, v80
	v_rcp_f32_e32 v81, v81
	v_mul_f32_e32 v80, v92, v80
	v_mul_f32_e32 v81, v93, v81
	v_mul_f32_e32 v80, v80, v84
	v_mul_f32_e32 v81, v81, v85
	v_cvt_pk_bf16_f32 v80, v80, v81
	v_mul_f32_e32 v81, 0xbfb8aa3b, v94
	v_mul_f32_e32 v84, 0xbfb8aa3b, v95
	v_exp_f32_e32 v81, v81
	v_exp_f32_e32 v84, v84
	v_add_f32_e32 v81, 1.0, v81
	v_add_f32_e32 v84, 1.0, v84
	v_rcp_f32_e32 v81, v81
	v_rcp_f32_e32 v84, v84
	v_mul_f32_e32 v81, v94, v81
	v_mul_f32_e32 v84, v95, v84
	v_mul_f32_e32 v81, v81, v86
	v_mul_f32_e32 v84, v84, v87
	v_cvt_pk_bf16_f32 v81, v81, v84
	v_mul_f32_e32 v84, 0xbfb8aa3b, v88
	v_exp_f32_e32 v84, v84
	s_nop 0
	v_add_f32_e32 v84, 1.0, v84
	v_rcp_f32_e32 v84, v84
	s_nop 0
	v_mul_f32_e32 v84, v88, v84
	v_mul_f32_e32 v82, v84, v82
	v_mul_f32_e32 v84, 0xbfb8aa3b, v89
	v_exp_f32_e32 v84, v84
	s_nop 0
	v_add_f32_e32 v84, 1.0, v84
	v_rcp_f32_e32 v84, v84
	s_nop 0
	v_mul_f32_e32 v84, v89, v84
	v_mul_f32_e32 v83, v84, v83
	v_cvt_pk_bf16_f32 v82, v82, v83
	v_mul_f32_e32 v83, 0xbfb8aa3b, v90
	v_mul_f32_e32 v84, 0xbfb8aa3b, v91
	v_exp_f32_e32 v83, v83
	v_exp_f32_e32 v84, v84
	v_add_f32_e32 v83, 1.0, v83
	v_add_f32_e32 v84, 1.0, v84
	v_rcp_f32_e32 v83, v83
	v_rcp_f32_e32 v84, v84
	v_mul_f32_e32 v83, v90, v83
	v_mul_f32_e32 v84, v91, v84
	v_mul_f32_e32 v83, v83, v96
	v_mul_f32_e32 v84, v84, v97
	v_cvt_pk_bf16_f32 v83, v83, v84
	v_or_b32_e32 v84, 32, v169
	v_mad_i64_i32 v[84:85], s[80:81], v84, s44, v[112:113]
	v_lshl_add_u64 v[84:85], v[84:85], 0, s[42:43]
	v_lshl_add_u64 v[84:85], v[84:85], 0, v[144:145]
	global_store_dwordx4 v[84:85], v[80:83], off
	s_nop 1
	v_pk_mul_f32 v[80:81], v[170:171], v[66:67] op_sel_hi:[0,1]
	v_pk_mul_f32 v[66:67], v[170:171], v[64:65] op_sel_hi:[0,1]
	v_mul_f32_e32 v64, 0xbfb8aa3b, v76
	v_mul_f32_e32 v65, 0xbfb8aa3b, v77
	v_exp_f32_e32 v64, v64
	v_exp_f32_e32 v65, v65
	v_add_f32_e32 v64, 1.0, v64
	v_add_f32_e32 v65, 1.0, v65
	v_rcp_f32_e32 v64, v64
	v_rcp_f32_e32 v65, v65
	v_mul_f32_e32 v64, v76, v64
	v_mul_f32_e32 v65, v77, v65
	v_mul_f32_e32 v64, v64, v68
	v_mul_f32_e32 v65, v65, v69
	v_cvt_pk_bf16_f32 v64, v64, v65
	v_mul_f32_e32 v65, 0xbfb8aa3b, v78
	v_mul_f32_e32 v68, 0xbfb8aa3b, v79
	v_exp_f32_e32 v65, v65
	v_exp_f32_e32 v68, v68
	v_add_f32_e32 v65, 1.0, v65
	v_add_f32_e32 v68, 1.0, v68
	v_rcp_f32_e32 v65, v65
	v_rcp_f32_e32 v68, v68
	v_mul_f32_e32 v65, v78, v65
	v_mul_f32_e32 v68, v79, v68
	v_mul_f32_e32 v65, v65, v70
	v_mul_f32_e32 v68, v68, v71
	v_cvt_pk_bf16_f32 v65, v65, v68
	v_mul_f32_e32 v68, 0xbfb8aa3b, v72
	v_exp_f32_e32 v68, v68
	s_nop 0
	v_add_f32_e32 v68, 1.0, v68
	v_rcp_f32_e32 v68, v68
	s_nop 0
	v_mul_f32_e32 v68, v72, v68
	v_mul_f32_e32 v66, v68, v66
	v_mul_f32_e32 v68, 0xbfb8aa3b, v73
	v_exp_f32_e32 v68, v68
	s_nop 0
	v_add_f32_e32 v68, 1.0, v68
	v_rcp_f32_e32 v68, v68
	s_nop 0
	v_mul_f32_e32 v68, v73, v68
	v_mul_f32_e32 v67, v68, v67
	v_cvt_pk_bf16_f32 v66, v66, v67
	v_mul_f32_e32 v67, 0xbfb8aa3b, v74
	v_mul_f32_e32 v68, 0xbfb8aa3b, v75
	v_exp_f32_e32 v67, v67
	v_exp_f32_e32 v68, v68
	v_add_f32_e32 v67, 1.0, v67
	v_add_f32_e32 v68, 1.0, v68
	v_rcp_f32_e32 v67, v67
	v_rcp_f32_e32 v68, v68
	v_mul_f32_e32 v67, v74, v67
	v_mul_f32_e32 v68, v75, v68
	v_mul_f32_e32 v67, v67, v80
	v_mul_f32_e32 v68, v68, v81
	v_cvt_pk_bf16_f32 v67, v67, v68
	v_or_b32_e32 v68, 48, v169
	v_mad_i64_i32 v[68:69], s[80:81], v68, s44, v[112:113]
	v_lshl_add_u64 v[68:69], v[68:69], 0, s[42:43]
	v_lshl_add_u64 v[68:69], v[68:69], 0, v[144:145]
	global_store_dwordx4 v[68:69], v[64:67], off
	s_nop 1
	v_pk_mul_f32 v[64:65], v[172:173], v[50:51] op_sel_hi:[0,1]
	v_pk_mul_f32 v[50:51], v[172:173], v[48:49] op_sel_hi:[0,1]
	v_mul_f32_e32 v48, 0xbfb8aa3b, v60
	v_mul_f32_e32 v49, 0xbfb8aa3b, v61
	v_exp_f32_e32 v48, v48
	v_exp_f32_e32 v49, v49
	v_add_u32_e32 v66, 0x80, v169
	v_add_f32_e32 v48, 1.0, v48
	v_add_f32_e32 v49, 1.0, v49
	v_rcp_f32_e32 v48, v48
	v_rcp_f32_e32 v49, v49
	v_mul_f32_e32 v48, v60, v48
	v_mul_f32_e32 v49, v61, v49
; __device__ __forceinline__ unsigned pk2(float lo, float hi) { unsigned r; asm("v_cvt_pk_bf16_f32 %0, %1, %2" : "=v"(r) : "v"(lo), "v"(hi)); return r; }
; __device__ __forceinline__ float silu_mul(float g, float u) { return g * frcp(1.0f + fexp2(g * (-LOG2E))) * u; }
; __device__ __forceinline__ void epilogue(const f32x4 (&acc)[2][2][4][2], const Unit& u, int wr, int wc, int fr, int fq, int mode, bf16_t* out, int ld, bf16_t* proj, bf16_t* vt, bf16_t* km, bf16_t* vmt, const float* rs, const float (&rsv)[2][4]) {
;     ...
;                 const float r = rsv[ai][m];
;                 const f32x4 g0 = acc[ai][0][m][0] * r, g1 = acc[ai][0][m][1] * r, u0 = acc[ai][1][m][0] * r, u1 = acc[ai][1][m][1] * r;
;                 u32x4 w;
;                 w.x = pk2(silu_mul(g0.x, u0.x), silu_mul(g0.y, u0.y)); w.y = pk2(silu_mul(g0.z, u0.z), silu_mul(g0.w, u0.w));
;                 w.z = pk2(silu_mul(g1.x, u1.x), silu_mul(g1.y, u1.y)); w.w = pk2(silu_mul(g1.z, u1.z), silu_mul(g1.w, u1.w));
;                 *(u32x4*)(out + (size_t)(row0 + ai * HALF + m * 16) * DFF + u.pn * 128 + cb) = w;
	v_mul_f32_e32 v48, v48, v52
	v_mul_f32_e32 v49, v49, v53
	v_cvt_pk_bf16_f32 v48, v48, v49
	v_mul_f32_e32 v49, 0xbfb8aa3b, v62
	v_mul_f32_e32 v52, 0xbfb8aa3b, v63
	v_exp_f32_e32 v49, v49
	v_exp_f32_e32 v52, v52
	v_add_f32_e32 v49, 1.0, v49
	v_add_f32_e32 v52, 1.0, v52
	v_rcp_f32_e32 v49, v49
	v_rcp_f32_e32 v52, v52
	v_mul_f32_e32 v49, v62, v49
	v_mul_f32_e32 v52, v63, v52
	v_mul_f32_e32 v49, v49, v54
	v_mul_f32_e32 v52, v52, v55
	v_cvt_pk_bf16_f32 v49, v49, v52
	v_mul_f32_e32 v52, 0xbfb8aa3b, v56
	v_exp_f32_e32 v52, v52
	s_nop 0
	v_add_f32_e32 v52, 1.0, v52
	v_rcp_f32_e32 v52, v52
	s_nop 0
	v_mul_f32_e32 v52, v56, v52
	v_mul_f32_e32 v50, v52, v50
	v_mul_f32_e32 v52, 0xbfb8aa3b, v57
	v_exp_f32_e32 v52, v52
	s_nop 0
	v_add_f32_e32 v52, 1.0, v52
	v_rcp_f32_e32 v52, v52
	s_nop 0
	v_mul_f32_e32 v52, v57, v52
	v_mul_f32_e32 v51, v52, v51
	v_cvt_pk_bf16_f32 v50, v50, v51
	v_mul_f32_e32 v51, 0xbfb8aa3b, v58
	v_mul_f32_e32 v52, 0xbfb8aa3b, v59
	v_exp_f32_e32 v51, v51
	v_exp_f32_e32 v52, v52
	v_add_f32_e32 v51, 1.0, v51
	v_add_f32_e32 v52, 1.0, v52
	v_rcp_f32_e32 v51, v51
	v_rcp_f32_e32 v52, v52
	v_mul_f32_e32 v51, v58, v51
	v_mul_f32_e32 v52, v59, v52
	v_mul_f32_e32 v51, v51, v64
	v_mul_f32_e32 v52, v52, v65
	v_cvt_pk_bf16_f32 v51, v51, v52
	v_mad_i64_i32 v[52:53], s[80:81], v66, s44, v[112:113]
	v_lshl_add_u64 v[52:53], v[52:53], 0, s[42:43]
	v_lshl_add_u64 v[52:53], v[52:53], 0, v[144:145]
	global_store_dwordx4 v[52:53], v[48:51], off
	s_nop 1
	v_pk_mul_f32 v[48:49], v[174:175], v[34:35] op_sel_hi:[0,1]
	v_pk_mul_f32 v[34:35], v[174:175], v[32:33] op_sel_hi:[0,1]
	v_mul_f32_e32 v32, 0xbfb8aa3b, v44
	v_mul_f32_e32 v33, 0xbfb8aa3b, v45
	v_exp_f32_e32 v32, v32
	v_exp_f32_e32 v33, v33
	v_add_f32_e32 v32, 1.0, v32
	v_add_f32_e32 v33, 1.0, v33
	v_rcp_f32_e32 v32, v32
	v_rcp_f32_e32 v33, v33
	v_mul_f32_e32 v32, v44, v32
	v_mul_f32_e32 v33, v45, v33
	v_mul_f32_e32 v32, v32, v36
	v_mul_f32_e32 v33, v33, v37
	v_cvt_pk_bf16_f32 v32, v32, v33
	v_mul_f32_e32 v33, 0xbfb8aa3b, v46
	v_mul_f32_e32 v36, 0xbfb8aa3b, v47
	v_exp_f32_e32 v33, v33
	v_exp_f32_e32 v36, v36
	v_add_f32_e32 v33, 1.0, v33
	v_add_f32_e32 v36, 1.0, v36
	v_rcp_f32_e32 v33, v33
	v_rcp_f32_e32 v36, v36
	v_mul_f32_e32 v33, v46, v33
	v_mul_f32_e32 v36, v47, v36
	v_mul_f32_e32 v33, v33, v38
	v_mul_f32_e32 v36, v36, v39
	v_cvt_pk_bf16_f32 v33, v33, v36
	v_mul_f32_e32 v36, 0xbfb8aa3b, v40
	v_exp_f32_e32 v36, v36
	s_nop 0
	v_add_f32_e32 v36, 1.0, v36
	v_rcp_f32_e32 v36, v36
	s_nop 0
	v_mul_f32_e32 v36, v40, v36
	v_mul_f32_e32 v34, v36, v34
	v_mul_f32_e32 v36, 0xbfb8aa3b, v41
	v_exp_f32_e32 v36, v36
	s_nop 0
	v_add_f32_e32 v36, 1.0, v36
	v_rcp_f32_e32 v36, v36
	s_nop 0
	v_mul_f32_e32 v36, v41, v36
	v_mul_f32_e32 v35, v36, v35
	v_cvt_pk_bf16_f32 v34, v34, v35
	v_mul_f32_e32 v35, 0xbfb8aa3b, v42
	v_mul_f32_e32 v36, 0xbfb8aa3b, v43
	v_exp_f32_e32 v35, v35
	v_exp_f32_e32 v36, v36
	v_add_f32_e32 v35, 1.0, v35
	v_add_f32_e32 v36, 1.0, v36
	v_rcp_f32_e32 v35, v35
	v_rcp_f32_e32 v36, v36
	v_mul_f32_e32 v35, v42, v35
	v_mul_f32_e32 v36, v43, v36
	v_mul_f32_e32 v35, v35, v48
	v_mul_f32_e32 v36, v36, v49
	v_cvt_pk_bf16_f32 v35, v35, v36
	v_add_u32_e32 v36, 0x90, v169
	v_mad_i64_i32 v[36:37], s[80:81], v36, s44, v[112:113]
	v_lshl_add_u64 v[36:37], v[36:37], 0, s[42:43]
	v_lshl_add_u64 v[36:37], v[36:37], 0, v[144:145]
	global_store_dwordx4 v[36:37], v[32:35], off
	s_nop 1
	v_pk_mul_f32 v[32:33], v[176:177], v[18:19] op_sel_hi:[0,1]
	v_pk_mul_f32 v[18:19], v[176:177], v[16:17] op_sel_hi:[0,1]
	v_mul_f32_e32 v16, 0xbfb8aa3b, v28
	v_mul_f32_e32 v17, 0xbfb8aa3b, v29
; __device__ __forceinline__ unsigned pk2(float lo, float hi) { unsigned r; asm("v_cvt_pk_bf16_f32 %0, %1, %2" : "=v"(r) : "v"(lo), "v"(hi)); return r; }
; __device__ __forceinline__ float silu_mul(float g, float u) { return g * frcp(1.0f + fexp2(g * (-LOG2E))) * u; }
; #define PG8_BAR __builtin_amdgcn_s_barrier()
; __device__ __forceinline__ void epilogue(const f32x4 (&acc)[2][2][4][2], const Unit& u, int wr, int wc, int fr, int fq, int mode, bf16_t* out, int ld, bf16_t* proj, bf16_t* vt, bf16_t* km, bf16_t* vmt, const float* rs, const float (&rsv)[2][4]) {
;     ...
;                 const float r = rsv[ai][m];
;                 const f32x4 g0 = acc[ai][0][m][0] * r, g1 = acc[ai][0][m][1] * r, u0 = acc[ai][1][m][0] * r, u1 = acc[ai][1][m][1] * r;
;                 u32x4 w;
;                 w.x = pk2(silu_mul(g0.x, u0.x), silu_mul(g0.y, u0.y)); w.y = pk2(silu_mul(g0.z, u0.z), silu_mul(g0.w, u0.w));
;                 w.z = pk2(silu_mul(g1.x, u1.x), silu_mul(g1.y, u1.y)); w.w = pk2(silu_mul(g1.z, u1.z), silu_mul(g1.w, u1.w));
;                 *(u32x4*)(out + (size_t)(row0 + ai * HALF + m * 16) * DFF + u.pn * 128 + cb) = w;
;             }
; __device__ __forceinline__ void gemm_phase(LAS unsigned char* lds, const GP p, const int tid) {
;     ...
;         if (!has_next) break;
; #pragma unroll
;         for (int a = 0; a < 2; ++a)
; #pragma unroll
;             for (int b = 0; b < 2; ++b)
; #pragma unroll
;                 for (int m = 0; m < 4; ++m)
; #pragma unroll
;                     for (int n = 0; n < 2; ++n) acc[a][b][m][n] = (f32x4){0.f, 0.f, 0.f, 0.f};
;         cur = nxt; cA = nA; cB = nB; ++ui;
;         if (wr == 1) PG8_BAR;
	v_exp_f32_e32 v16, v16
	v_exp_f32_e32 v17, v17
	v_add_f32_e32 v16, 1.0, v16
	v_add_f32_e32 v17, 1.0, v17
	v_rcp_f32_e32 v16, v16
	v_rcp_f32_e32 v17, v17
	v_mul_f32_e32 v16, v28, v16
	v_mul_f32_e32 v17, v29, v17
	v_mul_f32_e32 v16, v16, v20
	v_mul_f32_e32 v17, v17, v21
	v_cvt_pk_bf16_f32 v16, v16, v17
	v_mul_f32_e32 v17, 0xbfb8aa3b, v30
	v_mul_f32_e32 v20, 0xbfb8aa3b, v31
	v_exp_f32_e32 v17, v17
	v_exp_f32_e32 v20, v20
	v_add_f32_e32 v17, 1.0, v17
	v_add_f32_e32 v20, 1.0, v20
	v_rcp_f32_e32 v17, v17
	v_rcp_f32_e32 v20, v20
	v_mul_f32_e32 v17, v30, v17
	v_mul_f32_e32 v20, v31, v20
	v_mul_f32_e32 v17, v17, v22
	v_mul_f32_e32 v20, v20, v23
	v_cvt_pk_bf16_f32 v17, v17, v20
	v_mul_f32_e32 v20, 0xbfb8aa3b, v24
	v_exp_f32_e32 v20, v20
	s_nop 0
	v_add_f32_e32 v20, 1.0, v20
	v_rcp_f32_e32 v20, v20
	s_nop 0
	v_mul_f32_e32 v20, v24, v20
	v_mul_f32_e32 v18, v20, v18
	v_mul_f32_e32 v20, 0xbfb8aa3b, v25
	v_exp_f32_e32 v20, v20
	s_nop 0
	v_add_f32_e32 v20, 1.0, v20
	v_rcp_f32_e32 v20, v20
	s_nop 0
	v_mul_f32_e32 v20, v25, v20
	v_mul_f32_e32 v19, v20, v19
	v_cvt_pk_bf16_f32 v18, v18, v19
	v_mul_f32_e32 v19, 0xbfb8aa3b, v26
	v_mul_f32_e32 v20, 0xbfb8aa3b, v27
	v_exp_f32_e32 v19, v19
	v_exp_f32_e32 v20, v20
	v_add_f32_e32 v19, 1.0, v19
	v_add_f32_e32 v20, 1.0, v20
	v_rcp_f32_e32 v19, v19
	v_rcp_f32_e32 v20, v20
	v_mul_f32_e32 v19, v26, v19
	v_mul_f32_e32 v20, v27, v20
	v_mul_f32_e32 v19, v19, v32
	v_mul_f32_e32 v20, v20, v33
	v_cvt_pk_bf16_f32 v19, v19, v20
	v_add_u32_e32 v20, 0xa0, v169
	v_mad_i64_i32 v[20:21], s[80:81], v20, s44, v[112:113]
	v_lshl_add_u64 v[20:21], v[20:21], 0, s[42:43]
	v_lshl_add_u64 v[20:21], v[20:21], 0, v[144:145]
	global_store_dwordx4 v[20:21], v[16:19], off
	s_nop 1
	v_pk_mul_f32 v[16:17], v[178:179], v[2:3] op_sel_hi:[0,1]
	v_pk_mul_f32 v[2:3], v[178:179], v[0:1] op_sel_hi:[0,1]
	v_mul_f32_e32 v0, 0xbfb8aa3b, v12
	v_mul_f32_e32 v1, 0xbfb8aa3b, v13
	v_exp_f32_e32 v0, v0
	v_exp_f32_e32 v1, v1
	v_add_f32_e32 v0, 1.0, v0
	v_add_f32_e32 v1, 1.0, v1
	v_rcp_f32_e32 v0, v0
	v_rcp_f32_e32 v1, v1
	v_mul_f32_e32 v0, v12, v0
	v_mul_f32_e32 v1, v13, v1
	v_mul_f32_e32 v0, v0, v4
	v_mul_f32_e32 v1, v1, v5
	v_cvt_pk_bf16_f32 v0, v0, v1
	v_mul_f32_e32 v1, 0xbfb8aa3b, v14
	v_mul_f32_e32 v4, 0xbfb8aa3b, v15
	v_exp_f32_e32 v1, v1
	v_exp_f32_e32 v4, v4
	v_add_f32_e32 v1, 1.0, v1
	v_add_f32_e32 v4, 1.0, v4
	v_rcp_f32_e32 v1, v1
	v_rcp_f32_e32 v4, v4
	v_mul_f32_e32 v1, v14, v1
	v_mul_f32_e32 v4, v15, v4
	v_mul_f32_e32 v1, v1, v6
	v_mul_f32_e32 v4, v4, v7
	v_cvt_pk_bf16_f32 v1, v1, v4
	v_mul_f32_e32 v4, 0xbfb8aa3b, v8
	v_exp_f32_e32 v4, v4
	s_nop 0
	v_add_f32_e32 v4, 1.0, v4
	v_rcp_f32_e32 v4, v4
	s_nop 0
	v_mul_f32_e32 v4, v8, v4
	v_mul_f32_e32 v2, v4, v2
	v_mul_f32_e32 v4, 0xbfb8aa3b, v9
	v_exp_f32_e32 v4, v4
	s_nop 0
	v_add_f32_e32 v4, 1.0, v4
	v_rcp_f32_e32 v4, v4
	s_nop 0
	v_mul_f32_e32 v4, v9, v4
	v_mul_f32_e32 v3, v4, v3
	v_cvt_pk_bf16_f32 v2, v2, v3
	v_mul_f32_e32 v3, 0xbfb8aa3b, v10
	v_mul_f32_e32 v4, 0xbfb8aa3b, v11
	v_exp_f32_e32 v3, v3
	v_exp_f32_e32 v4, v4
	v_add_f32_e32 v3, 1.0, v3
	v_add_f32_e32 v4, 1.0, v4
	v_rcp_f32_e32 v3, v3
	v_rcp_f32_e32 v4, v4
	v_mul_f32_e32 v3, v10, v3
	v_mul_f32_e32 v4, v11, v4
	v_mul_f32_e32 v3, v3, v16
	v_mul_f32_e32 v4, v4, v17
	v_cvt_pk_bf16_f32 v3, v3, v4
	v_add_u32_e32 v4, 0xb0, v169
	v_mad_i64_i32 v[4:5], s[80:81], v4, s44, v[112:113]
	v_lshl_add_u64 v[4:5], v[4:5], 0, s[42:43]
	v_lshl_add_u64 v[4:5], v[4:5], 0, v[144:145]
	global_store_dwordx4 v[4:5], v[0:3], off
	s_and_b64 vcc, exec, s[40:41]
	s_mov_b64 s[40:41], -1
	s_cbranch_vccnz .LBB0_84

; #define LAS __attribute__((address_space(3)))
; __device__ __forceinline__ unsigned pk2(float lo, float hi) { unsigned r; asm("v_cvt_pk_bf16_f32 %0, %1, %2" : "=v"(r) : "v"(lo), "v"(hi)); return r; }
; __device__ __forceinline__ float bflo(unsigned u) { return __uint_as_float(u << 16); }
; __device__ __forceinline__ float bfhi(unsigned u) { return __uint_as_float(u & 0xffff0000u); }
; __device__ __forceinline__ void p5_unit(const Ptrs& P, LAS unsigned char* lds, int unit, int tid_in, int wave) {
;     ...
;         {   const int g = tid >> 7, tok = tid & 127; float a = 0.f, q2 = 0.f;
; #pragma unroll 8
;             for (int tt = 0; tt < 32; ++tt) { const f32x2 v2 = *(const LAS f32x2*)(st + ((g * 32 + tt) * 128 + tok) * 2); a += v2.x; q2 += v2.y; }
;             const float mu = a * (1.0f / 128), var = fmaxf(q2 * (1.0f / 128) - mu * mu, 0.f);
;             *(LAS f32x2*)(st2 + (g * 128 + tok) * 2) = (f32x2){mu, rsqrtf(var + EPS)}; }
;         __syncthreads();
; #pragma unroll
;         for (int g = 0; g < 4; ++g) {
;             const LAS f32x4* mp = (const LAS f32x4*)(st2 + (g * 128 + p * 8) * 2);
;             const f32x4 m01 = mp[0], m23 = mp[1], m45 = mp[2], m67 = mp[3];
; #pragma unroll
;             for (int jj = 0; jj < 4; ++jj) { const u32x4 w = d[4 * g + jj]; const int c = t + 32 * jj;
;                 const float lg = lgv[4 * g + jj], lb = lbv[4 * g + jj];
;                 u32x4 o;
;                 o.x = pk2((bflo(w.x) - m01.x) * m01.y * lg + lb, (bfhi(w.x) - m01.z) * m01.w * lg + lb);
;                 o.y = pk2((bflo(w.y) - m23.x) * m23.y * lg + lb, (bfhi(w.y) - m23.z) * m23.w * lg + lb);
;                 o.z = pk2((bflo(w.z) - m45.x) * m45.y * lg + lb, (bfhi(w.z) - m45.z) * m45.w * lg + lb);
;                 o.w = pk2((bflo(w.w) - m67.x) * m67.y * lg + lb, (bfhi(w.w) - m67.z) * m67.w * lg + lb);
;                 *(LAS u32x4*)(vvt + (g * 128 + c) * VVT_LD + p * 8) = o; }
.LBB0_218:
	v_add_u32_e32 v172, s10, v136
	ds_read2st64_b64 v[168:171], v172 offset1:2
	s_addk_i32 s10, 0x2000
	s_cmpk_eq_u32 s10, 0x8000
	s_waitcnt lgkmcnt(0)
	v_pk_add_f32 v[10:11], v[10:11], v[168:169]
	s_nop 0
	v_pk_add_f32 v[10:11], v[10:11], v[170:171]
	ds_read2st64_b64 v[168:171], v172 offset0:4 offset1:6
	s_waitcnt lgkmcnt(0)
	v_pk_add_f32 v[10:11], v[10:11], v[168:169]
	s_nop 0
	v_pk_add_f32 v[10:11], v[10:11], v[170:171]
	ds_read2st64_b64 v[168:171], v172 offset0:8 offset1:10
	s_waitcnt lgkmcnt(0)
	v_pk_add_f32 v[10:11], v[10:11], v[168:169]
	s_nop 0
	v_pk_add_f32 v[10:11], v[10:11], v[170:171]
	ds_read2st64_b64 v[168:171], v172 offset0:12 offset1:14
	s_waitcnt lgkmcnt(0)
	v_pk_add_f32 v[10:11], v[10:11], v[168:169]
	s_nop 0
	v_pk_add_f32 v[10:11], v[10:11], v[170:171]
	s_cbranch_scc0 .LBB0_218
	s_brev_b32 s10, 60
	v_pk_mul_f32 v[10:11], v[10:11], s[10:11] op_sel_hi:[1,0]
	v_readlane_b32 s0, v251, 54
	v_fma_f32 v11, -v10, v10, v11
	v_max_f32_e32 v11, 0, v11
	v_add_f32_e32 v11, 0x358637bd, v11
	v_mul_f32_e32 v136, 0x4b800000, v11
	v_cmp_gt_f32_e32 vcc, s45, v11
	v_add_u32_e32 v135, s0, v135
	s_movk_i32 s34, 0x110
	v_cndmask_b32_e32 v11, v11, v136, vcc
	v_rsq_f32_e32 v11, v11
	v_mul_lo_u32 v48, v48, s34
	s_or_b32 s42, s9, s7
	v_readlane_b32 s30, v252, 18
	v_mul_f32_e32 v136, 0x45800000, v11
	v_cndmask_b32_e32 v11, v11, v136, vcc
	ds_write_b64 v135, v[10:11]
	v_add_u32_e32 v11, s0, v140
	s_waitcnt lgkmcnt(0)
	s_barrier
	ds_read_b128 v[168:171], v11
	ds_read_b128 v[172:175], v11 offset:16
	ds_read_b128 v[176:179], v11 offset:32
	ds_read_b128 v[180:183], v11 offset:48
	v_lshlrev_b32_e32 v10, 1, v134
	v_add3_u32 v10, 0, v10, v48
	v_readlane_b32 s0, v253, 5
	s_waitcnt lgkmcnt(3)
	v_sub_f32_e32 v110, v110, v168
	v_mul_f32_e32 v110, v169, v110
	v_sub_f32_e32 v111, v111, v170
	s_waitcnt vmcnt(23)
	v_fma_f32 v110, v166, v110, v167
	v_mul_f32_e32 v111, v171, v111
	v_fma_f32 v111, v166, v111, v167
	v_cvt_pk_bf16_f32 v184, v110, v111
	s_waitcnt lgkmcnt(2)
	v_sub_f32_e32 v110, v120, v172
	v_mul_f32_e32 v110, v173, v110
	v_sub_f32_e32 v111, v121, v174
	v_fma_f32 v110, v166, v110, v167
	v_mul_f32_e32 v111, v175, v111
	v_fma_f32 v111, v166, v111, v167
	v_cvt_pk_bf16_f32 v185, v110, v111
	s_waitcnt lgkmcnt(1)
	v_sub_f32_e32 v110, v128, v176
	v_sub_f32_e32 v48, v80, v168
	v_mul_f32_e32 v110, v177, v110
	v_sub_f32_e32 v111, v129, v178
	v_mul_f32_e32 v48, v169, v48
	v_sub_f32_e32 v80, v81, v170
	v_fma_f32 v110, v166, v110, v167
	v_mul_f32_e32 v111, v179, v111
	s_waitcnt vmcnt(22)
	v_fma_f32 v48, v164, v48, v165
	v_mul_f32_e32 v80, v171, v80
	v_fma_f32 v111, v166, v111, v167
	v_cvt_pk_bf16_f32 v186, v110, v111
	s_waitcnt lgkmcnt(0)
	v_sub_f32_e32 v110, v132, v180
	v_fma_f32 v80, v164, v80, v165
	v_cvt_pk_bf16_f32 v132, v48, v80
	v_sub_f32_e32 v48, v98, v172
	v_mul_f32_e32 v48, v173, v48
	v_sub_f32_e32 v80, v99, v174
	v_fma_f32 v48, v164, v48, v165
	v_mul_f32_e32 v80, v175, v80
	v_sub_f32_e32 v111, v133, v182
	v_fma_f32 v80, v164, v80, v165
	v_cvt_pk_bf16_f32 v133, v48, v80
	v_sub_f32_e32 v48, v114, v176
	v_mul_f32_e32 v48, v177, v48
	v_sub_f32_e32 v80, v115, v178
	v_fma_f32 v48, v164, v48, v165
	v_mul_f32_e32 v80, v179, v80
	v_fma_f32 v80, v164, v80, v165
	v_cvt_pk_bf16_f32 v134, v48, v80
	v_sub_f32_e32 v48, v124, v180
	v_mul_f32_e32 v48, v181, v48
	v_sub_f32_e32 v80, v125, v182
	v_fma_f32 v48, v164, v48, v165
	v_mul_f32_e32 v80, v183, v80
	v_fmac_f32_e32 v165, v164, v80
	v_cvt_pk_bf16_f32 v135, v48, v165
	v_sub_f32_e32 v48, v58, v168
	v_mul_f32_e32 v48, v169, v48
	v_sub_f32_e32 v58, v59, v170
	s_waitcnt vmcnt(21)
	v_fma_f32 v48, v162, v48, v163
	v_mul_f32_e32 v58, v171, v58
	ds_write_b128 v10, v[132:135] offset:8704
	v_fma_f32 v58, v162, v58, v163
	v_cvt_pk_bf16_f32 v132, v48, v58
	v_sub_f32_e32 v48, v70, v172
	v_mul_f32_e32 v48, v173, v48
	v_sub_f32_e32 v58, v71, v174
	v_fma_f32 v48, v162, v48, v163
	v_mul_f32_e32 v58, v175, v58
	v_fma_f32 v58, v162, v58, v163
	v_cvt_pk_bf16_f32 v133, v48, v58
	v_sub_f32_e32 v48, v90, v176
	v_mul_f32_e32 v48, v177, v48
	v_sub_f32_e32 v58, v91, v178
	v_fma_f32 v48, v162, v48, v163
	v_mul_f32_e32 v58, v179, v58
	v_fma_f32 v58, v162, v58, v163
	v_cvt_pk_bf16_f32 v134, v48, v58
	v_sub_f32_e32 v48, v106, v180
	v_mul_f32_e32 v48, v181, v48
	v_sub_f32_e32 v58, v107, v182
	v_fma_f32 v48, v162, v48, v163
	v_mul_f32_e32 v58, v183, v58
	v_fmac_f32_e32 v163, v162, v58
	v_cvt_pk_bf16_f32 v135, v48, v163
	v_sub_f32_e32 v48, v52, v168
	v_sub_f32_e32 v52, v53, v170
	v_mul_f32_e32 v48, v169, v48
	v_mul_f32_e32 v52, v171, v52
	s_waitcnt vmcnt(20)
	v_fma_f32 v48, v160, v48, v161
	v_fma_f32 v52, v160, v52, v161
	v_cvt_pk_bf16_f32 v58, v48, v52
	v_sub_f32_e32 v48, v56, v172
	v_sub_f32_e32 v52, v57, v174
	v_mul_f32_e32 v48, v173, v48
	v_mul_f32_e32 v52, v175, v52
	v_fma_f32 v48, v160, v48, v161
	v_fma_f32 v52, v160, v52, v161
	v_cvt_pk_bf16_f32 v59, v48, v52
	v_sub_f32_e32 v48, v60, v176
	v_sub_f32_e32 v52, v61, v178
	v_mul_f32_e32 v48, v177, v48
	v_mul_f32_e32 v52, v179, v52
	v_fma_f32 v48, v160, v48, v161
	v_fma_f32 v52, v160, v52, v161
	v_cvt_pk_bf16_f32 v60, v48, v52
	v_sub_f32_e32 v48, v76, v180
	v_sub_f32_e32 v52, v77, v182
	v_mul_f32_e32 v110, v181, v110
	v_mul_f32_e32 v111, v183, v111
	v_mul_f32_e32 v48, v181, v48
	v_mul_f32_e32 v52, v183, v52
	v_fma_f32 v110, v166, v110, v167
	v_fmac_f32_e32 v167, v166, v111
	v_cvt_pk_bf16_f32 v187, v110, v167
	ds_write_b128 v10, v[184:187]
	ds_write_b128 v10, v[132:135] offset:17408
	v_fma_f32 v48, v160, v48, v161
	v_fmac_f32_e32 v161, v160, v52
	v_cvt_pk_bf16_f32 v61, v48, v161
	ds_write_b128 v10, v[58:61] offset:26112
	ds_read_b128 v[56:59], v11 offset:1024
	ds_read_b128 v[132:135], v11 offset:1040
	ds_read_b128 v[160:163], v11 offset:1056
	ds_read_b128 v[164:167], v11 offset:1072
	s_lshl_b32 s7, s8, 6
	s_waitcnt lgkmcnt(3)
; #define LAS __attribute__((address_space(3)))
; __device__ __forceinline__ unsigned pk2(float lo, float hi) { unsigned r; asm("v_cvt_pk_bf16_f32 %0, %1, %2" : "=v"(r) : "v"(lo), "v"(hi)); return r; }
; __device__ __forceinline__ float bflo(unsigned u) { return __uint_as_float(u << 16); }
; __device__ __forceinline__ float bfhi(unsigned u) { return __uint_as_float(u & 0xffff0000u); }
; __device__ __forceinline__ void p5_unit(const Ptrs& P, LAS unsigned char* lds, int unit, int tid_in, int wave) {
;     ...
; #pragma unroll
;         for (int g = 0; g < 4; ++g) {
;             const LAS f32x4* mp = (const LAS f32x4*)(st2 + (g * 128 + p * 8) * 2);
;             const f32x4 m01 = mp[0], m23 = mp[1], m45 = mp[2], m67 = mp[3];
; #pragma unroll
;             for (int jj = 0; jj < 4; ++jj) { const u32x4 w = d[4 * g + jj]; const int c = t + 32 * jj;
;                 const float lg = lgv[4 * g + jj], lb = lbv[4 * g + jj];
;                 u32x4 o;
;                 o.x = pk2((bflo(w.x) - m01.x) * m01.y * lg + lb, (bfhi(w.x) - m01.z) * m01.w * lg + lb);
;                 o.y = pk2((bflo(w.y) - m23.x) * m23.y * lg + lb, (bfhi(w.y) - m23.z) * m23.w * lg + lb);
;                 o.z = pk2((bflo(w.z) - m45.x) * m45.y * lg + lb, (bfhi(w.z) - m45.z) * m45.w * lg + lb);
;                 o.w = pk2((bflo(w.w) - m67.x) * m67.y * lg + lb, (bfhi(w.w) - m67.z) * m67.w * lg + lb);
;                 *(LAS u32x4*)(vvt + (g * 128 + c) * VVT_LD + p * 8) = o; }
	v_sub_f32_e32 v48, v96, v56
	v_mul_f32_e32 v48, v57, v48
	v_sub_f32_e32 v52, v97, v58
	s_waitcnt vmcnt(19)
	v_fma_f32 v48, v158, v48, v159
	v_mul_f32_e32 v52, v59, v52
	v_fma_f32 v52, v158, v52, v159
	v_cvt_pk_bf16_f32 v96, v48, v52
	s_waitcnt lgkmcnt(2)
	v_sub_f32_e32 v48, v112, v132
	v_mul_f32_e32 v48, v133, v48
	v_sub_f32_e32 v52, v113, v134
	v_fma_f32 v48, v158, v48, v159
	v_mul_f32_e32 v52, v135, v52
	v_fma_f32 v52, v158, v52, v159
	v_cvt_pk_bf16_f32 v97, v48, v52
	s_waitcnt lgkmcnt(1)
	v_sub_f32_e32 v48, v122, v160
	v_mul_f32_e32 v48, v161, v48
	v_sub_f32_e32 v52, v123, v162
	v_fma_f32 v48, v158, v48, v159
	v_mul_f32_e32 v52, v163, v52
	v_fma_f32 v52, v158, v52, v159
	v_cvt_pk_bf16_f32 v98, v48, v52
	s_waitcnt lgkmcnt(0)
	v_sub_f32_e32 v48, v130, v164
	v_mul_f32_e32 v48, v165, v48
	v_sub_f32_e32 v52, v131, v166
	v_fma_f32 v48, v158, v48, v159
	v_mul_f32_e32 v52, v167, v52
	v_fmac_f32_e32 v159, v158, v52
	v_cvt_pk_bf16_f32 v99, v48, v159
	v_sub_f32_e32 v48, v68, v56
	v_mul_f32_e32 v48, v57, v48
	v_sub_f32_e32 v52, v69, v58
	s_waitcnt vmcnt(18)
	v_fma_f32 v48, v156, v48, v157
	v_mul_f32_e32 v52, v59, v52
	v_fma_f32 v52, v156, v52, v157
	v_cvt_pk_bf16_f32 v68, v48, v52
	v_sub_f32_e32 v48, v88, v132
	v_mul_f32_e32 v48, v133, v48
	v_sub_f32_e32 v52, v89, v134
	v_fma_f32 v48, v156, v48, v157
	v_mul_f32_e32 v52, v135, v52
	v_fma_f32 v52, v156, v52, v157
	v_cvt_pk_bf16_f32 v69, v48, v52
	v_sub_f32_e32 v48, v104, v160
	v_sub_f32_e32 v44, v44, v132
	v_sub_f32_e32 v45, v45, v134
	v_mul_f32_e32 v48, v161, v48
	v_sub_f32_e32 v52, v105, v162
	v_mul_f32_e32 v44, v133, v44
	v_mul_f32_e32 v45, v135, v45
	v_fma_f32 v48, v156, v48, v157
	v_mul_f32_e32 v52, v163, v52
	s_waitcnt vmcnt(17)
	v_fma_f32 v44, v154, v44, v155
	v_fma_f32 v45, v154, v45, v155
	v_fma_f32 v52, v156, v52, v157
	v_cvt_pk_bf16_f32 v70, v48, v52
	v_sub_f32_e32 v48, v118, v164
	v_cvt_pk_bf16_f32 v53, v44, v45
	v_sub_f32_e32 v44, v74, v160
	v_sub_f32_e32 v45, v75, v162
	v_mul_f32_e32 v48, v165, v48
	v_sub_f32_e32 v52, v119, v166
	v_mul_f32_e32 v44, v161, v44
	v_mul_f32_e32 v45, v163, v45
	v_fma_f32 v48, v156, v48, v157
	v_mul_f32_e32 v52, v167, v52
	v_fma_f32 v44, v154, v44, v155
	v_fma_f32 v45, v154, v45, v155
	v_sub_f32_e32 v36, v36, v132
	v_sub_f32_e32 v37, v37, v134
	v_fmac_f32_e32 v157, v156, v52
	v_cvt_pk_bf16_f32 v71, v48, v157
	v_sub_f32_e32 v48, v54, v56
	v_sub_f32_e32 v52, v55, v58
	v_cvt_pk_bf16_f32 v54, v44, v45
	v_sub_f32_e32 v44, v92, v164
	v_sub_f32_e32 v45, v93, v166
	v_mul_f32_e32 v36, v133, v36
	v_mul_f32_e32 v37, v135, v37
	v_mul_f32_e32 v48, v57, v48
	v_mul_f32_e32 v52, v59, v52
	v_mul_f32_e32 v44, v165, v44
	v_mul_f32_e32 v45, v167, v45
	s_waitcnt vmcnt(16)
	v_fma_f32 v36, v152, v36, v153
	v_fma_f32 v37, v152, v37, v153
	v_fma_f32 v48, v154, v48, v155
	v_fma_f32 v52, v154, v52, v155
	v_fma_f32 v44, v154, v44, v155
	v_fmac_f32_e32 v155, v154, v45
	v_sub_f32_e32 v45, v51, v58
	v_cvt_pk_bf16_f32 v51, v36, v37
	v_sub_f32_e32 v36, v40, v160
	v_sub_f32_e32 v37, v41, v162
	v_mul_f32_e32 v36, v161, v36
	v_mul_f32_e32 v37, v163, v37
	v_cvt_pk_bf16_f32 v52, v48, v52
	v_fma_f32 v36, v152, v36, v153
	v_fma_f32 v37, v152, v37, v153
	v_cvt_pk_bf16_f32 v55, v44, v155
	ds_write_b128 v10, v[52:55] offset:52224
	v_sub_f32_e32 v44, v50, v56
	v_cvt_pk_bf16_f32 v52, v36, v37
	v_sub_f32_e32 v36, v46, v164
	v_sub_f32_e32 v37, v47, v166
	v_mul_f32_e32 v44, v57, v44
	v_mul_f32_e32 v45, v59, v45
	v_mul_f32_e32 v36, v165, v36
	v_mul_f32_e32 v37, v167, v37
	ds_write_b128 v10, v[96:99] offset:34816
	ds_write_b128 v10, v[68:71] offset:43520
	v_fma_f32 v44, v152, v44, v153
	v_fma_f32 v45, v152, v45, v153
	v_cvt_pk_bf16_f32 v50, v44, v45
	v_fma_f32 v36, v152, v36, v153
	v_fmac_f32_e32 v153, v152, v37
	v_cvt_pk_bf16_f32 v53, v36, v153
	ds_write_b128 v10, v[50:53] offset:60928
	ds_read_b128 v[44:47], v11 offset:2048
	ds_read_b128 v[50:53], v11 offset:2064
	ds_read_b128 v[54:57], v11 offset:2080
	ds_read_b128 v[58:61], v11 offset:2096
	s_ashr_i32 s43, s42, 31
	s_waitcnt lgkmcnt(3)
	v_sub_f32_e32 v36, v82, v44
	v_mul_f32_e32 v36, v45, v36
	v_sub_f32_e32 v37, v83, v46
	s_waitcnt vmcnt(7)
	v_fma_f32 v36, v150, v36, v151
	v_mul_f32_e32 v37, v47, v37
	v_fma_f32 v37, v150, v37, v151
	v_cvt_pk_bf16_f32 v68, v36, v37
	s_waitcnt lgkmcnt(2)
	v_sub_f32_e32 v36, v100, v50
	v_mul_f32_e32 v36, v51, v36
	v_sub_f32_e32 v37, v101, v52
	v_fma_f32 v36, v150, v36, v151
	v_mul_f32_e32 v37, v53, v37
	v_fma_f32 v37, v150, v37, v151
	v_cvt_pk_bf16_f32 v69, v36, v37
	s_waitcnt lgkmcnt(1)
	v_sub_f32_e32 v36, v116, v54
	v_mul_f32_e32 v36, v55, v36
	v_sub_f32_e32 v37, v117, v56
	v_fma_f32 v36, v150, v36, v151
	v_mul_f32_e32 v37, v57, v37
	v_fma_f32 v37, v150, v37, v151
	v_cvt_pk_bf16_f32 v70, v36, v37
	s_waitcnt lgkmcnt(0)
	v_sub_f32_e32 v36, v126, v58
	v_mul_f32_e32 v36, v59, v36
	v_sub_f32_e32 v37, v127, v60
	v_fma_f32 v36, v150, v36, v151
	v_mul_f32_e32 v37, v61, v37
	v_fmac_f32_e32 v151, v150, v37
	v_cvt_pk_bf16_f32 v71, v36, v151
	v_add_u32_e32 v36, 0x11000, v10
	ds_write_b128 v36, v[68:71]
	v_sub_f32_e32 v36, v38, v44
	v_sub_f32_e32 v37, v39, v46
	v_mul_f32_e32 v36, v45, v36
	v_mul_f32_e32 v37, v47, v37
	s_waitcnt vmcnt(6)
	v_fma_f32 v36, v148, v36, v149
	v_fma_f32 v37, v148, v37, v149
	v_cvt_pk_bf16_f32 v36, v36, v37
	v_sub_f32_e32 v37, v66, v50
	v_sub_f32_e32 v38, v67, v52
	v_mul_f32_e32 v37, v51, v37
	v_mul_f32_e32 v38, v53, v38
	v_fma_f32 v37, v148, v37, v149
	v_fma_f32 v38, v148, v38, v149
	v_cvt_pk_bf16_f32 v37, v37, v38
	v_sub_f32_e32 v38, v86, v54
	v_sub_f32_e32 v39, v87, v56
	v_sub_f32_e32 v34, v34, v44
	v_sub_f32_e32 v35, v35, v46
	v_sub_f32_e32 v28, v28, v50
	v_sub_f32_e32 v29, v29, v52
	v_mul_f32_e32 v38, v55, v38
	v_mul_f32_e32 v39, v57, v39
	v_mul_f32_e32 v34, v45, v34
	v_mul_f32_e32 v35, v47, v35
	v_mul_f32_e32 v28, v51, v28
	v_mul_f32_e32 v29, v53, v29
	v_fma_f32 v38, v148, v38, v149
	v_fma_f32 v39, v148, v39, v149
	s_waitcnt vmcnt(5)
; #define LAS __attribute__((address_space(3)))
; __device__ __forceinline__ unsigned pk2(float lo, float hi) { unsigned r; asm("v_cvt_pk_bf16_f32 %0, %1, %2" : "=v"(r) : "v"(lo), "v"(hi)); return r; }
; __device__ __forceinline__ float bflo(unsigned u) { return __uint_as_float(u << 16); }
; __device__ __forceinline__ float bfhi(unsigned u) { return __uint_as_float(u & 0xffff0000u); }
; __device__ __forceinline__ void p5_unit(const Ptrs& P, LAS unsigned char* lds, int unit, int tid_in, int wave) {
;     ...
; #pragma unroll
;         for (int g = 0; g < 4; ++g) {
;             const LAS f32x4* mp = (const LAS f32x4*)(st2 + (g * 128 + p * 8) * 2);
;             const f32x4 m01 = mp[0], m23 = mp[1], m45 = mp[2], m67 = mp[3];
; #pragma unroll
;             for (int jj = 0; jj < 4; ++jj) { const u32x4 w = d[4 * g + jj]; const int c = t + 32 * jj;
;                 const float lg = lgv[4 * g + jj], lb = lbv[4 * g + jj];
;                 u32x4 o;
;                 o.x = pk2((bflo(w.x) - m01.x) * m01.y * lg + lb, (bfhi(w.x) - m01.z) * m01.w * lg + lb);
;                 o.y = pk2((bflo(w.y) - m23.x) * m23.y * lg + lb, (bfhi(w.y) - m23.z) * m23.w * lg + lb);
;                 o.z = pk2((bflo(w.z) - m45.x) * m45.y * lg + lb, (bfhi(w.z) - m45.z) * m45.w * lg + lb);
;                 o.w = pk2((bflo(w.w) - m67.x) * m67.y * lg + lb, (bfhi(w.w) - m67.z) * m67.w * lg + lb);
;                 *(LAS u32x4*)(vvt + (g * 128 + c) * VVT_LD + p * 8) = o; }
	v_fma_f32 v34, v146, v34, v147
	v_fma_f32 v35, v146, v35, v147
	v_fma_f32 v28, v146, v28, v147
	v_fma_f32 v29, v146, v29, v147
	v_cvt_pk_bf16_f32 v38, v38, v39
	v_sub_f32_e32 v39, v102, v58
	v_sub_f32_e32 v40, v103, v60
	v_cvt_pk_bf16_f32 v34, v34, v35
	v_cvt_pk_bf16_f32 v35, v28, v29
	v_sub_f32_e32 v28, v42, v54
	v_sub_f32_e32 v29, v43, v56
	v_mul_f32_e32 v39, v59, v39
	v_mul_f32_e32 v40, v61, v40
	v_mul_f32_e32 v28, v55, v28
	v_mul_f32_e32 v29, v57, v29
	v_fma_f32 v39, v148, v39, v149
	v_fmac_f32_e32 v149, v148, v40
	v_add_u32_e32 v40, 0x13200, v10
	v_fma_f32 v28, v146, v28, v147
	v_fma_f32 v29, v146, v29, v147
	v_sub_f32_e32 v20, v20, v50
	v_cvt_pk_bf16_f32 v39, v39, v149
	ds_write_b128 v40, v[36:39]
	v_cvt_pk_bf16_f32 v36, v28, v29
	v_sub_f32_e32 v28, v72, v58
	v_sub_f32_e32 v29, v73, v60
	v_mul_f32_e32 v20, v51, v20
	v_sub_f32_e32 v21, v21, v52
	v_mul_f32_e32 v28, v59, v28
	v_mul_f32_e32 v29, v61, v29
	s_waitcnt vmcnt(4)
	v_fma_f32 v20, v143, v20, v144
	v_mul_f32_e32 v21, v53, v21
	v_fma_f32 v28, v146, v28, v147
	v_fmac_f32_e32 v147, v146, v29
	v_sub_f32_e32 v29, v33, v46
	v_fma_f32 v21, v143, v21, v144
	v_cvt_pk_bf16_f32 v33, v20, v21
	v_sub_f32_e32 v20, v24, v54
	v_mul_f32_e32 v20, v55, v20
	v_sub_f32_e32 v21, v25, v56
	v_cvt_pk_bf16_f32 v37, v28, v147
	v_add_u32_e32 v28, 0x15400, v10
	v_fma_f32 v20, v143, v20, v144
	v_mul_f32_e32 v21, v57, v21
	ds_write_b128 v28, v[34:37]
	v_fma_f32 v21, v143, v21, v144
	v_cvt_pk_bf16_f32 v34, v20, v21
	v_sub_f32_e32 v20, v26, v58
	v_sub_f32_e32 v28, v32, v44
	v_mul_f32_e32 v20, v59, v20
	v_sub_f32_e32 v21, v27, v60
	v_mul_f32_e32 v28, v45, v28
	v_mul_f32_e32 v29, v47, v29
	v_fma_f32 v20, v143, v20, v144
	v_mul_f32_e32 v21, v61, v21
	v_fma_f32 v28, v143, v28, v144
	v_fma_f32 v29, v143, v29, v144
	v_fmac_f32_e32 v144, v143, v21
	v_cvt_pk_bf16_f32 v35, v20, v144
	v_add_u32_e32 v20, 0x17600, v10
	v_cvt_pk_bf16_f32 v32, v28, v29
	ds_write_b128 v20, v[32:35]
	ds_read_b128 v[24:27], v11 offset:3072
	ds_read_b128 v[32:35], v11 offset:3088
	ds_read_b128 v[36:39], v11 offset:3104
	ds_read_b128 v[40:43], v11 offset:3120
	v_readlane_b32 s8, v252, 40
	v_readlane_b32 s31, v252, 19
	s_waitcnt lgkmcnt(2)
	v_sub_f32_e32 v21, v31, v34
	v_sub_f32_e32 v11, v62, v24
	v_mul_f32_e32 v11, v25, v11
	v_sub_f32_e32 v20, v63, v26
	s_waitcnt vmcnt(3)
	v_fma_f32 v11, v141, v11, v142
	v_mul_f32_e32 v20, v27, v20
	v_fma_f32 v20, v141, v20, v142
	v_cvt_pk_bf16_f32 v44, v11, v20
	v_sub_f32_e32 v11, v78, v32
	v_mul_f32_e32 v11, v33, v11
	v_sub_f32_e32 v20, v79, v34
	v_fma_f32 v11, v141, v11, v142
	v_mul_f32_e32 v20, v35, v20
	v_fma_f32 v20, v141, v20, v142
	v_cvt_pk_bf16_f32 v45, v11, v20
	s_waitcnt lgkmcnt(1)
	v_sub_f32_e32 v11, v94, v36
	v_mul_f32_e32 v11, v37, v11
	v_sub_f32_e32 v20, v95, v38
	v_fma_f32 v11, v141, v11, v142
	v_mul_f32_e32 v20, v39, v20
	v_fma_f32 v20, v141, v20, v142
	v_cvt_pk_bf16_f32 v46, v11, v20
	s_waitcnt lgkmcnt(0)
	v_sub_f32_e32 v11, v108, v40
	v_mul_f32_e32 v11, v41, v11
	v_sub_f32_e32 v20, v109, v42
	v_fma_f32 v11, v141, v11, v142
	v_mul_f32_e32 v20, v43, v20
	v_fmac_f32_e32 v142, v141, v20
	v_cvt_pk_bf16_f32 v47, v11, v142
	v_add_u32_e32 v11, 0x19800, v10
	ds_write_b128 v11, v[44:47]
	v_sub_f32_e32 v11, v22, v24
	v_sub_f32_e32 v20, v23, v26
	v_mul_f32_e32 v11, v25, v11
	v_mul_f32_e32 v20, v27, v20
	s_waitcnt vmcnt(2)
	v_fma_f32 v11, v138, v11, v139
	v_fma_f32 v20, v138, v20, v139
	v_cvt_pk_bf16_f32 v20, v11, v20
	v_sub_f32_e32 v11, v30, v32
	v_mul_f32_e32 v11, v33, v11
	v_mul_f32_e32 v21, v35, v21
	v_fma_f32 v11, v138, v11, v139
	v_fma_f32 v21, v138, v21, v139
	v_cvt_pk_bf16_f32 v21, v11, v21
	v_sub_f32_e32 v11, v64, v36
	v_sub_f32_e32 v22, v65, v38
	v_mul_f32_e32 v11, v37, v11
	v_mul_f32_e32 v22, v39, v22
	v_fma_f32 v11, v138, v11, v139
	v_fma_f32 v22, v138, v22, v139
	v_cvt_pk_bf16_f32 v22, v11, v22
	v_sub_f32_e32 v11, v84, v40
	v_mul_f32_e32 v11, v41, v11
	v_sub_f32_e32 v23, v85, v42
	v_sub_f32_e32 v8, v8, v32
	v_sub_f32_e32 v9, v9, v34
	v_fma_f32 v11, v138, v11, v139
	v_mul_f32_e32 v23, v43, v23
	v_mul_f32_e32 v8, v33, v8
	v_mul_f32_e32 v9, v35, v9
	v_fmac_f32_e32 v139, v138, v23
	v_cvt_pk_bf16_f32 v23, v11, v139
	v_add_u32_e32 v11, 0x1ba00, v10
	s_waitcnt vmcnt(1)
	v_fma_f32 v8, v49, v8, v137
	v_fma_f32 v9, v49, v9, v137
	v_sub_f32_e32 v6, v6, v40
	ds_write_b128 v11, v[20:23]
	v_sub_f32_e32 v11, v18, v24
	v_sub_f32_e32 v18, v19, v26
	v_cvt_pk_bf16_f32 v19, v8, v9
	v_sub_f32_e32 v8, v12, v36
	v_sub_f32_e32 v9, v13, v38
	v_mul_f32_e32 v6, v41, v6
	v_sub_f32_e32 v7, v7, v42
	v_mul_f32_e32 v11, v25, v11
	v_mul_f32_e32 v18, v27, v18
	v_mul_f32_e32 v8, v37, v8
	v_mul_f32_e32 v9, v39, v9
	v_fma_f32 v6, v49, v6, v137
	v_mul_f32_e32 v7, v43, v7
	v_fma_f32 v11, v49, v11, v137
	v_fma_f32 v18, v49, v18, v137
	v_fma_f32 v8, v49, v8, v137
	v_fma_f32 v9, v49, v9, v137
	v_fmac_f32_e32 v137, v49, v7
	v_cvt_pk_bf16_f32 v21, v6, v137
	v_add_u32_e32 v6, 0x1dc00, v10
	v_cvt_pk_bf16_f32 v18, v11, v18
	v_cvt_pk_bf16_f32 v20, v8, v9
	ds_write_b128 v6, v[18:21]
	v_sub_f32_e32 v6, v16, v24
	v_sub_f32_e32 v7, v17, v26
	v_sub_f32_e32 v0, v0, v32
	v_mul_f32_e32 v6, v25, v6
	v_mul_f32_e32 v7, v27, v7
	v_mul_f32_e32 v0, v33, v0
	v_sub_f32_e32 v1, v1, v34
	s_waitcnt vmcnt(0)
; #define LAS __attribute__((address_space(3)))
; #define SCHED_FENCE() __builtin_amdgcn_sched_barrier(0)
; __device__ __forceinline__ f32x4 mfma16(bf16x8 a, bf16x8 b, f32x4 c) { return __builtin_amdgcn_mfma_f32_16x16x32_bf16(a, b, c, 0, 0, 0); }
; __device__ __forceinline__ void p5_unit(const Ptrs& P, LAS unsigned char* lds, int unit, int tid_in, int wave) {
;     ...
;         const int g = wave & 3, half = wave >> 2;
;         bf16x8 wf[2][4]; u32x2 uw[2][8]; float bs[2];
; #pragma unroll
;         for (int pb = 0; pb < 2; ++pb) {
;             const int pl = half * 32 + pb * 16 + fr, pp = (r & 1) * 64 + pl;
;             const bf16_t* up = proj + ((size_t)tok0 + pl) * PROJ_LD + 2048 + g * 128 + fq * 4;
; #pragma unroll
;             for (int qc = 0; qc < 4; ++qc) wf[pb][qc] = *(const bf16x8*)(wsb + (size_t)(g * 128 + pp) * 128 + qc * 32 + fq * 8);
; #pragma unroll
;             for (int c = 0; c < 8; ++c) uw[pb][c] = *(const u32x2*)(up + c * 16);
;             bs[pb] = P.in[14][g * 128 + pp];
;         }
;         SCHED_FENCE();
;         __syncthreads();
; #pragma unroll
;         for (int pb = 0; pb < 2; ++pb) {
;             const int pl = half * 32 + pb * 16 + fr;
;             f32x4 acc[8];
; #pragma unroll
;             for (int c = 0; c < 8; ++c) acc[c] = (f32x4){0.f, 0.f, 0.f, 0.f};
; #pragma unroll
;             for (int qc = 0; qc < 4; ++qc)
; #pragma unroll
;                 for (int c = 0; c < 8; ++c) {
;                     const bf16x8 af = *(const LAS bf16x8*)(vvt + (g * 128 + c * 16 + fr) * VVT_LD + qc * 32 + fq * 8);
;                     acc[c] = mfma16(af, wf[pb][qc], acc[c]);
	v_fma_f32 v6, v14, v6, v15
	v_fma_f32 v7, v14, v7, v15
	v_fma_f32 v0, v14, v0, v15
	v_mul_f32_e32 v1, v35, v1
	v_cvt_pk_bf16_f32 v6, v6, v7
	v_fma_f32 v1, v14, v1, v15
	v_cvt_pk_bf16_f32 v7, v0, v1
	v_sub_f32_e32 v0, v4, v36
	v_mul_f32_e32 v0, v37, v0
	v_sub_f32_e32 v1, v5, v38
	v_fma_f32 v0, v14, v0, v15
	v_mul_f32_e32 v1, v39, v1
	v_fma_f32 v1, v14, v1, v15
	v_cvt_pk_bf16_f32 v8, v0, v1
	v_sub_f32_e32 v0, v2, v40
	v_mul_f32_e32 v0, v41, v0
	v_sub_f32_e32 v1, v3, v42
	v_fma_f32 v0, v14, v0, v15
	v_mul_f32_e32 v1, v43, v1
	v_fmac_f32_e32 v15, v14, v1
	v_cvt_pk_bf16_f32 v9, v0, v15
	v_add_u32_e32 v0, 0x1fe00, v10
	ds_write_b128 v0, v[6:9]
	v_mov_b32_e32 v0, v217
	s_and_b32 s7, s7, 64
	v_and_b32_e32 v61, 15, v0
	v_bfe_u32 v1, v0, 4, 2
	v_or_b32_e32 v0, s0, v61
	v_lshlrev_b32_e32 v144, 3, v1
	v_lshlrev_b32_e32 v32, 4, v1
	v_mov_b32_e32 v1, v145
	v_mov_b32_e32 v33, v145
	v_readlane_b32 s9, v252, 41
	v_lshl_add_u64 v[38:39], v[0:1], 0, s[42:43]
	v_mov_b64_e32 v[40:41], s[30:31]
	s_movk_i32 s35, 0x1800
	v_readlane_b32 s0, v251, 28
	v_lshl_add_u64 v[2:3], s[8:9], 0, v[32:33]
	v_mad_u64_u32 v[4:5], s[8:9], v38, s35, v[40:41]
	s_or_b32 s7, s7, s0
	v_mad_i32_i24 v5, v39, s35, v5
	s_lshl_b32 s74, s0, 1
	v_add_u32_e32 v6, s7, v0
	v_mov_b32_e32 v7, v145
	v_lshl_add_u64 v[4:5], v[4:5], 0, s[74:75]
	v_lshlrev_b64 v[8:9], 8, v[6:7]
	v_lshl_add_u64 v[8:9], v[2:3], 0, v[8:9]
	v_lshl_add_u64 v[4:5], v[4:5], 0, v[144:145]
	s_mov_b64 s[10:11], 0x1000
	global_load_dwordx4 v[16:19], v[8:9], off
	global_load_dwordx4 v[20:23], v[8:9], off offset:64
	global_load_dwordx4 v[24:27], v[8:9], off offset:128
	global_load_dwordx4 v[28:31], v[8:9], off offset:192
	v_lshl_add_u64 v[8:9], v[4:5], 0, s[10:11]
	v_add_co_u32_e32 v4, vcc, s71, v4
	v_or_b32_e32 v0, 16, v0
	s_nop 0
	v_addc_co_u32_e32 v5, vcc, 0, v5, vcc
	v_lshl_add_u64 v[56:57], v[0:1], 0, s[42:43]
	global_load_dwordx2 v[90:91], v[8:9], off offset:32
	global_load_dwordx2 v[92:93], v[8:9], off offset:64
	global_load_dwordx2 v[94:95], v[8:9], off offset:96
	global_load_dwordx2 v[96:97], v[8:9], off offset:128
	global_load_dwordx2 v[98:99], v[4:5], off
	global_load_dwordx2 v[100:101], v[8:9], off offset:160
	global_load_dwordx2 v[102:103], v[8:9], off offset:192
	global_load_dwordx2 v[104:105], v[8:9], off offset:224
	v_mad_u64_u32 v[4:5], s[8:9], v56, s35, v[40:41]
	v_mad_i32_i24 v5, v57, s35, v5
	v_lshl_add_u64 v[34:35], v[4:5], 0, s[74:75]
	v_add_u32_e32 v0, s7, v0
	v_lshlrev_b64 v[0:1], 8, v[0:1]
	v_lshl_add_u64 v[34:35], v[34:35], 0, v[144:145]
	v_lshl_add_u64 v[0:1], v[2:3], 0, v[0:1]
	v_lshl_add_u64 v[36:37], v[34:35], 0, s[10:11]
	v_add_co_u32_e32 v34, vcc, s71, v34
	v_lshlrev_b32_e32 v33, 2, v6
	global_load_dwordx4 v[12:15], v[0:1], off
	global_load_dwordx4 v[8:11], v[0:1], off offset:64
	global_load_dwordx4 v[4:7], v[0:1], off offset:128
	s_nop 0
	global_load_dwordx4 v[0:3], v[0:1], off offset:192
	v_addc_co_u32_e32 v35, vcc, 0, v35, vcc
	global_load_dwordx2 v[54:55], v[36:37], off offset:32
	global_load_dwordx2 v[52:53], v[36:37], off offset:64
	global_load_dwordx2 v[50:51], v[36:37], off offset:96
	global_load_dwordx2 v[48:49], v[36:37], off offset:128
	global_load_dwordx2 v[58:59], v[34:35], off
	global_load_dwordx2 v[46:47], v[36:37], off offset:160
	global_load_dwordx2 v[44:45], v[36:37], off offset:192
	global_load_dwordx2 v[42:43], v[36:37], off offset:224
	s_nop 0
	global_load_dword v37, v33, s[56:57]
	global_load_dword v60, v33, s[56:57] offset:64
	s_mov_b32 s13, 0
	v_or_b32_e32 v33, s0, v61
	v_mul_u32_u24_e32 v33, 0x110, v33
	v_add3_u32 v36, 0, v32, v33
	s_waitcnt lgkmcnt(0)
	s_barrier
	ds_read_b128 v[32:35], v36
	ds_read_b128 v[62:65], v36 offset:4352
	ds_read_b128 v[66:69], v36 offset:8704
	ds_read_b128 v[70:73], v36 offset:13056
	ds_read_b128 v[74:77], v36 offset:17408
	ds_read_b128 v[78:81], v36 offset:21760
	ds_read_b128 v[82:85], v36 offset:26112
	ds_read_b128 v[86:89], v36 offset:30464
	s_waitcnt vmcnt(25) lgkmcnt(7)
	v_mfma_f32_16x16x32_bf16 v[32:35], v[32:35], v[16:19], 0
	v_readlane_b32 s0, v251, 29
	v_readlane_b32 s1, v251, 30
	s_min_u32 s22, s19, 56
	s_waitcnt lgkmcnt(6)
	v_mfma_f32_16x16x32_bf16 v[62:65], v[62:65], v[16:19], 0
	s_waitcnt lgkmcnt(5)
	v_mfma_f32_16x16x32_bf16 v[66:69], v[66:69], v[16:19], 0
	s_waitcnt lgkmcnt(4)
	v_mfma_f32_16x16x32_bf16 v[70:73], v[70:73], v[16:19], 0
	s_waitcnt lgkmcnt(3)
	v_mfma_f32_16x16x32_bf16 v[74:77], v[74:77], v[16:19], 0
	s_waitcnt lgkmcnt(2)
	v_mfma_f32_16x16x32_bf16 v[78:81], v[78:81], v[16:19], 0
	s_waitcnt lgkmcnt(1)
	v_mfma_f32_16x16x32_bf16 v[82:85], v[82:85], v[16:19], 0
	s_waitcnt lgkmcnt(0)
	v_mfma_f32_16x16x32_bf16 v[16:19], v[86:89], v[16:19], 0
	ds_read_b128 v[240:243], v36 offset:64
	ds_read_b128 v[244:247], v36 offset:4416
	s_waitcnt vmcnt(24) lgkmcnt(1)
	v_mfma_f32_16x16x32_bf16 v[32:35], v[240:243], v[20:23], v[32:35]
	ds_read_b128 v[240:243], v36 offset:8768
	s_waitcnt lgkmcnt(1)
	v_mfma_f32_16x16x32_bf16 v[62:65], v[244:247], v[20:23], v[62:65]
	ds_read_b128 v[244:247], v36 offset:13120
	s_waitcnt lgkmcnt(1)
	v_mfma_f32_16x16x32_bf16 v[66:69], v[240:243], v[20:23], v[66:69]
	ds_read_b128 v[240:243], v36 offset:17472
	s_waitcnt lgkmcnt(1)
	v_mfma_f32_16x16x32_bf16 v[70:73], v[244:247], v[20:23], v[70:73]
	ds_read_b128 v[244:247], v36 offset:21824
	s_waitcnt lgkmcnt(1)
	v_mfma_f32_16x16x32_bf16 v[74:77], v[240:243], v[20:23], v[74:77]
	ds_read_b128 v[240:243], v36 offset:26176
	s_waitcnt lgkmcnt(1)
	v_mfma_f32_16x16x32_bf16 v[78:81], v[244:247], v[20:23], v[78:81]
	s_waitcnt lgkmcnt(0)
	v_mfma_f32_16x16x32_bf16 v[82:85], v[240:243], v[20:23], v[82:85]
	ds_read_b128 v[86:89], v36 offset:30528
	s_waitcnt lgkmcnt(0)
; #define LAS __attribute__((address_space(3)))
; __device__ __forceinline__ unsigned pk2(float lo, float hi) { unsigned r; asm("v_cvt_pk_bf16_f32 %0, %1, %2" : "=v"(r) : "v"(lo), "v"(hi)); return r; }
; __device__ __forceinline__ float bflo(unsigned u) { return __uint_as_float(u << 16); }
; __device__ __forceinline__ float bfhi(unsigned u) { return __uint_as_float(u & 0xffff0000u); }
; __device__ __forceinline__ f32x4 mfma16(bf16x8 a, bf16x8 b, f32x4 c) { return __builtin_amdgcn_mfma_f32_16x16x32_bf16(a, b, c, 0, 0, 0); }
; __device__ __forceinline__ void p5_unit(const Ptrs& P, LAS unsigned char* lds, int unit, int tid_in, int wave) {
;     ...
;             for (int qc = 0; qc < 4; ++qc)
; #pragma unroll
;                 for (int c = 0; c < 8; ++c) {
;                     const bf16x8 af = *(const LAS bf16x8*)(vvt + (g * 128 + c * 16 + fr) * VVT_LD + qc * 32 + fq * 8);
;                     acc[c] = mfma16(af, wf[pb][qc], acc[c]);
;                 }
;             bf16_t* yp = Y + ((size_t)tok0 + pl) * DM + 1024 + g * 128 + fq * 4;
; #pragma unroll
;             for (int c = 0; c < 8; ++c) {
;                 u32x2 w; w.x = pk2(bflo(uw[pb][c].x) * (acc[c].x + bs[pb]), bfhi(uw[pb][c].x) * (acc[c].y + bs[pb])); w.y = pk2(bflo(uw[pb][c].y) * (acc[c].z + bs[pb]), bfhi(uw[pb][c].y) * (acc[c].w + bs[pb]));
;                 *(u32x2*)(yp + c * 16) = w; }
	v_mfma_f32_16x16x32_bf16 v[16:19], v[86:89], v[20:23], v[16:19]
	ds_read_b128 v[240:243], v36 offset:128
	ds_read_b128 v[244:247], v36 offset:4480
	s_waitcnt vmcnt(23) lgkmcnt(1)
	v_mfma_f32_16x16x32_bf16 v[20:23], v[240:243], v[24:27], v[32:35]
	ds_read_b128 v[240:243], v36 offset:8832
	s_waitcnt lgkmcnt(1)
	v_mfma_f32_16x16x32_bf16 v[32:35], v[244:247], v[24:27], v[62:65]
	ds_read_b128 v[244:247], v36 offset:13184
	s_waitcnt lgkmcnt(1)
	v_mfma_f32_16x16x32_bf16 v[62:65], v[240:243], v[24:27], v[66:69]
	ds_read_b128 v[240:243], v36 offset:17536
	s_waitcnt lgkmcnt(1)
	v_mfma_f32_16x16x32_bf16 v[66:69], v[244:247], v[24:27], v[70:73]
	ds_read_b128 v[244:247], v36 offset:21888
	s_waitcnt lgkmcnt(1)
	v_mfma_f32_16x16x32_bf16 v[70:73], v[240:243], v[24:27], v[74:77]
	ds_read_b128 v[240:243], v36 offset:26240
	s_waitcnt lgkmcnt(1)
	v_mfma_f32_16x16x32_bf16 v[74:77], v[244:247], v[24:27], v[78:81]
	s_waitcnt lgkmcnt(0)
	v_mfma_f32_16x16x32_bf16 v[78:81], v[240:243], v[24:27], v[82:85]
	ds_read_b128 v[82:85], v36 offset:30592
	s_waitcnt lgkmcnt(0)
	v_mfma_f32_16x16x32_bf16 v[16:19], v[82:85], v[24:27], v[16:19]
	ds_read_b128 v[24:27], v36 offset:192
	s_waitcnt vmcnt(22) lgkmcnt(0)
	v_mfma_f32_16x16x32_bf16 v[20:23], v[24:27], v[28:31], v[20:23]
	ds_read_b128 v[24:27], v36 offset:4544
	s_waitcnt vmcnt(1)
	s_nop 5
	v_add_f32_e32 v20, v37, v20
	s_waitcnt lgkmcnt(0)
	v_mfma_f32_16x16x32_bf16 v[24:27], v[24:27], v[28:31], v[32:35]
	s_nop 2
	ds_read_b128 v[32:35], v36 offset:8896
	v_add_f32_e32 v21, v37, v21
	v_add_f32_e32 v22, v37, v22
	s_waitcnt lgkmcnt(0)
	v_mfma_f32_16x16x32_bf16 v[32:35], v[32:35], v[28:31], v[62:65]
	s_nop 2
	ds_read_b128 v[62:65], v36 offset:13248
	v_add_f32_e32 v23, v37, v23
	s_waitcnt lgkmcnt(0)
	v_mfma_f32_16x16x32_bf16 v[62:65], v[62:65], v[28:31], v[66:69]
	s_nop 2
	ds_read_b128 v[240:243], v36 offset:17600
	ds_read_b128 v[244:247], v36 offset:21952
	s_waitcnt lgkmcnt(1)
	v_mfma_f32_16x16x32_bf16 v[66:69], v[240:243], v[28:31], v[70:73]
	ds_read_b128 v[240:243], v36 offset:26304
	s_waitcnt lgkmcnt(1)
	v_mfma_f32_16x16x32_bf16 v[70:73], v[244:247], v[28:31], v[74:77]
	s_waitcnt lgkmcnt(0)
	v_mfma_f32_16x16x32_bf16 v[74:77], v[240:243], v[28:31], v[78:81]
	ds_read_b128 v[78:81], v36 offset:30656
	s_waitcnt lgkmcnt(0)
	v_mfma_f32_16x16x32_bf16 v[16:19], v[78:81], v[28:31], v[16:19]
	v_lshlrev_b32_e32 v30, 16, v98
	v_mul_f32_e32 v20, v20, v30
	v_and_b32_e32 v30, 0xffff0000, v98
	v_mul_f32_e32 v21, v21, v30
	v_lshlrev_b64 v[28:29], 12, v[38:39]
	v_cvt_pk_bf16_f32 v20, v20, v21
	v_lshlrev_b32_e32 v21, 16, v99
	v_lshl_add_u64 v[28:29], s[0:1], 0, v[28:29]
	v_mul_f32_e32 v21, v22, v21
	v_and_b32_e32 v22, 0xffff0000, v99
	v_lshl_add_u64 v[28:29], v[28:29], 0, v[144:145]
	v_mul_f32_e32 v22, v23, v22
	v_cvt_pk_bf16_f32 v21, v21, v22
	global_store_dwordx2 v[28:29], v[20:21], off offset:2048
	v_lshlrev_b32_e32 v20, 16, v90
	v_add_f32_e32 v21, v37, v24
	v_mul_f32_e32 v20, v21, v20
	v_and_b32_e32 v21, 0xffff0000, v90
	v_add_f32_e32 v22, v37, v25
	v_mul_f32_e32 v21, v22, v21
	v_cvt_pk_bf16_f32 v20, v20, v21
	v_lshlrev_b32_e32 v21, 16, v91
	v_add_f32_e32 v22, v37, v26
	v_mul_f32_e32 v21, v22, v21
	v_and_b32_e32 v22, 0xffff0000, v91
	v_add_f32_e32 v23, v37, v27
	v_mul_f32_e32 v22, v23, v22
	v_cvt_pk_bf16_f32 v21, v21, v22
	global_store_dwordx2 v[28:29], v[20:21], off offset:2080
	v_lshlrev_b32_e32 v20, 16, v92
	v_add_f32_e32 v21, v37, v32
	v_mul_f32_e32 v20, v21, v20
	v_and_b32_e32 v21, 0xffff0000, v92
	v_add_f32_e32 v22, v37, v33
	v_mul_f32_e32 v21, v22, v21
	v_cvt_pk_bf16_f32 v20, v20, v21
	v_lshlrev_b32_e32 v21, 16, v93
	v_add_f32_e32 v22, v37, v34
	v_mul_f32_e32 v21, v22, v21
	v_and_b32_e32 v22, 0xffff0000, v93
	v_add_f32_e32 v23, v37, v35
	v_mul_f32_e32 v22, v23, v22
	v_cvt_pk_bf16_f32 v21, v21, v22
	global_store_dwordx2 v[28:29], v[20:21], off offset:2112
	v_lshlrev_b32_e32 v20, 16, v94
	v_add_f32_e32 v21, v37, v62
	v_mul_f32_e32 v20, v21, v20
	v_and_b32_e32 v21, 0xffff0000, v94
	v_add_f32_e32 v22, v37, v63
	v_mul_f32_e32 v21, v22, v21
	v_cvt_pk_bf16_f32 v20, v20, v21
	v_lshlrev_b32_e32 v21, 16, v95
	v_add_f32_e32 v22, v37, v64
	v_mul_f32_e32 v21, v22, v21
	v_and_b32_e32 v22, 0xffff0000, v95
	v_add_f32_e32 v23, v37, v65
	v_mul_f32_e32 v22, v23, v22
	v_cvt_pk_bf16_f32 v21, v21, v22
	global_store_dwordx2 v[28:29], v[20:21], off offset:2144
	v_lshlrev_b32_e32 v20, 16, v96
	v_add_f32_e32 v21, v37, v66
	v_mul_f32_e32 v20, v21, v20
	v_and_b32_e32 v21, 0xffff0000, v96
	v_add_f32_e32 v22, v37, v67
	v_mul_f32_e32 v21, v22, v21
	v_cvt_pk_bf16_f32 v20, v20, v21
	v_lshlrev_b32_e32 v21, 16, v97
	v_add_f32_e32 v22, v37, v68
	v_mul_f32_e32 v21, v22, v21
	v_and_b32_e32 v22, 0xffff0000, v97
	v_add_f32_e32 v23, v37, v69
	v_mul_f32_e32 v22, v23, v22
	v_cvt_pk_bf16_f32 v21, v21, v22
	global_store_dwordx2 v[28:29], v[20:21], off offset:2176
	v_lshlrev_b32_e32 v20, 16, v100
	v_add_f32_e32 v21, v37, v70
	v_mul_f32_e32 v20, v21, v20
	v_and_b32_e32 v21, 0xffff0000, v100
	v_add_f32_e32 v22, v37, v71
	v_mul_f32_e32 v21, v22, v21
	v_cvt_pk_bf16_f32 v20, v20, v21
	v_lshlrev_b32_e32 v21, 16, v101
	v_add_f32_e32 v22, v37, v72
	v_mul_f32_e32 v21, v22, v21
	v_and_b32_e32 v22, 0xffff0000, v101
	v_add_f32_e32 v23, v37, v73
	v_mul_f32_e32 v22, v23, v22
	v_cvt_pk_bf16_f32 v21, v21, v22
	global_store_dwordx2 v[28:29], v[20:21], off offset:2208
	v_lshlrev_b32_e32 v20, 16, v102
	v_add_f32_e32 v21, v37, v74
	v_mul_f32_e32 v20, v21, v20
	v_and_b32_e32 v21, 0xffff0000, v102
	v_add_f32_e32 v22, v37, v75
	v_mul_f32_e32 v21, v22, v21
	v_cvt_pk_bf16_f32 v20, v20, v21
	v_lshlrev_b32_e32 v21, 16, v103
	v_add_f32_e32 v22, v37, v76
	v_mul_f32_e32 v21, v22, v21
	v_and_b32_e32 v22, 0xffff0000, v103
	v_add_f32_e32 v23, v37, v77
	v_mul_f32_e32 v22, v23, v22
	v_cvt_pk_bf16_f32 v21, v21, v22
	global_store_dwordx2 v[28:29], v[20:21], off offset:2240
	v_lshlrev_b32_e32 v20, 16, v104
	v_add_f32_e32 v16, v37, v16
	v_mul_f32_e32 v16, v16, v20
	v_and_b32_e32 v20, 0xffff0000, v104
	v_add_f32_e32 v17, v37, v17
	v_mul_f32_e32 v17, v17, v20
	v_cvt_pk_bf16_f32 v16, v16, v17
	v_lshlrev_b32_e32 v17, 16, v105
	v_add_f32_e32 v18, v37, v18
	v_mul_f32_e32 v17, v18, v17
	v_and_b32_e32 v18, 0xffff0000, v105
	v_add_f32_e32 v19, v37, v19
	v_mul_f32_e32 v18, v19, v18
	v_cvt_pk_bf16_f32 v17, v17, v18
	global_store_dwordx2 v[28:29], v[16:17], off offset:2272
	ds_read_b128 v[16:19], v36
	ds_read_b128 v[20:23], v36 offset:4352
	ds_read_b128 v[24:27], v36 offset:8704
	ds_read_b128 v[28:31], v36 offset:13056
	ds_read_b128 v[32:35], v36 offset:17408
	ds_read_b128 v[62:65], v36 offset:21760
	ds_read_b128 v[66:69], v36 offset:26112
	ds_read_b128 v[70:73], v36 offset:30464
	s_waitcnt lgkmcnt(7)
; #define LAS __attribute__((address_space(3)))
; __device__ __forceinline__ unsigned pk2(float lo, float hi) { unsigned r; asm("v_cvt_pk_bf16_f32 %0, %1, %2" : "=v"(r) : "v"(lo), "v"(hi)); return r; }
; __device__ __forceinline__ float bflo(unsigned u) { return __uint_as_float(u << 16); }
; __device__ __forceinline__ float bfhi(unsigned u) { return __uint_as_float(u & 0xffff0000u); }
; __device__ __forceinline__ f32x4 mfma16(bf16x8 a, bf16x8 b, f32x4 c) { return __builtin_amdgcn_mfma_f32_16x16x32_bf16(a, b, c, 0, 0, 0); }
; __device__ __forceinline__ void p5_unit(const Ptrs& P, LAS unsigned char* lds, int unit, int tid_in, int wave) {
;     ...
;             for (int qc = 0; qc < 4; ++qc)
; #pragma unroll
;                 for (int c = 0; c < 8; ++c) {
;                     const bf16x8 af = *(const LAS bf16x8*)(vvt + (g * 128 + c * 16 + fr) * VVT_LD + qc * 32 + fq * 8);
;                     acc[c] = mfma16(af, wf[pb][qc], acc[c]);
;                 }
;             bf16_t* yp = Y + ((size_t)tok0 + pl) * DM + 1024 + g * 128 + fq * 4;
; #pragma unroll
;             for (int c = 0; c < 8; ++c) {
;                 u32x2 w; w.x = pk2(bflo(uw[pb][c].x) * (acc[c].x + bs[pb]), bfhi(uw[pb][c].x) * (acc[c].y + bs[pb])); w.y = pk2(bflo(uw[pb][c].y) * (acc[c].z + bs[pb]), bfhi(uw[pb][c].y) * (acc[c].w + bs[pb]));
;                 *(u32x2*)(yp + c * 16) = w; }
	v_mfma_f32_16x16x32_bf16 v[16:19], v[16:19], v[12:15], 0
	v_mov_b32_e32 v97, v217
	s_waitcnt lgkmcnt(6)
	v_mfma_f32_16x16x32_bf16 v[20:23], v[20:23], v[12:15], 0
	s_waitcnt lgkmcnt(5)
	v_mfma_f32_16x16x32_bf16 v[24:27], v[24:27], v[12:15], 0
	s_waitcnt lgkmcnt(4)
	v_mfma_f32_16x16x32_bf16 v[28:31], v[28:31], v[12:15], 0
	s_waitcnt lgkmcnt(3)
	v_mfma_f32_16x16x32_bf16 v[32:35], v[32:35], v[12:15], 0
	s_waitcnt lgkmcnt(2)
	v_mfma_f32_16x16x32_bf16 v[62:65], v[62:65], v[12:15], 0
	s_waitcnt lgkmcnt(1)
	v_mfma_f32_16x16x32_bf16 v[66:69], v[66:69], v[12:15], 0
	s_waitcnt lgkmcnt(0)
	v_mfma_f32_16x16x32_bf16 v[12:15], v[70:73], v[12:15], 0
	ds_read_b128 v[240:243], v36 offset:64
	ds_read_b128 v[244:247], v36 offset:4416
	s_waitcnt lgkmcnt(1)
	v_mfma_f32_16x16x32_bf16 v[16:19], v[240:243], v[8:11], v[16:19]
	ds_read_b128 v[240:243], v36 offset:8768
	s_waitcnt lgkmcnt(1)
	v_mfma_f32_16x16x32_bf16 v[20:23], v[244:247], v[8:11], v[20:23]
	ds_read_b128 v[244:247], v36 offset:13120
	s_waitcnt lgkmcnt(1)
	v_mfma_f32_16x16x32_bf16 v[24:27], v[240:243], v[8:11], v[24:27]
	ds_read_b128 v[240:243], v36 offset:17472
	s_waitcnt lgkmcnt(1)
	v_mfma_f32_16x16x32_bf16 v[28:31], v[244:247], v[8:11], v[28:31]
	ds_read_b128 v[244:247], v36 offset:21824
	s_waitcnt lgkmcnt(1)
	v_mfma_f32_16x16x32_bf16 v[32:35], v[240:243], v[8:11], v[32:35]
	ds_read_b128 v[240:243], v36 offset:26176
	s_waitcnt lgkmcnt(1)
	v_mfma_f32_16x16x32_bf16 v[62:65], v[244:247], v[8:11], v[62:65]
	s_waitcnt lgkmcnt(0)
	v_mfma_f32_16x16x32_bf16 v[66:69], v[240:243], v[8:11], v[66:69]
	ds_read_b128 v[70:73], v36 offset:30528
	s_waitcnt lgkmcnt(0)
	v_mfma_f32_16x16x32_bf16 v[8:11], v[70:73], v[8:11], v[12:15]
	s_nop 2
	ds_read_b128 v[240:243], v36 offset:128
	ds_read_b128 v[244:247], v36 offset:4480
	s_waitcnt lgkmcnt(1)
	v_mfma_f32_16x16x32_bf16 v[12:15], v[240:243], v[4:7], v[16:19]
	ds_read_b128 v[240:243], v36 offset:8832
	s_waitcnt lgkmcnt(1)
	v_mfma_f32_16x16x32_bf16 v[16:19], v[244:247], v[4:7], v[20:23]
	ds_read_b128 v[244:247], v36 offset:13184
	s_waitcnt lgkmcnt(1)
	v_mfma_f32_16x16x32_bf16 v[20:23], v[240:243], v[4:7], v[24:27]
	ds_read_b128 v[240:243], v36 offset:17536
	s_waitcnt lgkmcnt(1)
	v_mfma_f32_16x16x32_bf16 v[24:27], v[244:247], v[4:7], v[28:31]
	ds_read_b128 v[244:247], v36 offset:21888
	s_waitcnt lgkmcnt(1)
	v_mfma_f32_16x16x32_bf16 v[28:31], v[240:243], v[4:7], v[32:35]
	ds_read_b128 v[240:243], v36 offset:26240
	s_waitcnt lgkmcnt(1)
	v_mfma_f32_16x16x32_bf16 v[32:35], v[244:247], v[4:7], v[62:65]
	s_waitcnt lgkmcnt(0)
	v_mfma_f32_16x16x32_bf16 v[62:65], v[240:243], v[4:7], v[66:69]
	ds_read_b128 v[66:69], v36 offset:30592
	s_waitcnt lgkmcnt(0)
	v_mfma_f32_16x16x32_bf16 v[4:7], v[66:69], v[4:7], v[8:11]
	s_nop 2
	ds_read_b128 v[240:243], v36 offset:192
	ds_read_b128 v[244:247], v36 offset:4544
	s_waitcnt lgkmcnt(1)
	v_mfma_f32_16x16x32_bf16 v[8:11], v[240:243], v[0:3], v[12:15]
	ds_read_b128 v[240:243], v36 offset:8896
	s_waitcnt lgkmcnt(1)
	v_mfma_f32_16x16x32_bf16 v[12:15], v[244:247], v[0:3], v[16:19]
	ds_read_b128 v[244:247], v36 offset:13248
	s_waitcnt lgkmcnt(1)
	v_mfma_f32_16x16x32_bf16 v[16:19], v[240:243], v[0:3], v[20:23]
	ds_read_b128 v[240:243], v36 offset:17600
	s_waitcnt lgkmcnt(1)
	v_mfma_f32_16x16x32_bf16 v[20:23], v[244:247], v[0:3], v[24:27]
	ds_read_b128 v[244:247], v36 offset:21952
	s_waitcnt lgkmcnt(1)
	v_mfma_f32_16x16x32_bf16 v[24:27], v[240:243], v[0:3], v[28:31]
	s_waitcnt lgkmcnt(0)
	v_mfma_f32_16x16x32_bf16 v[28:31], v[244:247], v[0:3], v[32:35]
	s_nop 2
	ds_read_b128 v[32:35], v36 offset:26304
	ds_read_b128 v[36:39], v36 offset:30656
	s_waitcnt lgkmcnt(1)
	v_mfma_f32_16x16x32_bf16 v[32:35], v[32:35], v[0:3], v[62:65]
	s_waitcnt lgkmcnt(0)
	v_mfma_f32_16x16x32_bf16 v[0:3], v[36:39], v[0:3], v[4:7]
	v_mov_b32_e32 v37, v145
	s_nop 1
	v_lshlrev_b32_e32 v6, 16, v58
	s_waitcnt vmcnt(8)
	v_add_f32_e32 v7, v60, v8
	v_mul_f32_e32 v6, v7, v6
	v_and_b32_e32 v7, 0xffff0000, v58
	v_add_f32_e32 v8, v60, v9
	v_mul_f32_e32 v7, v8, v7
	v_lshlrev_b64 v[4:5], 12, v[56:57]
	v_cvt_pk_bf16_f32 v6, v6, v7
	v_lshlrev_b32_e32 v7, 16, v59
	v_add_f32_e32 v8, v60, v10
	v_lshl_add_u64 v[4:5], s[0:1], 0, v[4:5]
	v_mul_f32_e32 v7, v8, v7
	v_and_b32_e32 v8, 0xffff0000, v59
	v_add_f32_e32 v9, v60, v11
	v_lshl_add_u64 v[4:5], v[4:5], 0, v[144:145]
	v_mul_f32_e32 v8, v9, v8
	v_cvt_pk_bf16_f32 v7, v7, v8
	global_store_dwordx2 v[4:5], v[6:7], off offset:2048
	v_lshlrev_b32_e32 v6, 16, v54
	v_add_f32_e32 v7, v60, v12
	v_mul_f32_e32 v6, v7, v6
	v_and_b32_e32 v7, 0xffff0000, v54
	v_add_f32_e32 v8, v60, v13
	v_mul_f32_e32 v7, v8, v7
	v_cvt_pk_bf16_f32 v6, v6, v7
	v_lshlrev_b32_e32 v7, 16, v55
	v_add_f32_e32 v8, v60, v14
	v_mul_f32_e32 v7, v8, v7
	v_and_b32_e32 v8, 0xffff0000, v55
	v_add_f32_e32 v9, v60, v15
	v_mul_f32_e32 v8, v9, v8
	v_cvt_pk_bf16_f32 v7, v7, v8
	global_store_dwordx2 v[4:5], v[6:7], off offset:2080
	v_lshlrev_b32_e32 v6, 16, v52
	v_add_f32_e32 v7, v60, v16
	v_mul_f32_e32 v6, v7, v6
	v_and_b32_e32 v7, 0xffff0000, v52
	v_add_f32_e32 v8, v60, v17
	v_mul_f32_e32 v7, v8, v7
	v_cvt_pk_bf16_f32 v6, v6, v7
	v_lshlrev_b32_e32 v7, 16, v53
	v_add_f32_e32 v8, v60, v18
	v_mul_f32_e32 v7, v8, v7
	v_and_b32_e32 v8, 0xffff0000, v53
	v_add_f32_e32 v9, v60, v19
	v_mul_f32_e32 v8, v9, v8
	v_cvt_pk_bf16_f32 v7, v7, v8
	global_store_dwordx2 v[4:5], v[6:7], off offset:2112
	v_lshlrev_b32_e32 v6, 16, v50
	v_add_f32_e32 v7, v60, v20
	v_mul_f32_e32 v6, v7, v6
	v_and_b32_e32 v7, 0xffff0000, v50
	v_add_f32_e32 v8, v60, v21
	v_mul_f32_e32 v7, v8, v7
	v_cvt_pk_bf16_f32 v6, v6, v7
	v_lshlrev_b32_e32 v7, 16, v51
	v_add_f32_e32 v8, v60, v22
	v_mul_f32_e32 v7, v8, v7
	v_and_b32_e32 v8, 0xffff0000, v51
; __device__ __forceinline__ unsigned pk2(float lo, float hi) { unsigned r; asm("v_cvt_pk_bf16_f32 %0, %1, %2" : "=v"(r) : "v"(lo), "v"(hi)); return r; }
; __device__ __forceinline__ float bflo(unsigned u) { return __uint_as_float(u << 16); }
; __device__ __forceinline__ float bfhi(unsigned u) { return __uint_as_float(u & 0xffff0000u); }
; #define A2_LOADK(hp_, s_) do { const char* _g = (const char*)(kg0 + (size_t)(s_) * kstep + (hp_) * 256); _Pragma("unroll") for (int j = 0; j < 8; ++j) t8[j] = *(const u32x4*)(_g + (size_t)j * (16 * kld * 2) + kgo); } while (0)
; #define A2_WRITEK(buf_) do { _Pragma("unroll") for (int j = 0; j < 8; ++j) *(LAS u32x4*)((buf_) + klo + j * (16 * 272)) = t8[j]; } while (0)
; template <bool NA> ...
;     ...
;     const unsigned kgo = (unsigned)(((size_t)(tid >> 5) * kld + (tid & 31) * 8) * 2), vgo = (unsigned)(((size_t)(tid >> 4) * vld + (tid & 15) * 8) * 2);
;     const unsigned klo = (unsigned)((((tid >> 4) & 1) * 128 + (tid >> 5)) * 272 + (tid & 15) * 16), vlo = (unsigned)((tid >> 4) * 272 + (tid & 15) * 16);
;     int bidx[8];
;     if (NA) { const int cs = min(max(qc - 8, 0), 48);
; #pragma unroll
;         for (int e = 0; e < 8; ++e) { const int kc = w0 + (e >> 2) * 16 + fq * 4 + (e & 3); bidx[e] = (kc >= cs && kc < cs + 16) ? min(max(kc - qc, -15), 15) + 15 : 31; } }
;     u32x4 t8[8];
;     ...
;     A2_LOADK(0, 0);
;     __syncthreads();
;     A2_WRITEK(lds);
; __device__ __forceinline__ void p5_unit(const Ptrs& P, LAS unsigned char* lds, int unit, int tid_in, int wave) {
;     ...
;             bf16_t* yp = Y + ((size_t)tok0 + pl) * DM + 1024 + g * 128 + fq * 4;
; #pragma unroll
;             for (int c = 0; c < 8; ++c) {
;                 u32x2 w; w.x = pk2(bflo(uw[pb][c].x) * (acc[c].x + bs[pb]), bfhi(uw[pb][c].x) * (acc[c].y + bs[pb])); w.y = pk2(bflo(uw[pb][c].y) * (acc[c].z + bs[pb]), bfhi(uw[pb][c].y) * (acc[c].w + bs[pb]));
;                 *(u32x2*)(yp + c * 16) = w; }
	v_add_f32_e32 v9, v60, v23
	v_mul_f32_e32 v8, v9, v8
	v_cvt_pk_bf16_f32 v7, v7, v8
	global_store_dwordx2 v[4:5], v[6:7], off offset:2144
	v_lshlrev_b32_e32 v6, 16, v48
	v_add_f32_e32 v7, v60, v24
	v_mul_f32_e32 v6, v7, v6
	v_and_b32_e32 v7, 0xffff0000, v48
	v_add_f32_e32 v8, v60, v25
	v_mul_f32_e32 v7, v8, v7
	v_cvt_pk_bf16_f32 v6, v6, v7
	v_lshlrev_b32_e32 v7, 16, v49
	v_add_f32_e32 v8, v60, v26
	v_mul_f32_e32 v7, v8, v7
	v_and_b32_e32 v8, 0xffff0000, v49
	v_add_f32_e32 v9, v60, v27
	v_mul_f32_e32 v8, v9, v8
	v_cvt_pk_bf16_f32 v7, v7, v8
	global_store_dwordx2 v[4:5], v[6:7], off offset:2176
	v_lshlrev_b32_e32 v6, 16, v46
	v_add_f32_e32 v7, v60, v28
	v_mul_f32_e32 v6, v7, v6
	v_and_b32_e32 v7, 0xffff0000, v46
	v_add_f32_e32 v8, v60, v29
	v_mul_f32_e32 v7, v8, v7
	v_cvt_pk_bf16_f32 v6, v6, v7
	v_lshlrev_b32_e32 v7, 16, v47
	v_add_f32_e32 v8, v60, v30
	v_mul_f32_e32 v7, v8, v7
	v_and_b32_e32 v8, 0xffff0000, v47
	v_add_f32_e32 v9, v60, v31
	v_mul_f32_e32 v8, v9, v8
	v_cvt_pk_bf16_f32 v7, v7, v8
	global_store_dwordx2 v[4:5], v[6:7], off offset:2208
	v_lshlrev_b32_e32 v6, 16, v44
	v_add_f32_e32 v7, v60, v32
	v_mul_f32_e32 v6, v7, v6
	v_and_b32_e32 v7, 0xffff0000, v44
	v_add_f32_e32 v8, v60, v33
	v_mul_f32_e32 v7, v8, v7
	v_cvt_pk_bf16_f32 v6, v6, v7
	v_lshlrev_b32_e32 v7, 16, v45
	v_add_f32_e32 v8, v60, v34
	v_mul_f32_e32 v7, v8, v7
	v_and_b32_e32 v8, 0xffff0000, v45
	v_add_f32_e32 v9, v60, v35
	v_mul_f32_e32 v8, v9, v8
	v_cvt_pk_bf16_f32 v7, v7, v8
	global_store_dwordx2 v[4:5], v[6:7], off offset:2240
	v_lshlrev_b32_e32 v6, 16, v42
	v_add_f32_e32 v0, v60, v0
	v_mul_f32_e32 v0, v0, v6
	v_and_b32_e32 v6, 0xffff0000, v42
	v_add_f32_e32 v1, v60, v1
	v_mul_f32_e32 v1, v1, v6
	v_cvt_pk_bf16_f32 v0, v0, v1
	v_lshlrev_b32_e32 v1, 16, v43
	v_add_f32_e32 v2, v60, v2
	v_mul_f32_e32 v1, v2, v1
	v_and_b32_e32 v2, 0xffff0000, v43
	v_add_f32_e32 v3, v60, v3
	v_readlane_b32 s0, v253, 6
	v_mul_f32_e32 v2, v3, v2
	v_cvt_pk_bf16_f32 v1, v1, v2
	global_store_dwordx2 v[4:5], v[0:1], off offset:2272
	s_add_u32 s8, s42, s0
	v_and_b32_e32 v144, 15, v97
	s_addc_u32 s9, s43, 0
	s_ashr_i32 s7, s6, 31
	v_or_b32_e32 v1, s0, v144
	v_bfe_u32 v0, v97, 4, 2
	v_or_b32_e32 v92, s8, v144
	s_lshl_b64 s[10:11], s[6:7], 12
	s_lshl_b32 s23, s22, 6
	v_ashrrev_i32_e32 v114, 5, v97
	s_movk_i32 s0, 0xc00
	v_max_i32_e32 v3, 8, v1
	s_or_b32 s10, s10, s23
	s_mul_i32 s23, s9, 0x1800
	v_mad_u64_u32 v[94:95], s[28:29], v92, s35, v[40:41]
	v_lshlrev_b32_e32 v96, 3, v0
	v_lshlrev_b32_e32 v116, 2, v0
	v_mul_lo_u32 v0, v114, s0
	v_add_u32_e32 v3, -8, v3
	v_readlane_b32 s0, v253, 8
	v_add_u32_e32 v95, s23, v95
	s_mul_i32 s23, s10, 0x1800
	s_mul_hi_u32 s10, s10, 0x1800
	s_mulk_i32 s11, 0x1800
	v_min_u32_e32 v3, 48, v3
	v_add_u32_e32 v4, s0, v116
	s_add_i32 s11, s10, s11
	v_add_u32_e32 v5, 16, v3
	v_sub_u32_e32 v6, v4, v1
	s_add_u32 s10, s30, s23
	v_cmp_ge_u32_e32 vcc, v4, v3
	v_cmp_lt_u32_e64 s[38:39], v4, v5
	v_med3_i32 v6, v6, -15, 15
	s_addc_u32 s11, s31, s11
	s_and_b64 vcc, vcc, s[38:39]
	v_add_u32_e32 v6, 15, v6
	v_cndmask_b32_e32 v41, 31, v6, vcc
	v_or_b32_e32 v6, 1, v4
	v_cmp_ge_u32_e32 vcc, v6, v3
	v_cmp_lt_u32_e64 s[38:39], v6, v5
	v_sub_u32_e32 v6, v6, v1
	v_med3_i32 v6, v6, -15, 15
	s_and_b64 vcc, vcc, s[38:39]
	v_add_u32_e32 v6, 15, v6
	v_cndmask_b32_e32 v38, 31, v6, vcc
	v_or_b32_e32 v6, 2, v4
	v_cmp_ge_u32_e32 vcc, v6, v3
	v_cmp_lt_u32_e64 s[38:39], v6, v5
	v_sub_u32_e32 v6, v6, v1
	v_med3_i32 v6, v6, -15, 15
	v_and_b32_e32 v32, 48, v97
	v_mov_b32_e32 v33, v145
	s_and_b64 vcc, vcc, s[38:39]
	v_add_u32_e32 v6, 15, v6
	v_lshl_add_u64 v[34:35], v[94:95], 0, v[32:33]
	v_cndmask_b32_e32 v33, 31, v6, vcc
	v_or_b32_e32 v6, 3, v4
	v_cmp_ge_u32_e32 vcc, v6, v3
	v_cmp_lt_u32_e64 s[38:39], v6, v5
	v_sub_u32_e32 v6, v6, v1
	v_med3_i32 v6, v6, -15, 15
	s_and_b64 vcc, vcc, s[38:39]
	v_add_u32_e32 v6, 15, v6
	v_cndmask_b32_e32 v39, 31, v6, vcc
	v_add_u32_e32 v6, 16, v4
	v_cmp_ge_u32_e32 vcc, v6, v3
	v_sub_u32_e32 v6, v6, v1
	v_cmp_lt_u32_e64 s[38:39], v4, v3
	v_med3_i32 v6, v6, -15, 15
	s_and_b64 vcc, vcc, s[38:39]
	v_add_u32_e32 v6, 15, v6
	v_cndmask_b32_e32 v44, 31, v6, vcc
	v_add_u32_e32 v6, 17, v4
	v_cmp_ge_u32_e32 vcc, v6, v3
	v_cmp_lt_u32_e64 s[38:39], v6, v5
	v_sub_u32_e32 v6, v6, v1
	v_med3_i32 v6, v6, -15, 15
	s_and_b64 vcc, vcc, s[38:39]
	v_add_u32_e32 v6, 15, v6
	v_cndmask_b32_e32 v40, 31, v6, vcc
	v_add_u32_e32 v6, 18, v4
	v_cmp_ge_u32_e32 vcc, v6, v3
	v_cmp_lt_u32_e64 s[38:39], v6, v5
	v_sub_u32_e32 v6, v6, v1
	v_lshlrev_b32_e32 v2, 3, v97
	s_movk_i32 s23, 0xf8
	v_med3_i32 v6, v6, -15, 15
	v_add_u32_e32 v4, 19, v4
	v_and_or_b32 v0, v2, s23, v0
	s_and_b64 vcc, vcc, s[38:39]
	v_add_u32_e32 v6, 15, v6
	v_sub_u32_e32 v1, v4, v1
	v_cndmask_b32_e32 v43, 31, v6, vcc
	v_cmp_ge_u32_e32 vcc, v4, v3
	v_cmp_lt_u32_e64 s[38:39], v4, v5
	v_med3_i32 v1, v1, -15, 15
	v_lshlrev_b32_e32 v36, 1, v0
	s_and_b64 vcc, vcc, s[38:39]
	v_add_u32_e32 v1, 15, v1
	v_lshl_add_u64 v[28:29], s[10:11], 0, v[36:37]
	s_mov_b32 s0, 0x18000
	v_cndmask_b32_e32 v45, 31, v1, vcc
	v_add_co_u32_e32 v4, vcc, s0, v28
	v_ashrrev_i32_e32 v99, 4, v97
	s_nop 0
	v_addc_co_u32_e32 v5, vcc, 0, v29, vcc
	v_add_co_u32_e32 v8, vcc, s3, v28
	s_mov_b32 s0, 0x48000
	s_nop 0
	v_addc_co_u32_e32 v9, vcc, 0, v29, vcc
	v_lshlrev_b32_e32 v2, 7, v99
	v_add_co_u32_e32 v12, vcc, s0, v28
	v_lshlrev_b32_e32 v115, 4, v97
	v_and_b32_e32 v2, 0x80, v2
	v_addc_co_u32_e32 v13, vcc, 0, v29, vcc
	v_add_u32_e32 v2, v2, v114
	v_and_b32_e32 v98, 0xf0, v115
	v_add_co_u32_e32 v16, vcc, s26, v28
	v_mad_u64_u32 v[100:101], s[28:29], v2, s34, v[98:99]
	global_load_dwordx4 v[0:3], v36, s[10:11] offset:2048
	v_addc_co_u32_e32 v17, vcc, 0, v29, vcc
	s_mov_b32 s0, 0x78000
	global_load_dwordx4 v[4:7], v[4:5], off offset:2048
	v_add_co_u32_e32 v20, vcc, s0, v28
	global_load_dwordx4 v[8:11], v[8:9], off offset:2048
	s_nop 0
	v_addc_co_u32_e32 v21, vcc, 0, v29, vcc
	s_mov_b32 s0, 0x90000
	global_load_dwordx4 v[12:15], v[12:13], off offset:2048
	v_add_co_u32_e32 v24, vcc, s0, v28
	global_load_dwordx4 v[16:19], v[16:17], off offset:2048
	s_nop 0
	v_addc_co_u32_e32 v25, vcc, 0, v29, vcc
	s_mov_b32 s10, 0xa8000
	global_load_dwordx4 v[20:23], v[20:21], off offset:2048
	v_add_co_u32_e32 v28, vcc, s10, v28
	global_load_dwordx4 v[24:27], v[24:25], off offset:2048
	s_nop 0
	v_addc_co_u32_e32 v29, vcc, 0, v29, vcc
	global_load_dwordx4 v[28:31], v[28:29], off offset:2048
	v_add_u32_e32 v154, 0, v100
	s_lshl_b32 s74, s33, 1
	s_barrier
; #define A2_LOADK(hp_, s_) do { const char* _g = (const char*)(kg0 + (size_t)(s_) * kstep + (hp_) * 256); _Pragma("unroll") for (int j = 0; j < 8; ++j) t8[j] = *(const u32x4*)(_g + (size_t)j * (16 * kld * 2) + kgo); } while (0)
; #define A2_WRITEK(buf_) do { _Pragma("unroll") for (int j = 0; j < 8; ++j) *(LAS u32x4*)((buf_) + klo + j * (16 * 272)) = t8[j]; } while (0)
; template <bool NA> ...
;     ...
;     A2_LOADK(0, 0);
;     __syncthreads();
;     A2_WRITEK(lds);
;     __syncthreads();
;     int cb = 0;
;     bf16x8 qf[4], qfn[4];
;     { const bf16_t* qa = qbase + hh * 128;
; #pragma unroll
;       for (int dc = 0; dc < 4; ++dc) { qf[dc] = *(const bf16x8*)(qa + dc * 32); qfn[dc] = qf[dc]; } }
;     __builtin_amdgcn_s_waitcnt(0x0F70);
	s_waitcnt vmcnt(7)
	ds_write_b128 v154, v[0:3]
	s_waitcnt vmcnt(6)
	ds_write_b128 v154, v[4:7] offset:4352
	s_waitcnt vmcnt(5)
	ds_write_b128 v154, v[8:11] offset:8704
	s_waitcnt vmcnt(4)
	ds_write_b128 v154, v[12:15] offset:13056
	s_waitcnt vmcnt(3)
	ds_write_b128 v154, v[16:19] offset:17408
	s_waitcnt vmcnt(2)
	ds_write_b128 v154, v[20:23] offset:21760
	s_waitcnt vmcnt(1)
	ds_write_b128 v154, v[24:27] offset:26112
	s_waitcnt vmcnt(0)
	ds_write_b128 v154, v[28:31] offset:30464
	v_lshl_add_u64 v[12:13], v[34:35], 0, s[74:75]
	s_waitcnt lgkmcnt(0)
	s_barrier
	global_load_dwordx4 v[0:3], v[12:13], off
	global_load_dwordx4 v[4:7], v[12:13], off offset:64
	global_load_dwordx4 v[8:11], v[12:13], off offset:128
	s_nop 0
	global_load_dwordx4 v[12:15], v[12:13], off offset:192
	v_mad_u64_u32 v[102:103], s[10:11], v99, s34, v[98:99]
	s_lshl_b64 s[10:11], s[6:7], 13
	v_and_b32_e32 v42, 63, v97
	s_cmp_lt_u32 s19, 56
	v_readlane_b32 s0, v253, 7
	v_lshlrev_b32_e32 v17, 2, v42
	s_cselect_b32 s7, s19, 56
	v_add_u32_e32 v16, s0, v144
	v_xor_b32_e32 v156, 64, v17
	v_xor_b32_e32 v157, 0x80, v17
	v_or_b32_e32 v17, s33, v144
	s_lshl_b32 s19, s7, 7
	v_mul_u32_u24_e32 v158, 0x110, v17
	v_mad_u32_u24 v101, v17, s34, 0
	v_mul_u32_u24_e32 v117, 0x110, v16
	s_or_b32 s10, s10, s19
	v_lshl_or_b32 v16, v99, 15, v98
	v_mov_b32_e32 v17, v145
	v_lshl_add_u64 v[104:105], s[10:11], 0, v[16:17]
	s_lshl_b32 s10, s22, 7
	v_readlane_b32 s0, v253, 9
	v_lshl_add_u32 v16, v41, 2, s10
	s_lshl_b32 s11, s18, 7
	v_add3_u32 v103, v101, v96, s0
	v_subrev_u32_e32 v16, s11, v16
	v_readlane_b32 s0, v251, 46
	s_mul_hi_u32 s18, s7, 0x60000
	s_mul_i32 s7, s7, 0x60000
	v_add_u32_e32 v152, s0, v16
	v_lshl_add_u64 v[16:17], s[8:9], 0, v[144:145]
	v_lshlrev_b64 v[18:19], 12, v[16:17]
	v_or_b32_e32 v18, v18, v96
	s_mul_i32 s8, s6, 0x1800000
	v_mov_b32_e32 v93, s9
	v_lshl_add_u64 v[106:107], s[64:65], 0, v[18:19]
	s_mul_hi_i32 s9, s6, 0x1800000
	s_add_u32 s8, s8, s7
	v_lshl_add_u32 v18, v44, 2, s10
	s_addc_u32 s9, s9, s18
	v_subrev_u32_e32 v18, s11, v18
	v_lshl_add_u64 v[108:109], s[8:9], 0, v[36:37]
	v_add_u32_e32 v144, s0, v18
	v_mad_u64_u32 v[18:19], s[8:9], v16, s35, 0
	v_mov_b32_e32 v16, v19
	v_mad_u64_u32 v[16:17], s[8:9], v17, s35, v[16:17]
	v_mov_b32_e32 v19, v16
	v_lshl_add_u32 v16, v45, 2, s10
	v_subrev_u32_e32 v16, s11, v16
	v_add_u32_e32 v153, s0, v16
	v_lshl_add_u32 v16, v38, 2, s10
	v_subrev_u32_e32 v16, s11, v16
	v_add_u32_e32 v163, s0, v16
	v_lshl_add_u32 v16, v39, 2, s10
	v_subrev_u32_e32 v16, s11, v16
	v_add_u32_e32 v164, s0, v16
	v_lshl_add_u32 v16, v40, 2, s10
	v_subrev_u32_e32 v16, s11, v16
	v_add_u32_e32 v165, s0, v16
	v_lshl_add_u32 v16, v43, 2, s10
	v_subrev_u32_e32 v16, s11, v16
	v_add_u32_e32 v166, s0, v16
	v_lshl_add_u32 v16, v33, 2, s10
	v_subrev_u32_e32 v16, s11, v16
	v_add_u32_e32 v155, 0, v32
	v_or_b32_e32 v18, v18, v32
	s_mov_b64 s[8:9], 0xe820280
	v_add_u32_e32 v167, s0, v16
	v_readlane_b32 s0, v251, 47
	v_add_u32_e32 v159, 0x11000, v155
	v_add_u32_e32 v118, 0x11000, v103
	v_add_u32_e32 v119, 0x11020, v103
	v_add_u32_e32 v120, 0x12100, v103
	v_add_u32_e32 v121, 0x12120, v103
	v_add_u32_e32 v122, 0x13200, v103
	v_add_u32_e32 v123, 0x13220, v103
	v_add_u32_e32 v124, 0x14300, v103
	v_add_u32_e32 v125, 0x14320, v103
	v_add_u32_e32 v126, 0x15400, v103
	v_add_u32_e32 v127, 0x15420, v103
	v_add_u32_e32 v128, 0x16500, v103
	v_add_u32_e32 v129, 0x16520, v103
	v_add_u32_e32 v130, 0x17600, v103
	v_add_u32_e32 v131, 0x17620, v103
	v_add_u32_e32 v132, 0x18700, v103
	v_add_u32_e32 v133, 0x18720, v103
	v_add_u32_e32 v134, 0x11080, v103
	v_add_u32_e32 v135, 0x110a0, v103
	v_add_u32_e32 v136, 0x12180, v103
	v_add_u32_e32 v137, 0x121a0, v103
	v_add_u32_e32 v138, 0x13280, v103
	v_add_u32_e32 v139, 0x132a0, v103
	v_add_u32_e32 v140, 0x14380, v103
	v_add_u32_e32 v141, 0x143a0, v103
	v_add_u32_e32 v142, 0x15480, v103
	v_add_u32_e32 v143, 0x154a0, v103
	v_add_u32_e32 v146, 0x16580, v103
	v_add_u32_e32 v147, 0x165a0, v103
	v_add_u32_e32 v148, 0x17680, v103
	v_add_u32_e32 v149, 0x176a0, v103
	v_add_u32_e32 v150, 0x18780, v103
	v_add_u32_e32 v151, 0x187a0, v103
	v_lshl_add_u64 v[110:111], v[18:19], 0, s[8:9]
	v_readlane_b32 s1, v251, 48
	s_waitcnt vmcnt(0)
	s_branch .LBB0_221

; #define LAS __attribute__((address_space(3)))
; #define SCHED_FENCE() __builtin_amdgcn_sched_barrier(0)
; __device__ __forceinline__ f32x4 mfma16(bf16x8 a, bf16x8 b, f32x4 c) { return __builtin_amdgcn_mfma_f32_16x16x32_bf16(a, b, c, 0, 0, 0); }
; #define A2_LOADK(hp_, s_) do { const char* _g = (const char*)(kg0 + (size_t)(s_) * kstep + (hp_) * 256); _Pragma("unroll") for (int j = 0; j < 8; ++j) t8[j] = *(const u32x4*)(_g + (size_t)j * (16 * kld * 2) + kgo); } while (0)
; #define A2_LOADV(hp_, s_) do { const char* _g = (const char*)(vg0 + (size_t)(hp_) * 256 * vld + (size_t)(s_) * vstep); _Pragma("unroll") for (int j = 0; j < 8; ++j) t8[j] = *(const u32x4*)(_g + (size_t)j * (32 * vld * 2) + vgo); } while (0)
; #define A2_WRITEK(buf_) do { _Pragma("unroll") for (int j = 0; j < 8; ++j) *(LAS u32x4*)((buf_) + klo + j * (16 * 272)) = t8[j]; } while (0)
; template <bool NA> ...
;     ...
;         for (int ks = 0; ks < NSTEP; ++ks) {
;             LAS unsigned char* cur = lds + cb * ABUF2; LAS unsigned char* nxt = lds + (cb ^ 1) * ABUF2;
;             if (ks < NSTEP - 1) A2_LOADK(hp, ks + 1); else A2_LOADV(hp, 0);
;             SCHED_FENCE();
; #pragma unroll
;             for (int g = 0; g < NGRP; ++g) {
;                 const int gi = ks * NGRP + g, koff = NA ? g * 64 + w0 : g * 32;
;                 const LAS unsigned char* kp = cur + (hh * 128 + koff + fr) * 272 + fq * 16;
;                 bf16x8 kf[2][4];
; #pragma unroll
;                 for (int a = 0; a < 2; ++a)
; #pragma unroll
;                     for (int dc = 0; dc < 4; ++dc) kf[a][dc] = *(const LAS bf16x8*)(kp + a * 16 * 272 + dc * 64);
;                 f32x4 s0 = (f32x4){0.f, 0.f, 0.f, 0.f}, s1 = (f32x4){0.f, 0.f, 0.f, 0.f};
; #pragma unroll
;                 for (int dc = 0; dc < 4; ++dc) { s0 = mfma16(kf[0][dc], qf[dc], s0); s1 = mfma16(kf[1][dc], qf[dc], s1); }
;                 if (NA) { const LAS float* br = rpb + ((hp * 2 + hh) * 15 + brow0 + 2 * ks + g) * 32;
; #pragma unroll
;                     for (int e = 0; e < 4; ++e) { s0[e] += br[bidx[e]]; s1[e] += br[bidx[4 + e]]; } }
;                 sc[gi][0] = s0; sc[gi][1] = s1;
;             }
;             SCHED_FENCE();
;             if (ks < NSTEP - 1) A2_WRITEK(nxt); else A2_WRITEV(nxt);
;             __syncthreads(); cb ^= 1;
.LBB0_221:
	v_lshl_add_u64 v[112:113], s[66:67], 0, v[108:109]
	v_add_co_u32_e32 v16, vcc, 0xe8e0000, v112
	s_nop 1
	v_addc_co_u32_e32 v17, vcc, 0, v113, vcc
	v_add_co_u32_e32 v18, vcc, 0xe8f8000, v112
	s_nop 1
	v_addc_co_u32_e32 v19, vcc, 0, v113, vcc
	global_load_dwordx4 v[44:47], v[16:17], off offset:2048
	global_load_dwordx4 v[48:51], v[18:19], off offset:2048
	v_add_co_u32_e32 v16, vcc, 0xe910000, v112
	s_nop 1
	v_addc_co_u32_e32 v17, vcc, 0, v113, vcc
	v_add_co_u32_e32 v18, vcc, 0xe928000, v112
	s_nop 1
	v_addc_co_u32_e32 v19, vcc, 0, v113, vcc
	global_load_dwordx4 v[52:55], v[16:17], off offset:2048
	global_load_dwordx4 v[56:59], v[18:19], off offset:2048
	v_add_co_u32_e32 v16, vcc, 0xe940000, v112
	s_nop 1
	v_addc_co_u32_e32 v17, vcc, 0, v113, vcc
	v_add_co_u32_e32 v18, vcc, 0xe958000, v112
	s_nop 1
	v_addc_co_u32_e32 v19, vcc, 0, v113, vcc
	global_load_dwordx4 v[60:63], v[16:17], off offset:2048
	global_load_dwordx4 v[64:67], v[18:19], off offset:2048
	v_add_co_u32_e32 v16, vcc, 0xe970000, v112
	s_nop 1
	v_addc_co_u32_e32 v17, vcc, 0, v113, vcc
	v_add_co_u32_e32 v18, vcc, 0xe988000, v112
	s_nop 1
	v_addc_co_u32_e32 v19, vcc, 0, v113, vcc
	global_load_dwordx4 v[68:71], v[16:17], off offset:2048
	global_load_dwordx4 v[72:75], v[18:19], off offset:2048
	v_lshl_add_u64 v[16:17], s[66:67], 0, v[104:105]
	s_waitcnt vmcnt(21)
	v_add_u32_e32 v42, v155, v117
	ds_read_b128 v[18:21], v42
	ds_read_b128 v[22:25], v42 offset:64
	ds_read_b128 v[26:29], v42 offset:4352
	ds_read_b128 v[30:33], v42 offset:4416
	v_add_u32_e32 v35, s13, v144
	v_add_u32_e32 v41, s13, v164
	s_waitcnt vmcnt(19) lgkmcnt(3)
	v_mfma_f32_16x16x32_bf16 v[18:21], v[18:21], v[0:3], 0
	v_add_u32_e32 v40, s13, v153
	v_add_u32_e32 v161, 0x23380, v41
	v_add_u32_e32 v162, 0x23380, v40
	s_waitcnt lgkmcnt(1)
	v_mfma_f32_16x16x32_bf16 v[26:29], v[26:29], v[0:3], 0
	s_waitcnt vmcnt(18)
	v_mfma_f32_16x16x32_bf16 v[18:21], v[22:25], v[4:7], v[18:21]
	ds_read_b128 v[22:25], v42 offset:128
	ds_read_b128 v[36:39], v42 offset:4480
	ds_read_b128 v[76:79], v42 offset:192
	ds_read_b128 v[80:83], v42 offset:4544
	ds_read_b128 v[84:87], v42 offset:21824
	s_waitcnt lgkmcnt(5)
	v_mfma_f32_16x16x32_bf16 v[30:33], v[30:33], v[4:7], v[26:29]
	s_waitcnt vmcnt(17) lgkmcnt(4)
	v_mfma_f32_16x16x32_bf16 v[18:21], v[22:25], v[8:11], v[18:21]
	s_nop 0
	v_add_u32_e32 v29, s13, v152
	v_add_u32_e32 v26, 0x23380, v29
	v_add_u32_e32 v27, 0x23380, v35
	s_waitcnt lgkmcnt(3)
	v_mfma_f32_16x16x32_bf16 v[22:25], v[36:39], v[8:11], v[30:33]
	v_add_u32_e32 v36, s13, v163
	v_add_u32_e32 v37, s13, v165
	v_add_u32_e32 v38, s13, v167
	ds_read_b128 v[30:33], v42 offset:17408
	s_waitcnt vmcnt(16) lgkmcnt(3)
	v_mfma_f32_16x16x32_bf16 v[76:79], v[76:79], v[12:15], v[18:21]
	v_add_u32_e32 v39, s13, v166
	v_add_u32_e32 v28, 0x23380, v36
	v_add_u32_e32 v34, 0x23380, v37
	ds_read_b128 v[18:21], v42 offset:21760
	s_waitcnt lgkmcnt(3)
	v_mfma_f32_16x16x32_bf16 v[80:83], v[80:83], v[12:15], v[22:25]
	v_add_u32_e32 v43, 0x23380, v38
	v_add_u32_e32 v160, 0x23380, v39
	s_nop 0
	ds_read_b128 v[22:25], v42 offset:17472
	s_waitcnt lgkmcnt(2)
	v_mfma_f32_16x16x32_bf16 v[30:33], v[30:33], v[0:3], 0
	s_waitcnt lgkmcnt(1)
	v_mfma_f32_16x16x32_bf16 v[18:21], v[18:21], v[0:3], 0
	s_waitcnt lgkmcnt(0)
	v_mfma_f32_16x16x32_bf16 v[22:25], v[22:25], v[4:7], v[30:33]
	s_nop 3
	ds_read_b128 v[30:33], v42 offset:17536
	ds_read_b128 v[88:91], v42 offset:21888
	v_mfma_f32_16x16x32_bf16 v[18:21], v[84:87], v[4:7], v[18:21]
	ds_read_b32 v26, v26
	ds_read_b32 v27, v27
	ds_read_b32 v28, v28
	ds_read_b32 v34, v34
	ds_read_b32 v43, v43
	ds_read_b32 v160, v160
	ds_read_b32 v161, v161
	ds_read_b32 v162, v162
	ds_read_b128 v[84:87], v42 offset:17600
	ds_read_b128 v[168:171], v42 offset:21952
	s_waitcnt lgkmcnt(11)
	v_mfma_f32_16x16x32_bf16 v[30:33], v[30:33], v[8:11], v[22:25]
	s_waitcnt lgkmcnt(10)
	v_mfma_f32_16x16x32_bf16 v[88:91], v[88:91], v[8:11], v[18:21]
	s_waitcnt lgkmcnt(9)
	v_add_f32_e32 v24, v76, v26
	s_waitcnt lgkmcnt(8)
	v_add_f32_e32 v22, v80, v27
	s_waitcnt lgkmcnt(7)
	v_add_f32_e32 v25, v77, v28
	s_waitcnt lgkmcnt(1)
	v_mfma_f32_16x16x32_bf16 v[84:87], v[84:87], v[12:15], v[30:33]
	v_add_u32_e32 v26, 0x23400, v29
	v_add_u32_e32 v27, 0x23400, v35
	v_add_u32_e32 v28, 0x23400, v36
	v_add_u32_e32 v30, 0x23400, v37
	v_add_f32_e32 v23, v81, v34
	v_add_f32_e32 v20, v78, v43
	v_add_f32_e32 v21, v82, v160
	v_add_u32_e32 v31, 0x23400, v38
	v_add_u32_e32 v32, 0x23400, v39
	v_add_u32_e32 v33, 0x23400, v41
	v_add_u32_e32 v34, 0x23400, v40
	ds_read_b32 v26, v26
	ds_read_b32 v27, v27
	ds_read_b32 v28, v28
	ds_read_b32 v30, v30
	ds_read_b32 v43, v31
	ds_read_b32 v80, v32
	ds_read_b32 v81, v33
	ds_read_b32 v82, v34
	v_add_f32_e32 v19, v79, v161
	s_waitcnt lgkmcnt(8)
	v_mfma_f32_16x16x32_bf16 v[76:79], v[168:171], v[12:15], v[88:91]
	v_add_f32_e32 v18, v83, v162
	s_waitcnt lgkmcnt(7)
	v_add_f32_e32 v34, v84, v26
	s_waitcnt lgkmcnt(5)
	v_add_f32_e32 v32, v85, v28
	s_nop 2
	v_add_f32_e32 v33, v76, v27
	s_waitcnt lgkmcnt(4)
	v_add_f32_e32 v31, v77, v30
	s_waitcnt lgkmcnt(3)
	v_add_f32_e32 v30, v86, v43
	s_waitcnt lgkmcnt(2)
	v_add_f32_e32 v28, v78, v80
	s_waitcnt lgkmcnt(1)
	v_add_f32_e32 v27, v87, v81
	s_waitcnt lgkmcnt(0)
	v_add_f32_e32 v26, v79, v82
	s_add_i32 s7, 0, 0x11000
	v_add_u32_e32 v160, s7, v100
	s_mov_b32 s8, 0xe9a0000
	s_waitcnt vmcnt(7)
	ds_write_b128 v160, v[44:47]
	s_waitcnt vmcnt(6)
	ds_write_b128 v160, v[48:51] offset:4352
	s_waitcnt vmcnt(5)
	ds_write_b128 v160, v[52:55] offset:8704
	s_waitcnt vmcnt(4)
	ds_write_b128 v160, v[56:59] offset:13056
	s_waitcnt vmcnt(3)
	ds_write_b128 v160, v[60:63] offset:17408
	s_waitcnt vmcnt(2)
	ds_write_b128 v160, v[64:67] offset:21760
	s_waitcnt vmcnt(1)
	ds_write_b128 v160, v[68:71] offset:26112
	s_waitcnt vmcnt(0)
	ds_write_b128 v160, v[72:75] offset:30464
	v_add_co_u32_e32 v44, vcc, s8, v112
	s_mov_b32 s8, 0xe9b8000
	s_nop 0
	v_addc_co_u32_e32 v45, vcc, 0, v113, vcc
	v_add_co_u32_e32 v48, vcc, s8, v112
	s_mov_b32 s8, 0xe9d0000
	s_nop 0
	v_addc_co_u32_e32 v49, vcc, 0, v113, vcc
	v_add_co_u32_e32 v52, vcc, s8, v112
	s_mov_b32 s8, 0xe9e8000
	s_nop 0
	v_addc_co_u32_e32 v53, vcc, 0, v113, vcc
	v_add_co_u32_e32 v54, vcc, s8, v112
	s_mov_b32 s8, 0xea00000
	s_nop 0
	v_addc_co_u32_e32 v55, vcc, 0, v113, vcc
	s_waitcnt lgkmcnt(0)
	s_barrier
; #define LAS __attribute__((address_space(3)))
; #define SCHED_FENCE() __builtin_amdgcn_sched_barrier(0)
; __device__ __forceinline__ f32x4 mfma16(bf16x8 a, bf16x8 b, f32x4 c) { return __builtin_amdgcn_mfma_f32_16x16x32_bf16(a, b, c, 0, 0, 0); }
; #define A2_LOADK(hp_, s_) do { const char* _g = (const char*)(kg0 + (size_t)(s_) * kstep + (hp_) * 256); _Pragma("unroll") for (int j = 0; j < 8; ++j) t8[j] = *(const u32x4*)(_g + (size_t)j * (16 * kld * 2) + kgo); } while (0)
; #define A2_LOADV(hp_, s_) do { const char* _g = (const char*)(vg0 + (size_t)(hp_) * 256 * vld + (size_t)(s_) * vstep); _Pragma("unroll") for (int j = 0; j < 8; ++j) t8[j] = *(const u32x4*)(_g + (size_t)j * (32 * vld * 2) + vgo); } while (0)
; #define A2_WRITEK(buf_) do { _Pragma("unroll") for (int j = 0; j < 8; ++j) *(LAS u32x4*)((buf_) + klo + j * (16 * 272)) = t8[j]; } while (0)
; template <bool NA> ...
;     ...
;         for (int ks = 0; ks < NSTEP; ++ks) {
;             LAS unsigned char* cur = lds + cb * ABUF2; LAS unsigned char* nxt = lds + (cb ^ 1) * ABUF2;
;             if (ks < NSTEP - 1) A2_LOADK(hp, ks + 1); else A2_LOADV(hp, 0);
;             SCHED_FENCE();
; #pragma unroll
;             for (int g = 0; g < NGRP; ++g) {
;                 const int gi = ks * NGRP + g, koff = NA ? g * 64 + w0 : g * 32;
;                 const LAS unsigned char* kp = cur + (hh * 128 + koff + fr) * 272 + fq * 16;
;                 bf16x8 kf[2][4];
; #pragma unroll
;                 for (int a = 0; a < 2; ++a)
; #pragma unroll
;                     for (int dc = 0; dc < 4; ++dc) kf[a][dc] = *(const LAS bf16x8*)(kp + a * 16 * 272 + dc * 64);
;                 f32x4 s0 = (f32x4){0.f, 0.f, 0.f, 0.f}, s1 = (f32x4){0.f, 0.f, 0.f, 0.f};
; #pragma unroll
;                 for (int dc = 0; dc < 4; ++dc) { s0 = mfma16(kf[0][dc], qf[dc], s0); s1 = mfma16(kf[1][dc], qf[dc], s1); }
;                 if (NA) { const LAS float* br = rpb + ((hp * 2 + hh) * 15 + brow0 + 2 * ks + g) * 32;
; #pragma unroll
;                     for (int e = 0; e < 4; ++e) { s0[e] += br[bidx[e]]; s1[e] += br[bidx[4 + e]]; } }
;                 sc[gi][0] = s0; sc[gi][1] = s1;
;             }
;             SCHED_FENCE();
;             if (ks < NSTEP - 1) A2_WRITEK(nxt); else A2_WRITEV(nxt);
;             __syncthreads(); cb ^= 1;
	global_load_dwordx4 v[44:47], v[44:45], off offset:2048
	s_nop 0
	global_load_dwordx4 v[48:51], v[48:49], off offset:2048
	s_nop 0
	global_load_dwordx4 v[56:59], v[52:53], off offset:2048
	global_load_dwordx4 v[60:63], v[54:55], off offset:2048
	v_add_co_u32_e32 v52, vcc, s8, v112
	s_mov_b32 s8, 0xea18000
	s_nop 0
	v_addc_co_u32_e32 v53, vcc, 0, v113, vcc
	v_add_co_u32_e32 v54, vcc, s8, v112
	s_mov_b32 s8, 0xea30000
	s_nop 0
	v_addc_co_u32_e32 v55, vcc, 0, v113, vcc
	global_load_dwordx4 v[76:79], v[52:53], off offset:2048
	global_load_dwordx4 v[80:83], v[54:55], off offset:2048
	v_add_co_u32_e32 v52, vcc, s8, v112
	s_mov_b32 s8, 0xea48000
	s_nop 0
	v_addc_co_u32_e32 v53, vcc, 0, v113, vcc
	v_add_co_u32_e32 v54, vcc, s8, v112
	s_nop 1
	v_addc_co_u32_e32 v55, vcc, 0, v113, vcc
	global_load_dwordx4 v[84:87], v[52:53], off offset:2048
	global_load_dwordx4 v[88:91], v[54:55], off offset:2048
	v_add_u32_e32 v43, v159, v117
	ds_read_b128 v[52:55], v43
	ds_read_b128 v[64:67], v43 offset:64
	ds_read_b128 v[68:71], v43 offset:4352
	ds_read_b128 v[72:75], v43 offset:4416
	v_add_u32_e32 v161, 0x23480, v29
	v_add_u32_e32 v162, 0x23480, v35
	s_waitcnt lgkmcnt(3)
	v_mfma_f32_16x16x32_bf16 v[52:55], v[52:55], v[0:3], 0
	v_add_u32_e32 v176, 0x23480, v36
	v_add_u32_e32 v177, 0x23480, v37
	v_add_u32_e32 v178, 0x23480, v38
	s_waitcnt lgkmcnt(2)
	v_mfma_f32_16x16x32_bf16 v[52:55], v[64:67], v[4:7], v[52:55]
	ds_read_b128 v[64:67], v43 offset:128
	v_add_u32_e32 v179, 0x23480, v39
	v_add_u32_e32 v180, 0x23480, v41
	s_waitcnt lgkmcnt(2)
	v_mfma_f32_16x16x32_bf16 v[68:71], v[68:71], v[0:3], 0
	s_waitcnt lgkmcnt(1)
	v_mfma_f32_16x16x32_bf16 v[68:71], v[72:75], v[4:7], v[68:71]
	ds_read_b128 v[72:75], v43 offset:4480
	ds_read_b128 v[168:171], v43 offset:192
	s_waitcnt lgkmcnt(2)
	v_mfma_f32_16x16x32_bf16 v[52:55], v[64:67], v[8:11], v[52:55]
	ds_read_b128 v[64:67], v43 offset:4544
	s_waitcnt lgkmcnt(2)
	v_mfma_f32_16x16x32_bf16 v[68:71], v[72:75], v[8:11], v[68:71]
	ds_read_b128 v[72:75], v43 offset:17408
	s_waitcnt lgkmcnt(2)
	v_mfma_f32_16x16x32_bf16 v[52:55], v[168:171], v[12:15], v[52:55]
	ds_read_b128 v[168:171], v43 offset:17472
	ds_read_b128 v[172:175], v43 offset:21760
	s_waitcnt lgkmcnt(3)
	v_mfma_f32_16x16x32_bf16 v[66:69], v[64:67], v[12:15], v[68:71]
	v_add_u32_e32 v64, 0x23480, v40
	s_waitcnt lgkmcnt(2)
	v_mfma_f32_16x16x32_bf16 v[70:73], v[72:75], v[0:3], 0
	ds_read_b32 v65, v161
	ds_read_b32 v74, v162
	ds_read_b32 v75, v176
	ds_read_b32 v161, v177
	ds_read_b32 v162, v178
	ds_read_b32 v184, v179
	ds_read_b32 v185, v180
	ds_read_b32 v186, v64
	ds_read_b128 v[176:179], v43 offset:21824
	ds_read_b128 v[180:183], v43 offset:17536
	s_waitcnt lgkmcnt(9)
	v_add_f32_e32 v64, v52, v65
	v_mfma_f32_16x16x32_bf16 v[172:175], v[172:175], v[0:3], 0
	s_waitcnt lgkmcnt(8)
	v_add_f32_e32 v52, v66, v74
	s_waitcnt lgkmcnt(7)
	v_add_f32_e32 v65, v53, v75
	s_waitcnt lgkmcnt(6)
	v_add_f32_e32 v53, v67, v161
	v_mfma_f32_16x16x32_bf16 v[70:73], v[168:171], v[4:7], v[70:73]
	ds_read_b128 v[168:171], v43 offset:21888
	s_waitcnt lgkmcnt(6)
	v_add_f32_e32 v66, v54, v162
	s_waitcnt lgkmcnt(5)
	v_add_f32_e32 v54, v68, v184
	s_waitcnt lgkmcnt(2)
	v_mfma_f32_16x16x32_bf16 v[172:175], v[176:179], v[4:7], v[172:175]
	ds_read_b128 v[176:179], v43 offset:17600
	v_add_f32_e32 v67, v55, v185
	v_add_f32_e32 v55, v69, v186
	s_waitcnt lgkmcnt(2)
	v_mfma_f32_16x16x32_bf16 v[70:73], v[180:183], v[8:11], v[70:73]
	ds_read_b128 v[180:183], v43 offset:21952
	v_add_u32_e32 v68, 0x23500, v29
	v_add_u32_e32 v69, 0x23500, v35
	s_waitcnt lgkmcnt(2)
	v_mfma_f32_16x16x32_bf16 v[168:171], v[168:171], v[8:11], v[172:175]
	v_add_u32_e32 v74, 0x23500, v36
	v_add_u32_e32 v75, 0x23500, v40
	s_waitcnt lgkmcnt(1)
	v_mfma_f32_16x16x32_bf16 v[172:175], v[176:179], v[12:15], v[70:73]
	s_nop 2
	v_add_u32_e32 v70, 0x23500, v37
	v_add_u32_e32 v71, 0x23500, v38
	v_add_u32_e32 v72, 0x23500, v39
	v_add_u32_e32 v73, 0x23500, v41
	ds_read_b32 v68, v68
	ds_read_b32 v69, v69
	ds_read_b32 v161, v74
	ds_read_b32 v70, v70
	ds_read_b32 v71, v71
	ds_read_b32 v162, v72
	ds_read_b32 v176, v73
	ds_read_b32 v177, v75
	s_waitcnt lgkmcnt(8)
	v_mfma_f32_16x16x32_bf16 v[168:171], v[180:183], v[12:15], v[168:171]
	s_waitcnt lgkmcnt(7)
	v_add_f32_e32 v75, v172, v68
	s_waitcnt lgkmcnt(5)
	v_add_f32_e32 v73, v173, v161
	s_waitcnt lgkmcnt(3)
	v_add_f32_e32 v71, v174, v71
	s_nop 1
	v_add_f32_e32 v74, v168, v69
	v_add_f32_e32 v72, v169, v70
	s_waitcnt lgkmcnt(2)
	v_add_f32_e32 v70, v170, v162
	s_waitcnt lgkmcnt(1)
	v_add_f32_e32 v69, v175, v176
	s_waitcnt lgkmcnt(0)
	v_add_f32_e32 v68, v171, v177
	s_mov_b32 s8, 0xea60000
	s_waitcnt vmcnt(7)
	ds_write_b128 v154, v[44:47]
	s_waitcnt vmcnt(6)
	ds_write_b128 v154, v[48:51] offset:4352
	s_waitcnt vmcnt(5)
	ds_write_b128 v154, v[56:59] offset:8704
	s_waitcnt vmcnt(4)
	ds_write_b128 v154, v[60:63] offset:13056
	s_waitcnt vmcnt(3)
	ds_write_b128 v154, v[76:79] offset:17408
	s_waitcnt vmcnt(2)
	ds_write_b128 v154, v[80:83] offset:21760
	s_waitcnt vmcnt(1)
	ds_write_b128 v154, v[84:87] offset:26112
	s_waitcnt vmcnt(0)
	ds_write_b128 v154, v[88:91] offset:30464
	v_add_co_u32_e32 v44, vcc, s8, v112
	s_mov_b32 s8, 0xea78000
	s_nop 0
	v_addc_co_u32_e32 v45, vcc, 0, v113, vcc
	v_add_co_u32_e32 v48, vcc, s8, v112
	s_mov_b32 s8, 0xea90000
	s_nop 0
	v_addc_co_u32_e32 v49, vcc, 0, v113, vcc
	v_add_co_u32_e32 v56, vcc, s8, v112
	s_mov_b32 s8, 0xeaa8000
	s_nop 0
	v_addc_co_u32_e32 v57, vcc, 0, v113, vcc
	v_add_co_u32_e32 v60, vcc, s8, v112
	s_mov_b32 s8, 0xeac0000
	s_nop 0
	v_addc_co_u32_e32 v61, vcc, 0, v113, vcc
	v_add_co_u32_e32 v76, vcc, s8, v112
	s_mov_b32 s8, 0xead8000
	s_nop 0
	v_addc_co_u32_e32 v77, vcc, 0, v113, vcc
	v_add_co_u32_e32 v82, vcc, s8, v112
	s_mov_b32 s8, 0xeaf0000
	s_nop 0
	v_addc_co_u32_e32 v83, vcc, 0, v113, vcc
	s_waitcnt lgkmcnt(0)
	s_barrier
; #define LAS __attribute__((address_space(3)))
; #define SCHED_FENCE() __builtin_amdgcn_sched_barrier(0)
; __device__ __forceinline__ f32x4 mfma16(bf16x8 a, bf16x8 b, f32x4 c) { return __builtin_amdgcn_mfma_f32_16x16x32_bf16(a, b, c, 0, 0, 0); }
; #define A2_LOADK(hp_, s_) do { const char* _g = (const char*)(kg0 + (size_t)(s_) * kstep + (hp_) * 256); _Pragma("unroll") for (int j = 0; j < 8; ++j) t8[j] = *(const u32x4*)(_g + (size_t)j * (16 * kld * 2) + kgo); } while (0)
; #define A2_LOADV(hp_, s_) do { const char* _g = (const char*)(vg0 + (size_t)(hp_) * 256 * vld + (size_t)(s_) * vstep); _Pragma("unroll") for (int j = 0; j < 8; ++j) t8[j] = *(const u32x4*)(_g + (size_t)j * (32 * vld * 2) + vgo); } while (0)
; #define A2_WRITEK(buf_) do { _Pragma("unroll") for (int j = 0; j < 8; ++j) *(LAS u32x4*)((buf_) + klo + j * (16 * 272)) = t8[j]; } while (0)
; template <bool NA> ...
;     ...
;         for (int ks = 0; ks < NSTEP; ++ks) {
;             LAS unsigned char* cur = lds + cb * ABUF2; LAS unsigned char* nxt = lds + (cb ^ 1) * ABUF2;
;             if (ks < NSTEP - 1) A2_LOADK(hp, ks + 1); else A2_LOADV(hp, 0);
;             SCHED_FENCE();
; #pragma unroll
;             for (int g = 0; g < NGRP; ++g) {
;                 const int gi = ks * NGRP + g, koff = NA ? g * 64 + w0 : g * 32;
;                 const LAS unsigned char* kp = cur + (hh * 128 + koff + fr) * 272 + fq * 16;
;                 bf16x8 kf[2][4];
; #pragma unroll
;                 for (int a = 0; a < 2; ++a)
; #pragma unroll
;                     for (int dc = 0; dc < 4; ++dc) kf[a][dc] = *(const LAS bf16x8*)(kp + a * 16 * 272 + dc * 64);
;                 f32x4 s0 = (f32x4){0.f, 0.f, 0.f, 0.f}, s1 = (f32x4){0.f, 0.f, 0.f, 0.f};
; #pragma unroll
;                 for (int dc = 0; dc < 4; ++dc) { s0 = mfma16(kf[0][dc], qf[dc], s0); s1 = mfma16(kf[1][dc], qf[dc], s1); }
;                 if (NA) { const LAS float* br = rpb + ((hp * 2 + hh) * 15 + brow0 + 2 * ks + g) * 32;
; #pragma unroll
;                     for (int e = 0; e < 4; ++e) { s0[e] += br[bidx[e]]; s1[e] += br[bidx[4 + e]]; } }
;                 sc[gi][0] = s0; sc[gi][1] = s1;
;             }
;             SCHED_FENCE();
;             if (ks < NSTEP - 1) A2_WRITEK(nxt); else A2_WRITEV(nxt);
;             __syncthreads(); cb ^= 1;
	global_load_dwordx4 v[44:47], v[44:45], off offset:2048
	s_nop 0
	global_load_dwordx4 v[48:51], v[48:49], off offset:2048
	s_nop 0
	global_load_dwordx4 v[56:59], v[56:57], off offset:2048
	s_nop 0
	global_load_dwordx4 v[60:63], v[60:61], off offset:2048
	s_nop 0
	global_load_dwordx4 v[78:81], v[76:77], off offset:2048
	s_nop 0
	global_load_dwordx4 v[82:85], v[82:83], off offset:2048
	v_add_co_u32_e32 v76, vcc, s8, v112
	s_mov_b32 s8, 0xeb08000
	s_nop 0
	v_addc_co_u32_e32 v77, vcc, 0, v113, vcc
	v_add_co_u32_e32 v90, vcc, s8, v112
	s_nop 1
	v_addc_co_u32_e32 v91, vcc, 0, v113, vcc
	global_load_dwordx4 v[86:89], v[76:77], off offset:2048
	global_load_dwordx4 v[168:171], v[90:91], off offset:2048
	ds_read_b128 v[172:175], v42
	ds_read_b128 v[176:179], v42 offset:64
	ds_read_b128 v[180:183], v42 offset:4352
	ds_read_b128 v[184:187], v42 offset:4416
	v_add_u32_e32 v76, 0x23580, v29
	v_add_u32_e32 v77, 0x23580, v35
	s_waitcnt lgkmcnt(3)
	v_mfma_f32_16x16x32_bf16 v[172:175], v[172:175], v[0:3], 0
	v_add_u32_e32 v90, 0x23580, v36
	v_add_u32_e32 v91, 0x23580, v37
	v_add_u32_e32 v161, 0x23580, v38
	s_waitcnt lgkmcnt(2)
	v_mfma_f32_16x16x32_bf16 v[172:175], v[176:179], v[4:7], v[172:175]
	ds_read_b128 v[176:179], v42 offset:128
	v_add_u32_e32 v162, 0x23580, v39
	v_add_u32_e32 v192, 0x23580, v41
	s_waitcnt lgkmcnt(2)
	v_mfma_f32_16x16x32_bf16 v[180:183], v[180:183], v[0:3], 0
	v_add_u32_e32 v193, 0x23580, v40
	s_waitcnt lgkmcnt(1)
	v_mfma_f32_16x16x32_bf16 v[180:183], v[184:187], v[4:7], v[180:183]
	ds_read_b128 v[184:187], v42 offset:4480
	ds_read_b128 v[188:191], v42 offset:192
	s_waitcnt lgkmcnt(2)
	v_mfma_f32_16x16x32_bf16 v[172:175], v[176:179], v[8:11], v[172:175]
	ds_read_b128 v[176:179], v42 offset:4544
	s_waitcnt lgkmcnt(2)
	v_mfma_f32_16x16x32_bf16 v[180:183], v[184:187], v[8:11], v[180:183]
	ds_read_b128 v[184:187], v42 offset:17408
	s_waitcnt lgkmcnt(2)
	v_mfma_f32_16x16x32_bf16 v[172:175], v[188:191], v[12:15], v[172:175]
	s_waitcnt lgkmcnt(1)
	v_mfma_f32_16x16x32_bf16 v[176:179], v[176:179], v[12:15], v[180:183]
	s_nop 2
	ds_read_b128 v[180:183], v42 offset:17472
	ds_read_b128 v[188:191], v42 offset:21760
	ds_read_b32 v76, v76
	ds_read_b32 v77, v77
	ds_read_b32 v90, v90
	ds_read_b32 v91, v91
	ds_read_b32 v161, v161
	ds_read_b32 v162, v162
	ds_read_b32 v200, v192
	ds_read_b32 v201, v193
	ds_read_b128 v[192:195], v42 offset:21824
	s_waitcnt lgkmcnt(11)
	v_mfma_f32_16x16x32_bf16 v[184:187], v[184:187], v[0:3], 0
	ds_read_b128 v[196:199], v42 offset:17536
	s_waitcnt lgkmcnt(9)
	v_add_f32_e32 v222, v172, v76
	s_waitcnt lgkmcnt(7)
	v_add_f32_e32 v90, v173, v90
	v_mfma_f32_16x16x32_bf16 v[180:183], v[180:183], v[4:7], v[184:187]
	s_waitcnt lgkmcnt(5)
	v_add_f32_e32 v224, v174, v161
	s_waitcnt lgkmcnt(3)
	v_add_f32_e32 v225, v175, v200
	ds_read_b128 v[172:175], v42 offset:17600
	ds_read_b128 v[184:187], v42 offset:21888
	v_mfma_f32_16x16x32_bf16 v[188:191], v[188:191], v[0:3], 0
	v_add_f32_e32 v223, v176, v77
	v_add_f32_e32 v91, v177, v91
	v_add_f32_e32 v162, v178, v162
	s_waitcnt lgkmcnt(4)
	v_add_f32_e32 v226, v179, v201
	ds_read_b128 v[176:179], v42 offset:21952
	s_waitcnt lgkmcnt(4)
	v_mfma_f32_16x16x32_bf16 v[188:191], v[192:195], v[4:7], v[188:191]
	v_add_u32_e32 v42, 0x23600, v29
	v_add_u32_e32 v76, 0x23600, v35
	v_add_u32_e32 v77, 0x23600, v36
	s_waitcnt lgkmcnt(3)
	v_mfma_f32_16x16x32_bf16 v[180:183], v[196:199], v[8:11], v[180:183]
	v_add_u32_e32 v161, 0x23600, v37
	s_waitcnt lgkmcnt(1)
	v_mfma_f32_16x16x32_bf16 v[184:187], v[184:187], v[8:11], v[188:191]
	v_mfma_f32_16x16x32_bf16 v[172:175], v[172:175], v[12:15], v[180:183]
	s_nop 3
	v_add_u32_e32 v180, 0x23600, v38
	v_add_u32_e32 v181, 0x23600, v39
	v_add_u32_e32 v182, 0x23600, v41
	v_add_u32_e32 v183, 0x23600, v40
	ds_read_b32 v42, v42
	ds_read_b32 v76, v76
	ds_read_b32 v77, v77
	ds_read_b32 v161, v161
	ds_read_b32 v180, v180
	ds_read_b32 v181, v181
	ds_read_b32 v182, v182
	ds_read_b32 v183, v183
	s_waitcnt lgkmcnt(8)
	v_mfma_f32_16x16x32_bf16 v[176:179], v[176:179], v[12:15], v[184:187]
	s_waitcnt lgkmcnt(5)
	v_add_f32_e32 v229, v173, v77
	v_add_f32_e32 v227, v172, v42
	s_waitcnt lgkmcnt(1)
	v_add_f32_e32 v77, v175, v182
	v_add_f32_e32 v231, v174, v180
	s_nop 1
	v_add_f32_e32 v228, v176, v76
	s_waitcnt lgkmcnt(0)
	v_add_f32_e32 v76, v179, v183
	v_add_f32_e32 v230, v177, v161
	v_add_f32_e32 v232, v178, v181
	s_mov_b32 s8, 0x14820000
	s_waitcnt vmcnt(7)
	ds_write_b128 v160, v[44:47]
	s_waitcnt vmcnt(6)
	ds_write_b128 v160, v[48:51] offset:4352
	s_waitcnt vmcnt(5)
	ds_write_b128 v160, v[56:59] offset:8704
	s_waitcnt vmcnt(4)
	ds_write_b128 v160, v[60:63] offset:13056
	s_waitcnt vmcnt(3)
	ds_write_b128 v160, v[78:81] offset:17408
	s_waitcnt vmcnt(2)
	ds_write_b128 v160, v[82:85] offset:21760
	s_waitcnt vmcnt(1)
	ds_write_b128 v160, v[86:89] offset:26112
	s_waitcnt vmcnt(0)
	ds_write_b128 v160, v[168:171] offset:30464
	v_add_co_u32_e32 v44, vcc, s8, v16
	s_mov_b32 s8, 0x14920000
	s_nop 0
	v_addc_co_u32_e32 v45, vcc, 0, v17, vcc
	v_add_co_u32_e32 v46, vcc, s8, v16
	s_mov_b32 s8, 0x14a20000
	s_nop 0
	v_addc_co_u32_e32 v47, vcc, 0, v17, vcc
	v_add_co_u32_e32 v48, vcc, s8, v16
	s_mov_b32 s8, 0x14b20000
	s_nop 0
	v_addc_co_u32_e32 v49, vcc, 0, v17, vcc
	v_add_co_u32_e32 v50, vcc, s8, v16
	s_mov_b32 s8, 0x14c20000
	s_nop 0
	v_addc_co_u32_e32 v51, vcc, 0, v17, vcc
	v_add_co_u32_e32 v56, vcc, s8, v16
	s_mov_b32 s8, 0x14d20000
	s_nop 0
	v_addc_co_u32_e32 v57, vcc, 0, v17, vcc
	v_add_co_u32_e32 v58, vcc, s8, v16
	s_mov_b32 s8, 0x14e20000
	s_nop 0
	v_addc_co_u32_e32 v59, vcc, 0, v17, vcc
	v_add_co_u32_e32 v60, vcc, s8, v16
	s_mov_b32 s8, 0x14f20000
	s_nop 0
	v_addc_co_u32_e32 v61, vcc, 0, v17, vcc
	v_add_co_u32_e32 v62, vcc, s8, v16
	s_waitcnt lgkmcnt(0)
	s_barrier
; #define LAS __attribute__((address_space(3)))
; #define SCHED_FENCE() __builtin_amdgcn_sched_barrier(0)
; __device__ __forceinline__ float shfl_xor_l(float v, int lane, int mask) { return __int_as_float(__builtin_amdgcn_ds_bpermute((lane ^ mask) << 2, __float_as_int(v))); }
; __device__ __forceinline__ f32x4 mfma16(bf16x8 a, bf16x8 b, f32x4 c) { return __builtin_amdgcn_mfma_f32_16x16x32_bf16(a, b, c, 0, 0, 0); }
; #define A2_WRITEK(buf_) do { _Pragma("unroll") for (int j = 0; j < 8; ++j) *(LAS u32x4*)((buf_) + klo + j * (16 * 272)) = t8[j]; } while (0)
; template <bool NA> ...
;     ...
;         for (int ks = 0; ks < NSTEP; ++ks) {
;             LAS unsigned char* cur = lds + cb * ABUF2; LAS unsigned char* nxt = lds + (cb ^ 1) * ABUF2;
;             if (ks < NSTEP - 1) A2_LOADK(hp, ks + 1); else A2_LOADV(hp, 0);
;             SCHED_FENCE();
; #pragma unroll
;             for (int g = 0; g < NGRP; ++g) {
;                 const int gi = ks * NGRP + g, koff = NA ? g * 64 + w0 : g * 32;
;                 const LAS unsigned char* kp = cur + (hh * 128 + koff + fr) * 272 + fq * 16;
;                 bf16x8 kf[2][4];
; #pragma unroll
;                 for (int a = 0; a < 2; ++a)
; #pragma unroll
;                     for (int dc = 0; dc < 4; ++dc) kf[a][dc] = *(const LAS bf16x8*)(kp + a * 16 * 272 + dc * 64);
;                 f32x4 s0 = (f32x4){0.f, 0.f, 0.f, 0.f}, s1 = (f32x4){0.f, 0.f, 0.f, 0.f};
; #pragma unroll
;                 for (int dc = 0; dc < 4; ++dc) { s0 = mfma16(kf[0][dc], qf[dc], s0); s1 = mfma16(kf[1][dc], qf[dc], s1); }
;                 if (NA) { const LAS float* br = rpb + ((hp * 2 + hh) * 15 + brow0 + 2 * ks + g) * 32;
; #pragma unroll
;                     for (int e = 0; e < 4; ++e) { s0[e] += br[bidx[e]]; s1[e] += br[bidx[4 + e]]; } }
;                 sc[gi][0] = s0; sc[gi][1] = s1;
;             }
;             SCHED_FENCE();
;             if (ks < NSTEP - 1) A2_WRITEK(nxt); else A2_WRITEV(nxt);
;             __syncthreads(); cb ^= 1;
;         }
;         float mx = -3.0e38f;
; #pragma unroll
;         for (int gi = 0; gi < 8; ++gi)
; #pragma unroll
;             for (int a = 0; a < 2; ++a) mx = fmaxf(mx, fmaxf(fmaxf(sc[gi][a].x, sc[gi][a].y), fmaxf(sc[gi][a].z, sc[gi][a].w)));
;         mx = fmaxf(mx, shfl_xor_l(mx, lane, 16)); mx = fmaxf(mx, shfl_xor_l(mx, lane, 32));
	global_load_dwordx4 v[78:81], v[44:45], off
	global_load_dwordx4 v[82:85], v[46:47], off
	global_load_dwordx4 v[86:89], v[48:49], off
	global_load_dwordx4 v[168:171], v[50:51], off
	global_load_dwordx4 v[172:175], v[56:57], off
	global_load_dwordx4 v[176:179], v[58:59], off
	v_addc_co_u32_e32 v63, vcc, 0, v17, vcc
	global_load_dwordx4 v[180:183], v[60:61], off
	global_load_dwordx4 v[184:187], v[62:63], off
	ds_read_b128 v[188:191], v43
	ds_read_b128 v[192:195], v43 offset:64
	ds_read_b128 v[196:199], v43 offset:4352
	ds_read_b128 v[200:203], v43 offset:4416
	v_add_u32_e32 v16, 0x23680, v29
	v_add_u32_e32 v17, 0x23680, v35
	s_waitcnt lgkmcnt(3)
	v_mfma_f32_16x16x32_bf16 v[188:191], v[188:191], v[0:3], 0
	v_add_u32_e32 v42, 0x23680, v36
	v_add_u32_e32 v161, 0x23680, v37
	v_add_u32_e32 v208, 0x23680, v38
	s_waitcnt lgkmcnt(2)
	v_mfma_f32_16x16x32_bf16 v[188:191], v[192:195], v[4:7], v[188:191]
	ds_read_b128 v[192:195], v43 offset:128
	v_add_u32_e32 v209, 0x23680, v39
	v_add_u32_e32 v210, 0x23680, v41
	s_waitcnt lgkmcnt(2)
	v_mfma_f32_16x16x32_bf16 v[196:199], v[196:199], v[0:3], 0
	v_add_u32_e32 v211, 0x23680, v40
	v_add_u32_e32 v29, 0x23700, v29
	v_add_u32_e32 v35, 0x23700, v35
	s_waitcnt lgkmcnt(1)
	v_mfma_f32_16x16x32_bf16 v[196:199], v[200:203], v[4:7], v[196:199]
	ds_read_b128 v[200:203], v43 offset:4480
	ds_read_b128 v[204:207], v43 offset:192
	v_add_u32_e32 v41, 0x23700, v41
	v_add_u32_e32 v40, 0x23700, v40
	s_waitcnt lgkmcnt(2)
	v_mfma_f32_16x16x32_bf16 v[188:191], v[192:195], v[8:11], v[188:191]
	ds_read_b128 v[192:195], v43 offset:4544
	s_waitcnt lgkmcnt(2)
	v_mfma_f32_16x16x32_bf16 v[196:199], v[200:203], v[8:11], v[196:199]
	ds_read_b128 v[200:203], v43 offset:17408
	s_waitcnt lgkmcnt(2)
	v_mfma_f32_16x16x32_bf16 v[188:191], v[204:207], v[12:15], v[188:191]
	s_waitcnt lgkmcnt(1)
	v_mfma_f32_16x16x32_bf16 v[192:195], v[192:195], v[12:15], v[196:199]
	s_nop 2
	ds_read_b128 v[196:199], v43 offset:17472
	ds_read_b128 v[204:207], v43 offset:21760
	ds_read_b32 v16, v16
	ds_read_b32 v17, v17
	ds_read_b32 v42, v42
	ds_read_b32 v161, v161
	ds_read_b32 v233, v208
	ds_read_b32 v234, v209
	ds_read_b32 v235, v210
	ds_read_b32 v236, v211
	ds_read_b128 v[208:211], v43 offset:21824
	s_waitcnt lgkmcnt(11)
	v_mfma_f32_16x16x32_bf16 v[200:203], v[200:203], v[0:3], 0
	ds_read_b128 v[218:221], v43 offset:17536
	s_waitcnt lgkmcnt(9)
	v_add_f32_e32 v16, v188, v16
	s_waitcnt lgkmcnt(8)
	v_add_f32_e32 v17, v192, v17
	v_mfma_f32_16x16x32_bf16 v[204:207], v[204:207], v[0:3], 0
	s_waitcnt lgkmcnt(7)
	v_add_f32_e32 v237, v189, v42
	s_waitcnt lgkmcnt(6)
	v_add_f32_e32 v238, v193, v161
	s_waitcnt lgkmcnt(5)
	v_add_f32_e32 v233, v190, v233
	v_mfma_f32_16x16x32_bf16 v[196:199], v[196:199], v[4:7], v[200:203]
	v_add_u32_e32 v42, 0x23700, v36
	v_add_u32_e32 v161, 0x23700, v38
	s_nop 0
	ds_read_b128 v[200:203], v43 offset:21888
	s_waitcnt lgkmcnt(2)
	v_mfma_f32_16x16x32_bf16 v[204:207], v[208:211], v[4:7], v[204:207]
	v_add_f32_e32 v208, v194, v234
	v_add_f32_e32 v209, v191, v235
	ds_read_b128 v[188:191], v43 offset:17600
	v_add_f32_e32 v210, v195, v236
	ds_read_b128 v[192:195], v43 offset:21952
	s_waitcnt lgkmcnt(3)
	v_mfma_f32_16x16x32_bf16 v[196:199], v[218:221], v[8:11], v[196:199]
	v_add_u32_e32 v43, 0x23700, v37
	s_waitcnt lgkmcnt(2)
	v_mfma_f32_16x16x32_bf16 v[200:203], v[200:203], v[8:11], v[204:207]
	s_waitcnt lgkmcnt(1)
	v_mfma_f32_16x16x32_bf16 v[188:191], v[188:191], v[12:15], v[196:199]
	s_nop 2
	v_add_u32_e32 v196, 0x23700, v39
	s_waitcnt lgkmcnt(0)
	v_mfma_f32_16x16x32_bf16 v[36:39], v[192:195], v[12:15], v[200:203]
	ds_read_b32 v29, v29
	ds_read_b32 v35, v35
	ds_read_b32 v42, v42
	ds_read_b32 v43, v43
	ds_read_b32 v161, v161
	ds_read_b32 v192, v196
	ds_read_b32 v41, v41
	ds_read_b32 v40, v40
	s_waitcnt lgkmcnt(7)
	v_add_f32_e32 v188, v188, v29
	s_waitcnt lgkmcnt(5)
	v_add_f32_e32 v189, v189, v42
	v_add_f32_e32 v193, v36, v35
	s_waitcnt lgkmcnt(4)
	v_add_f32_e32 v194, v37, v43
	s_waitcnt lgkmcnt(3)
	v_add_f32_e32 v190, v190, v161
	s_waitcnt lgkmcnt(2)
	v_add_f32_e32 v192, v38, v192
	s_waitcnt lgkmcnt(1)
	v_add_f32_e32 v191, v191, v41
	s_waitcnt lgkmcnt(0)
	v_add_f32_e32 v195, v39, v40
	v_max_f32_e32 v29, v20, v19
	v_max_f32_e32 v35, v21, v18
	v_max3_f32 v29, v24, v25, v29
	v_max3_f32 v35, v22, v23, v35
	v_max3_f32 v29, v29, s27, v35
	v_max_f32_e32 v35, v30, v27
	v_max_f32_e32 v36, v28, v26
	v_max3_f32 v35, v34, v32, v35
	v_max3_f32 v36, v33, v31, v36
	v_max3_f32 v29, v29, v35, v36
	v_max_f32_e32 v35, v66, v67
	v_max_f32_e32 v36, v54, v55
	v_max3_f32 v35, v64, v65, v35
	v_max3_f32 v36, v52, v53, v36
	v_max3_f32 v29, v29, v35, v36
	v_max_f32_e32 v35, v71, v69
	v_max_f32_e32 v36, v70, v68
	v_max3_f32 v35, v75, v73, v35
	v_max3_f32 v36, v74, v72, v36
	v_max3_f32 v29, v29, v35, v36
	v_max_f32_e32 v35, v224, v225
	v_max_f32_e32 v36, v162, v226
	v_max3_f32 v35, v222, v90, v35
	v_max3_f32 v36, v223, v91, v36
	v_max3_f32 v29, v29, v35, v36
	v_max_f32_e32 v35, v231, v77
	v_max_f32_e32 v36, v232, v76
	v_max3_f32 v35, v227, v229, v35
	v_max3_f32 v36, v228, v230, v36
	v_max3_f32 v29, v29, v35, v36
	v_max_f32_e32 v35, v233, v209
	v_max_f32_e32 v36, v208, v210
	v_max3_f32 v35, v16, v237, v35
	v_max3_f32 v36, v17, v238, v36
	v_max3_f32 v29, v29, v35, v36
	v_max_f32_e32 v35, v190, v191
	v_max_f32_e32 v36, v192, v195
	v_max3_f32 v35, v188, v189, v35
	v_max3_f32 v36, v193, v194, v36
	v_max3_f32 v29, v29, v35, v36
	ds_bpermute_b32 v35, v156, v29
	v_add_u32_e32 v161, 0, v102
	s_waitcnt vmcnt(7)
	ds_write_b128 v161, v[78:81]
	s_waitcnt vmcnt(6)
	ds_write_b128 v161, v[82:85] offset:8704
	s_waitcnt vmcnt(5)
	ds_write_b128 v161, v[86:89] offset:17408
	s_waitcnt vmcnt(4)
	ds_write_b128 v161, v[168:171] offset:26112
	s_waitcnt vmcnt(3)
	ds_write_b128 v161, v[172:175] offset:34816
	s_waitcnt vmcnt(2)
	ds_write_b128 v161, v[176:179] offset:43520
	s_waitcnt vmcnt(1)
	ds_write_b128 v161, v[180:183] offset:52224
	s_waitcnt vmcnt(0)
	ds_write_b128 v161, v[184:187] offset:60928
	s_waitcnt lgkmcnt(8)
	v_max_f32_e32 v35, v35, v35
	v_max_f32_e32 v29, v29, v35
	ds_bpermute_b32 v35, v157, v29
	s_waitcnt lgkmcnt(0)
	s_barrier
; __device__ __forceinline__ unsigned pk2(float lo, float hi) { unsigned r; asm("v_cvt_pk_bf16_f32 %0, %1, %2" : "=v"(r) : "v"(lo), "v"(hi)); return r; }
; __device__ __forceinline__ float shfl_xor_l(float v, int lane, int mask) { return __int_as_float(__builtin_amdgcn_ds_bpermute((lane ^ mask) << 2, __float_as_int(v))); }
; __device__ __forceinline__ float fexp2(float x) { return __builtin_amdgcn_exp2f(x); }
; template <bool NA> ...
;     ...
;         mx = fmaxf(mx, shfl_xor_l(mx, lane, 16)); mx = fmaxf(mx, shfl_xor_l(mx, lane, 32));
;         float l = 0.f; bf16x8 pb[8];
; #pragma unroll
;         for (int gi = 0; gi < 8; ++gi) {
;             f32x4 p0 = sc[gi][0], p1 = sc[gi][1];
; #pragma unroll
;             for (int e = 0; e < 4; ++e) { p0[e] = fexp2(p0[e] - mx); p1[e] = fexp2(p1[e] - mx); }
;             l += ((p0.x + p0.y) + (p0.z + p0.w)) + ((p1.x + p1.y) + (p1.z + p1.w));
;             u32x4 pw; pw.x = pk2(p0.x, p0.y); pw.y = pk2(p0.z, p0.w); pw.z = pk2(p1.x, p1.y); pw.w = pk2(p1.z, p1.w);
;             pb[gi] = __builtin_bit_cast(bf16x8, pw);
;         }
;         l += shfl_xor_l(l, lane, 16); l += shfl_xor_l(l, lane, 32);
	s_cmpk_lg_i32 s13, 0x2d00
	v_max_f32_e32 v35, v35, v35
	v_max_f32_e32 v168, v29, v35
	v_sub_f32_e32 v24, v24, v168
	v_sub_f32_e32 v25, v25, v168
	v_sub_f32_e32 v20, v20, v168
	v_sub_f32_e32 v19, v19, v168
	v_exp_f32_e32 v24, v24
	v_sub_f32_e32 v22, v22, v168
	v_exp_f32_e32 v25, v25
	v_sub_f32_e32 v23, v23, v168
	v_exp_f32_e32 v20, v20
	v_sub_f32_e32 v21, v21, v168
	v_exp_f32_e32 v19, v19
	v_sub_f32_e32 v18, v18, v168
	v_exp_f32_e32 v22, v22
	v_exp_f32_e32 v23, v23
	v_exp_f32_e32 v21, v21
	v_exp_f32_e32 v18, v18
	v_add_f32_e32 v29, v24, v25
	v_add_f32_e32 v35, v20, v19
	v_add_f32_e32 v29, v29, v35
	v_add_f32_e32 v35, v22, v23
	v_add_f32_e32 v36, v21, v18
	v_cvt_pk_bf16_f32 v40, v24, v25
	v_cvt_pk_bf16_f32 v41, v20, v19
	v_cvt_pk_bf16_f32 v42, v22, v23
	v_cvt_pk_bf16_f32 v43, v21, v18
	v_sub_f32_e32 v18, v34, v168
	v_sub_f32_e32 v20, v32, v168
	v_sub_f32_e32 v22, v30, v168
	v_sub_f32_e32 v24, v27, v168
	v_exp_f32_e32 v18, v18
	v_sub_f32_e32 v19, v33, v168
	v_exp_f32_e32 v20, v20
	v_sub_f32_e32 v21, v31, v168
	v_exp_f32_e32 v22, v22
	v_sub_f32_e32 v23, v28, v168
	v_exp_f32_e32 v24, v24
	v_sub_f32_e32 v25, v26, v168
	v_exp_f32_e32 v19, v19
	v_exp_f32_e32 v21, v21
	v_exp_f32_e32 v23, v23
	v_exp_f32_e32 v25, v25
	v_add_f32_e32 v35, v35, v36
	v_add_f32_e32 v26, v18, v20
	v_add_f32_e32 v27, v22, v24
	v_cvt_pk_bf16_f32 v36, v18, v20
	v_cvt_pk_bf16_f32 v37, v22, v24
	v_sub_f32_e32 v18, v64, v168
	v_sub_f32_e32 v20, v65, v168
	v_sub_f32_e32 v22, v66, v168
	v_sub_f32_e32 v24, v67, v168
	v_add_f32_e32 v26, v26, v27
	v_add_f32_e32 v27, v19, v21
	v_add_f32_e32 v28, v23, v25
	v_cvt_pk_bf16_f32 v38, v19, v21
	v_cvt_pk_bf16_f32 v39, v23, v25
	v_exp_f32_e32 v18, v18
	v_sub_f32_e32 v19, v52, v168
	v_exp_f32_e32 v20, v20
	v_sub_f32_e32 v21, v53, v168
	v_exp_f32_e32 v22, v22
	v_sub_f32_e32 v23, v54, v168
	v_exp_f32_e32 v24, v24
	v_sub_f32_e32 v25, v55, v168
	v_exp_f32_e32 v19, v19
	v_exp_f32_e32 v21, v21
	v_exp_f32_e32 v23, v23
	v_exp_f32_e32 v25, v25
	v_add_f32_e32 v29, v29, v35
	v_add_f32_e32 v27, v27, v28
	v_add_f32_e32 v29, 0, v29
	v_add_f32_e32 v26, v26, v27
	v_add_f32_e32 v27, v18, v20
	v_add_f32_e32 v28, v22, v24
	v_add_f32_e32 v26, v26, v29
	v_add_f32_e32 v27, v27, v28
	v_add_f32_e32 v28, v19, v21
	v_add_f32_e32 v29, v23, v25
	v_cvt_pk_bf16_f32 v32, v18, v20
	v_cvt_pk_bf16_f32 v33, v22, v24
	v_cvt_pk_bf16_f32 v34, v19, v21
	v_cvt_pk_bf16_f32 v35, v23, v25
	v_sub_f32_e32 v18, v75, v168
	v_sub_f32_e32 v19, v74, v168
	v_sub_f32_e32 v20, v73, v168
	v_sub_f32_e32 v21, v72, v168
	v_sub_f32_e32 v22, v71, v168
	v_sub_f32_e32 v23, v70, v168
	v_sub_f32_e32 v24, v69, v168
	v_sub_f32_e32 v25, v68, v168
	global_load_dwordx4 v[64:67], v[44:45], off offset:256
	global_load_dwordx4 v[68:71], v[46:47], off offset:256
	global_load_dwordx4 v[72:75], v[48:49], off offset:256
	global_load_dwordx4 v[78:81], v[50:51], off offset:256
	global_load_dwordx4 v[82:85], v[56:57], off offset:256
	global_load_dwordx4 v[86:89], v[58:59], off offset:256
	global_load_dwordx4 v[170:173], v[60:61], off offset:256
	global_load_dwordx4 v[174:177], v[62:63], off offset:256
	v_exp_f32_e32 v18, v18
	v_exp_f32_e32 v20, v20
	v_exp_f32_e32 v22, v22
	v_exp_f32_e32 v24, v24
	v_exp_f32_e32 v19, v19
	v_exp_f32_e32 v21, v21
	v_exp_f32_e32 v23, v23
	v_exp_f32_e32 v25, v25
	v_add_f32_e32 v28, v28, v29
	v_add_f32_e32 v27, v27, v28
	v_add_f32_e32 v26, v27, v26
	v_add_f32_e32 v27, v18, v20
	v_add_f32_e32 v28, v22, v24
	v_add_f32_e32 v27, v27, v28
	v_add_f32_e32 v28, v19, v21
	v_add_f32_e32 v29, v23, v25
	v_add_f32_e32 v28, v28, v29
	v_add_f32_e32 v27, v27, v28
	v_cvt_pk_bf16_f32 v28, v18, v20
	v_cvt_pk_bf16_f32 v29, v22, v24
	v_sub_f32_e32 v18, v222, v168
	v_sub_f32_e32 v20, v90, v168
	v_sub_f32_e32 v22, v224, v168
	v_sub_f32_e32 v24, v225, v168
	v_cvt_pk_bf16_f32 v30, v19, v21
	v_cvt_pk_bf16_f32 v31, v23, v25
	v_exp_f32_e32 v18, v18
	v_sub_f32_e32 v19, v223, v168
	v_exp_f32_e32 v20, v20
	v_sub_f32_e32 v21, v91, v168
	v_exp_f32_e32 v22, v22
	v_sub_f32_e32 v23, v162, v168
	v_exp_f32_e32 v25, v24
	v_sub_f32_e32 v24, v226, v168
	v_add_f32_e32 v26, v27, v26
	v_exp_f32_e32 v19, v19
	v_exp_f32_e32 v21, v21
	v_exp_f32_e32 v23, v23
	v_exp_f32_e32 v27, v24
	v_add_f32_e32 v24, v18, v20
	v_add_f32_e32 v52, v22, v25
	v_add_f32_e32 v24, v24, v52
	v_add_f32_e32 v52, v19, v21
	v_add_f32_e32 v53, v23, v27
	v_add_f32_e32 v52, v52, v53
	v_add_f32_e32 v24, v24, v52
	v_add_f32_e32 v52, v24, v26
	v_cvt_pk_bf16_f32 v24, v18, v20
	v_cvt_pk_bf16_f32 v25, v22, v25
	v_sub_f32_e32 v18, v227, v168
	v_sub_f32_e32 v20, v229, v168
	v_sub_f32_e32 v22, v231, v168
	v_sub_f32_e32 v53, v77, v168
	v_cvt_pk_bf16_f32 v26, v19, v21
	v_cvt_pk_bf16_f32 v27, v23, v27
	v_exp_f32_e32 v18, v18
	v_sub_f32_e32 v19, v228, v168
	v_exp_f32_e32 v20, v20
	v_sub_f32_e32 v21, v230, v168
	v_exp_f32_e32 v22, v22
	v_sub_f32_e32 v23, v232, v168
	v_exp_f32_e32 v53, v53
	v_sub_f32_e32 v54, v76, v168
	v_exp_f32_e32 v19, v19
	v_exp_f32_e32 v21, v21
	v_exp_f32_e32 v23, v23
	v_exp_f32_e32 v55, v54
	v_add_f32_e32 v54, v18, v20
	v_add_f32_e32 v76, v22, v53
	v_add_f32_e32 v54, v54, v76
	v_add_f32_e32 v76, v19, v21
	v_add_f32_e32 v77, v23, v55
	v_add_f32_e32 v76, v76, v77
	v_add_f32_e32 v54, v54, v76
	v_add_f32_e32 v76, v54, v52
	v_cvt_pk_bf16_f32 v52, v18, v20
	v_sub_f32_e32 v20, v233, v168
	v_cvt_pk_bf16_f32 v54, v19, v21
	v_exp_f32_e32 v21, v20
	v_sub_f32_e32 v20, v208, v168
	v_cvt_pk_bf16_f32 v55, v23, v55
	v_sub_f32_e32 v16, v16, v168
	v_sub_f32_e32 v18, v237, v168
	v_exp_f32_e32 v23, v20
	v_sub_f32_e32 v20, v209, v168
	v_cvt_pk_bf16_f32 v53, v22, v53
	v_exp_f32_e32 v16, v16
	v_sub_f32_e32 v17, v17, v168
	v_exp_f32_e32 v18, v18
	v_sub_f32_e32 v19, v238, v168
	v_exp_f32_e32 v22, v20
	v_sub_f32_e32 v20, v210, v168
	v_exp_f32_e32 v17, v17
	v_exp_f32_e32 v19, v19
	v_exp_f32_e32 v77, v20
	v_add_f32_e32 v20, v16, v18
	v_add_f32_e32 v90, v21, v22
	v_add_f32_e32 v20, v20, v90
	v_add_f32_e32 v90, v17, v19
	v_add_f32_e32 v91, v23, v77
	v_add_f32_e32 v90, v90, v91
	v_add_f32_e32 v20, v20, v90
	v_cvt_pk_bf16_f32 v21, v21, v22
	v_cvt_pk_bf16_f32 v22, v17, v19
	v_sub_f32_e32 v17, v193, v168
	v_add_f32_e32 v76, v20, v76
	v_cvt_pk_bf16_f32 v20, v16, v18
	v_sub_f32_e32 v16, v188, v168
	v_exp_f32_e32 v18, v17
	v_sub_f32_e32 v17, v189, v168
	v_sub_f32_e32 v90, v190, v168
	v_sub_f32_e32 v162, v191, v168
	v_exp_f32_e32 v16, v16
	v_exp_f32_e32 v17, v17
	v_sub_f32_e32 v19, v194, v168
	v_exp_f32_e32 v90, v90
	v_sub_f32_e32 v91, v192, v168
	v_exp_f32_e32 v162, v162
	v_sub_f32_e32 v168, v195, v168
	v_exp_f32_e32 v19, v19
	v_exp_f32_e32 v91, v91
	v_exp_f32_e32 v178, v168
	v_add_f32_e32 v168, v16, v17
	v_add_f32_e32 v169, v90, v162
	v_add_f32_e32 v168, v168, v169
	v_add_f32_e32 v169, v18, v19
	v_add_f32_e32 v179, v91, v178
	v_add_f32_e32 v169, v169, v179
	v_add_f32_e32 v168, v168, v169
	v_add_f32_e32 v76, v168, v76
	ds_bpermute_b32 v168, v156, v76
	s_cselect_b64 s[8:9], -1, 0
	v_cvt_pk_bf16_f32 v23, v23, v77
	v_cvt_pk_bf16_f32 v16, v16, v17
	v_cvt_pk_bf16_f32 v17, v90, v162
	s_waitcnt lgkmcnt(0)
; #define LAS __attribute__((address_space(3)))
; #define SCHED_FENCE() __builtin_amdgcn_sched_barrier(0)
; __device__ __forceinline__ f32x4 mfma16(bf16x8 a, bf16x8 b, f32x4 c) { return __builtin_amdgcn_mfma_f32_16x16x32_bf16(a, b, c, 0, 0, 0); }
; #define A2_LOADK(hp_, s_) do { const char* _g = (const char*)(kg0 + (size_t)(s_) * kstep + (hp_) * 256); _Pragma("unroll") for (int j = 0; j < 8; ++j) t8[j] = *(const u32x4*)(_g + (size_t)j * (16 * kld * 2) + kgo); } while (0)
; #define A2_LOADV(hp_, s_) do { const char* _g = (const char*)(vg0 + (size_t)(hp_) * 256 * vld + (size_t)(s_) * vstep); _Pragma("unroll") for (int j = 0; j < 8; ++j) t8[j] = *(const u32x4*)(_g + (size_t)j * (32 * vld * 2) + vgo); } while (0)
; #define A2_WRITEK(buf_) do { _Pragma("unroll") for (int j = 0; j < 8; ++j) *(LAS u32x4*)((buf_) + klo + j * (16 * 272)) = t8[j]; } while (0)
; #define A2_WRITEV(buf_) do { _Pragma("unroll") for (int j = 0; j < 8; ++j) *(LAS u32x4*)((buf_) + vlo + j * (32 * 272)) = t8[j]; } while (0)
; template <bool NA> ...
;     ...
;         for (int vs = 0; vs < NSTEP; ++vs) {
;             LAS unsigned char* cur = lds + cb * ABUF2; LAS unsigned char* nxt = lds + (cb ^ 1) * ABUF2;
;             if (vs == NSTEP - 1 && hp < NHP - 1) {
;                 const bf16_t* qa = qbase + ((hp + 1) * 2 + hh) * 128;
; #pragma unroll
;                 for (int dc = 0; dc < 4; ++dc) qfn[dc] = *(const bf16x8*)(qa + dc * 32);
;             }
;             if (vs < NSTEP - 1) A2_LOADV(hp, vs + 1); else if (hp < NHP - 1) A2_LOADK(hp + 1, 0);
;             SCHED_FENCE();
; #pragma unroll
;             for (int g = 0; g < NGRP; ++g) {
;                 const int gi = vs * NGRP + g, voff = NA ? g * 64 + w0 : g * 32;
;                 const LAS unsigned char* vp = cur + (hh * 128 + fr) * 272 + (voff + fq * 4) * 2;
; #pragma unroll
;                 for (int d = 0; d < 8; ++d) {
;                     const u32x2 lo = *(const LAS u32x2*)(vp + d * 16 * 272), hi = *(const LAS u32x2*)(vp + d * 16 * 272 + 32);
;                     u32x4 vw; vw.x = lo.x; vw.y = lo.y; vw.z = hi.x; vw.w = hi.y;
;                     o[d] = mfma16(__builtin_bit_cast(bf16x8, vw), pb[gi], o[d]);
;                 }
;             }
;             SCHED_FENCE();
;             if (vs < NSTEP - 1) A2_WRITEV(nxt); else if (hp < NHP - 1) A2_WRITEK(nxt);
;             __syncthreads(); cb ^= 1;
	v_add_f32_e32 v168, v76, v168
	ds_bpermute_b32 v169, v157, v168
	v_cvt_pk_bf16_f32 v18, v18, v19
	v_cvt_pk_bf16_f32 v19, v91, v178
	s_cmpk_eq_i32 s13, 0x2d00
	v_add_u32_e32 v210, 0x1000, v103
	v_add_u32_e32 v211, 0x2000, v103
	v_add_u32_e32 v218, 0x3000, v103
	v_add_u32_e32 v219, 0x4000, v103
	v_add_u32_e32 v220, 0x5000, v103
	v_add_u32_e32 v221, 0x6000, v103
	v_add_u32_e32 v222, 0x7000, v103
	ds_read2_b64 v[178:181], v103 offset1:4
	ds_read2_b64 v[182:185], v210 offset0:32 offset1:36
	ds_read2_b64 v[186:189], v211 offset0:64 offset1:68
	ds_read2_b64 v[190:193], v218 offset0:96 offset1:100
	ds_read2_b64 v[194:197], v219 offset0:128 offset1:132
	ds_read2_b64 v[198:201], v220 offset0:160 offset1:164
	ds_read2_b64 v[202:205], v221 offset0:192 offset1:196
	ds_read2_b64 v[206:209], v222 offset0:224 offset1:228
	s_waitcnt lgkmcnt(7)
	v_mfma_f32_16x16x32_bf16 v[178:181], v[178:181], v[40:43], 0
	s_waitcnt lgkmcnt(6)
	v_mfma_f32_16x16x32_bf16 v[182:185], v[182:185], v[40:43], 0
	s_waitcnt lgkmcnt(5)
	v_mfma_f32_16x16x32_bf16 v[186:189], v[186:189], v[40:43], 0
	s_waitcnt lgkmcnt(4)
	v_mfma_f32_16x16x32_bf16 v[190:193], v[190:193], v[40:43], 0
	s_waitcnt lgkmcnt(3)
	v_mfma_f32_16x16x32_bf16 v[194:197], v[194:197], v[40:43], 0
	s_waitcnt lgkmcnt(2)
	v_mfma_f32_16x16x32_bf16 v[198:201], v[198:201], v[40:43], 0
	s_waitcnt lgkmcnt(1)
	v_mfma_f32_16x16x32_bf16 v[202:205], v[202:205], v[40:43], 0
	s_waitcnt lgkmcnt(0)
	v_mfma_f32_16x16x32_bf16 v[40:43], v[206:209], v[40:43], 0
	ds_read2_b64 v[206:209], v103 offset0:16 offset1:20
	s_waitcnt lgkmcnt(0)
	v_mfma_f32_16x16x32_bf16 v[178:181], v[206:209], v[36:39], v[178:181]
	ds_read2_b64 v[206:209], v210 offset0:48 offset1:52
	s_waitcnt lgkmcnt(0)
	v_mfma_f32_16x16x32_bf16 v[182:185], v[206:209], v[36:39], v[182:185]
	ds_read2_b64 v[206:209], v211 offset0:80 offset1:84
	s_waitcnt lgkmcnt(0)
	v_mfma_f32_16x16x32_bf16 v[186:189], v[206:209], v[36:39], v[186:189]
	ds_read2_b64 v[206:209], v218 offset0:112 offset1:116
	s_waitcnt lgkmcnt(0)
	v_mfma_f32_16x16x32_bf16 v[190:193], v[206:209], v[36:39], v[190:193]
	ds_read2_b64 v[206:209], v219 offset0:144 offset1:148
	s_waitcnt lgkmcnt(0)
	v_mfma_f32_16x16x32_bf16 v[194:197], v[206:209], v[36:39], v[194:197]
	ds_read2_b64 v[206:209], v220 offset0:176 offset1:180
	s_waitcnt lgkmcnt(0)
	v_mfma_f32_16x16x32_bf16 v[198:201], v[206:209], v[36:39], v[198:201]
	ds_read2_b64 v[206:209], v221 offset0:208 offset1:212
	s_waitcnt lgkmcnt(0)
	v_mfma_f32_16x16x32_bf16 v[202:205], v[206:209], v[36:39], v[202:205]
	ds_read2_b64 v[206:209], v222 offset0:240 offset1:244
	s_waitcnt lgkmcnt(0)
	v_mfma_f32_16x16x32_bf16 v[36:39], v[206:209], v[36:39], v[40:43]
	v_add_u32_e32 v162, s7, v102
	s_waitcnt vmcnt(7)
	ds_write_b128 v162, v[64:67]
	s_waitcnt vmcnt(6)
	ds_write_b128 v162, v[68:71] offset:8704
	s_waitcnt vmcnt(5)
	ds_write_b128 v162, v[72:75] offset:17408
	s_waitcnt vmcnt(4)
	ds_write_b128 v162, v[78:81] offset:26112
	s_waitcnt vmcnt(3)
	ds_write_b128 v162, v[82:85] offset:34816
	s_waitcnt vmcnt(2)
	ds_write_b128 v162, v[86:89] offset:43520
	s_waitcnt vmcnt(1)
	ds_write_b128 v162, v[170:173] offset:52224
	s_waitcnt vmcnt(0)
	ds_write_b128 v162, v[174:177] offset:60928
	s_waitcnt lgkmcnt(0)
	s_barrier
	global_load_dwordx4 v[40:43], v[44:45], off offset:512
	global_load_dwordx4 v[64:67], v[46:47], off offset:512
	global_load_dwordx4 v[68:71], v[48:49], off offset:512
	global_load_dwordx4 v[72:75], v[50:51], off offset:512
	global_load_dwordx4 v[76:79], v[56:57], off offset:512
	global_load_dwordx4 v[80:83], v[58:59], off offset:512
	global_load_dwordx4 v[84:87], v[60:61], off offset:512
	global_load_dwordx4 v[88:91], v[62:63], off offset:512
	ds_read_b64 v[170:171], v118
	ds_read_b64 v[172:173], v119
	ds_read_b64 v[174:175], v120
	ds_read_b64 v[176:177], v121
	s_waitcnt lgkmcnt(2)
	v_mfma_f32_16x16x32_bf16 v[170:173], v[170:173], v[32:35], v[178:181]
	s_nop 2
	ds_read_b64 v[178:179], v122
	ds_read_b64 v[180:181], v123
	s_waitcnt lgkmcnt(2)
	v_mfma_f32_16x16x32_bf16 v[174:177], v[174:177], v[32:35], v[182:185]
	s_nop 2
	ds_read_b64 v[182:183], v124
	ds_read_b64 v[184:185], v125
	s_waitcnt lgkmcnt(2)
	v_mfma_f32_16x16x32_bf16 v[178:181], v[178:181], v[32:35], v[186:189]
	s_nop 2
	ds_read_b64 v[186:187], v126
	ds_read_b64 v[188:189], v127
	s_waitcnt lgkmcnt(2)
	v_mfma_f32_16x16x32_bf16 v[182:185], v[182:185], v[32:35], v[190:193]
	s_nop 2
	ds_read_b64 v[190:191], v128
	ds_read_b64 v[192:193], v129
	s_waitcnt lgkmcnt(2)
	v_mfma_f32_16x16x32_bf16 v[186:189], v[186:189], v[32:35], v[194:197]
	s_nop 2
	ds_read_b64 v[194:195], v130
	ds_read_b64 v[196:197], v131
	s_waitcnt lgkmcnt(2)
	v_mfma_f32_16x16x32_bf16 v[190:193], v[190:193], v[32:35], v[198:201]
	s_nop 2
	ds_read_b64 v[198:199], v132
	ds_read_b64 v[200:201], v133
	s_waitcnt lgkmcnt(2)
	v_mfma_f32_16x16x32_bf16 v[194:197], v[194:197], v[32:35], v[202:205]
	s_waitcnt lgkmcnt(0)
	v_mfma_f32_16x16x32_bf16 v[32:35], v[198:201], v[32:35], v[36:39]
	s_nop 2
	ds_read_b64 v[240:241], v134
	ds_read_b64 v[242:243], v135
	ds_read_b64 v[244:245], v136
	ds_read_b64 v[246:247], v137
	s_waitcnt lgkmcnt(2)
	v_mfma_f32_16x16x32_bf16 v[170:173], v[240:243], v[28:31], v[170:173]
	ds_read_b64 v[240:241], v138
	ds_read_b64 v[242:243], v139
	s_waitcnt lgkmcnt(2)
	v_mfma_f32_16x16x32_bf16 v[174:177], v[244:247], v[28:31], v[174:177]
	ds_read_b64 v[244:245], v140
	ds_read_b64 v[246:247], v141
	s_waitcnt lgkmcnt(2)
	v_mfma_f32_16x16x32_bf16 v[178:181], v[240:243], v[28:31], v[178:181]
	ds_read_b64 v[240:241], v142
	ds_read_b64 v[242:243], v143
	s_waitcnt lgkmcnt(2)
	v_mfma_f32_16x16x32_bf16 v[182:185], v[244:247], v[28:31], v[182:185]
	ds_read_b64 v[244:245], v146
	ds_read_b64 v[246:247], v147
	s_waitcnt lgkmcnt(2)
	v_mfma_f32_16x16x32_bf16 v[186:189], v[240:243], v[28:31], v[186:189]
	ds_read_b64 v[240:241], v148
	ds_read_b64 v[242:243], v149
	s_waitcnt lgkmcnt(2)
	v_mfma_f32_16x16x32_bf16 v[190:193], v[244:247], v[28:31], v[190:193]
	ds_read_b64 v[244:245], v150
	ds_read_b64 v[246:247], v151
	s_waitcnt lgkmcnt(2)
	v_mfma_f32_16x16x32_bf16 v[194:197], v[240:243], v[28:31], v[194:197]
	s_waitcnt lgkmcnt(0)
	v_mfma_f32_16x16x32_bf16 v[198:201], v[244:247], v[28:31], v[32:35]
	s_waitcnt vmcnt(7)
	ds_write_b128 v161, v[40:43]
	s_waitcnt vmcnt(6)
	ds_write_b128 v161, v[64:67] offset:8704
	s_waitcnt vmcnt(5)
	ds_write_b128 v161, v[68:71] offset:17408
	s_waitcnt vmcnt(4)
	ds_write_b128 v161, v[72:75] offset:26112
	s_waitcnt vmcnt(3)
	ds_write_b128 v161, v[76:79] offset:34816
	s_waitcnt vmcnt(2)
	ds_write_b128 v161, v[80:83] offset:43520
	s_waitcnt vmcnt(1)
	ds_write_b128 v161, v[84:87] offset:52224
	s_waitcnt vmcnt(0)
	ds_write_b128 v161, v[88:91] offset:60928
	s_waitcnt lgkmcnt(0)
	s_barrier
; #define LAS __attribute__((address_space(3)))
; #define SCHED_FENCE() __builtin_amdgcn_sched_barrier(0)
; __device__ __forceinline__ f32x4 mfma16(bf16x8 a, bf16x8 b, f32x4 c) { return __builtin_amdgcn_mfma_f32_16x16x32_bf16(a, b, c, 0, 0, 0); }
; #define A2_LOADK(hp_, s_) do { const char* _g = (const char*)(kg0 + (size_t)(s_) * kstep + (hp_) * 256); _Pragma("unroll") for (int j = 0; j < 8; ++j) t8[j] = *(const u32x4*)(_g + (size_t)j * (16 * kld * 2) + kgo); } while (0)
; #define A2_LOADV(hp_, s_) do { const char* _g = (const char*)(vg0 + (size_t)(hp_) * 256 * vld + (size_t)(s_) * vstep); _Pragma("unroll") for (int j = 0; j < 8; ++j) t8[j] = *(const u32x4*)(_g + (size_t)j * (32 * vld * 2) + vgo); } while (0)
; #define A2_WRITEK(buf_) do { _Pragma("unroll") for (int j = 0; j < 8; ++j) *(LAS u32x4*)((buf_) + klo + j * (16 * 272)) = t8[j]; } while (0)
; #define A2_WRITEV(buf_) do { _Pragma("unroll") for (int j = 0; j < 8; ++j) *(LAS u32x4*)((buf_) + vlo + j * (32 * 272)) = t8[j]; } while (0)
; template <bool NA> ...
;     ...
;         for (int vs = 0; vs < NSTEP; ++vs) {
;             LAS unsigned char* cur = lds + cb * ABUF2; LAS unsigned char* nxt = lds + (cb ^ 1) * ABUF2;
;             if (vs == NSTEP - 1 && hp < NHP - 1) {
;                 const bf16_t* qa = qbase + ((hp + 1) * 2 + hh) * 128;
; #pragma unroll
;                 for (int dc = 0; dc < 4; ++dc) qfn[dc] = *(const bf16x8*)(qa + dc * 32);
;             }
;             if (vs < NSTEP - 1) A2_LOADV(hp, vs + 1); else if (hp < NHP - 1) A2_LOADK(hp + 1, 0);
;             SCHED_FENCE();
; #pragma unroll
;             for (int g = 0; g < NGRP; ++g) {
;                 const int gi = vs * NGRP + g, voff = NA ? g * 64 + w0 : g * 32;
;                 const LAS unsigned char* vp = cur + (hh * 128 + fr) * 272 + (voff + fq * 4) * 2;
; #pragma unroll
;                 for (int d = 0; d < 8; ++d) {
;                     const u32x2 lo = *(const LAS u32x2*)(vp + d * 16 * 272), hi = *(const LAS u32x2*)(vp + d * 16 * 272 + 32);
;                     u32x4 vw; vw.x = lo.x; vw.y = lo.y; vw.z = hi.x; vw.w = hi.y;
;                     o[d] = mfma16(__builtin_bit_cast(bf16x8, vw), pb[gi], o[d]);
;                 }
;             }
;             SCHED_FENCE();
;             if (vs < NSTEP - 1) A2_WRITEV(nxt); else if (hp < NHP - 1) A2_WRITEK(nxt);
;             __syncthreads(); cb ^= 1;
	global_load_dwordx4 v[32:35], v[44:45], off offset:768
	global_load_dwordx4 v[28:31], v[46:47], off offset:768
	global_load_dwordx4 v[40:43], v[48:49], off offset:768
	global_load_dwordx4 v[36:39], v[50:51], off offset:768
	s_nop 0
	global_load_dwordx4 v[48:51], v[56:57], off offset:768
	global_load_dwordx4 v[44:47], v[58:59], off offset:768
	s_nop 0
	global_load_dwordx4 v[56:59], v[60:61], off offset:768
	s_nop 0
	global_load_dwordx4 v[60:63], v[62:63], off offset:768
	ds_read2_b64 v[64:67], v103 offset1:4
	ds_read2_b64 v[80:83], v219 offset0:128 offset1:132
	ds_read2_b64 v[68:71], v210 offset0:32 offset1:36
	ds_read2_b64 v[72:75], v211 offset0:64 offset1:68
	ds_read2_b64 v[76:79], v218 offset0:96 offset1:100
	s_waitcnt lgkmcnt(4)
	v_mfma_f32_16x16x32_bf16 v[64:67], v[64:67], v[24:27], v[170:173]
	s_waitcnt lgkmcnt(3)
	v_mfma_f32_16x16x32_bf16 v[170:173], v[80:83], v[24:27], v[186:189]
	ds_read2_b64 v[80:83], v220 offset0:160 offset1:164
	s_waitcnt lgkmcnt(3)
	v_mfma_f32_16x16x32_bf16 v[68:71], v[68:71], v[24:27], v[174:177]
	s_waitcnt lgkmcnt(0)
	v_mfma_f32_16x16x32_bf16 v[174:177], v[80:83], v[24:27], v[190:193]
	ds_read2_b64 v[80:83], v221 offset0:192 offset1:196
	v_mfma_f32_16x16x32_bf16 v[72:75], v[72:75], v[24:27], v[178:181]
	s_waitcnt lgkmcnt(0)
	v_mfma_f32_16x16x32_bf16 v[178:181], v[80:83], v[24:27], v[194:197]
	ds_read2_b64 v[80:83], v222 offset0:224 offset1:228
	v_mfma_f32_16x16x32_bf16 v[76:79], v[76:79], v[24:27], v[182:185]
	s_waitcnt lgkmcnt(0)
	v_mfma_f32_16x16x32_bf16 v[24:27], v[80:83], v[24:27], v[198:201]
	ds_read2_b64 v[80:83], v103 offset0:16 offset1:20
	s_waitcnt lgkmcnt(0)
	v_mfma_f32_16x16x32_bf16 v[88:91], v[80:83], v[52:55], v[64:67]
	s_nop 2
	ds_read2_b64 v[64:67], v210 offset0:48 offset1:52
	s_waitcnt lgkmcnt(0)
	v_mfma_f32_16x16x32_bf16 v[84:87], v[64:67], v[52:55], v[68:71]
	ds_read2_b64 v[64:67], v211 offset0:80 offset1:84
	s_waitcnt lgkmcnt(0)
	v_mfma_f32_16x16x32_bf16 v[80:83], v[64:67], v[52:55], v[72:75]
	ds_read2_b64 v[64:67], v218 offset0:112 offset1:116
	s_waitcnt lgkmcnt(0)
	v_mfma_f32_16x16x32_bf16 v[76:79], v[64:67], v[52:55], v[76:79]
	ds_read2_b64 v[64:67], v219 offset0:144 offset1:148
	s_waitcnt lgkmcnt(0)
	v_mfma_f32_16x16x32_bf16 v[72:75], v[64:67], v[52:55], v[170:173]
	ds_read2_b64 v[64:67], v220 offset0:176 offset1:180
	s_nop 1
	ds_read2_b64 v[170:173], v222 offset0:240 offset1:244
	s_waitcnt lgkmcnt(1)
	v_mfma_f32_16x16x32_bf16 v[68:71], v[64:67], v[52:55], v[174:177]
	ds_read2_b64 v[64:67], v221 offset0:208 offset1:212
	s_waitcnt lgkmcnt(0)
	v_mfma_f32_16x16x32_bf16 v[64:67], v[64:67], v[52:55], v[178:181]
	v_mfma_f32_16x16x32_bf16 v[24:27], v[170:173], v[52:55], v[24:27]
	s_waitcnt vmcnt(7)
	ds_write_b128 v162, v[32:35]
	s_waitcnt vmcnt(6)
	ds_write_b128 v162, v[28:31] offset:8704
	s_waitcnt vmcnt(5)
	ds_write_b128 v162, v[40:43] offset:17408
	s_waitcnt vmcnt(4)
	ds_write_b128 v162, v[36:39] offset:26112
	s_waitcnt vmcnt(3)
	ds_write_b128 v162, v[48:51] offset:34816
	s_waitcnt vmcnt(2)
	ds_write_b128 v162, v[44:47] offset:43520
	s_waitcnt vmcnt(1)
	ds_write_b128 v162, v[56:59] offset:52224
	s_waitcnt vmcnt(0)
	ds_write_b128 v162, v[60:63] offset:60928
	s_waitcnt lgkmcnt(0)
	s_barrier
	s_cbranch_scc1 .LBB0_223
	v_lshl_add_u64 v[12:13], s[0:1], 0, v[110:111]
	global_load_dwordx4 v[0:3], v[12:13], off offset:-128
	global_load_dwordx4 v[4:7], v[12:13], off offset:-64
	global_load_dwordx4 v[8:11], v[12:13], off
	s_nop 0
	global_load_dwordx4 v[12:15], v[12:13], off offset:64

; #define LAS __attribute__((address_space(3)))
; #define SCHED_FENCE() __builtin_amdgcn_sched_barrier(0)
; __device__ __forceinline__ f32x4 mfma16(bf16x8 a, bf16x8 b, f32x4 c) { return __builtin_amdgcn_mfma_f32_16x16x32_bf16(a, b, c, 0, 0, 0); }
; #define A2_WRITEK(buf_) do { _Pragma("unroll") for (int j = 0; j < 8; ++j) *(LAS u32x4*)((buf_) + klo + j * (16 * 272)) = t8[j]; } while (0)
; #define A2_WRITEV(buf_) do { _Pragma("unroll") for (int j = 0; j < 8; ++j) *(LAS u32x4*)((buf_) + vlo + j * (32 * 272)) = t8[j]; } while (0)
; template <bool NA> ...
;     ...
;             for (int g = 0; g < NGRP; ++g) {
;                 const int gi = vs * NGRP + g, voff = NA ? g * 64 + w0 : g * 32;
;                 const LAS unsigned char* vp = cur + (hh * 128 + fr) * 272 + (voff + fq * 4) * 2;
; #pragma unroll
;                 for (int d = 0; d < 8; ++d) {
;                     const u32x2 lo = *(const LAS u32x2*)(vp + d * 16 * 272), hi = *(const LAS u32x2*)(vp + d * 16 * 272 + 32);
;                     u32x4 vw; vw.x = lo.x; vw.y = lo.y; vw.z = hi.x; vw.w = hi.y;
;                     o[d] = mfma16(__builtin_bit_cast(bf16x8, vw), pb[gi], o[d]);
;                 }
;             }
;             SCHED_FENCE();
;             if (vs < NSTEP - 1) A2_WRITEV(nxt); else if (hp < NHP - 1) A2_WRITEK(nxt);
.LBB0_225:
	ds_read_b64 v[240:241], v118
	ds_read_b64 v[242:243], v119
	ds_read_b64 v[244:245], v120
	ds_read_b64 v[246:247], v121
	s_waitcnt lgkmcnt(2)
	v_mfma_f32_16x16x32_bf16 v[52:55], v[240:243], v[20:23], v[88:91]
	ds_read_b64 v[240:241], v122
	ds_read_b64 v[242:243], v123
	s_waitcnt lgkmcnt(2)
	v_mfma_f32_16x16x32_bf16 v[84:87], v[244:247], v[20:23], v[84:87]
	ds_read_b64 v[244:245], v124
	ds_read_b64 v[246:247], v125
	s_waitcnt lgkmcnt(2)
	v_mfma_f32_16x16x32_bf16 v[80:83], v[240:243], v[20:23], v[80:83]
	ds_read_b64 v[240:241], v126
	ds_read_b64 v[242:243], v127
	s_waitcnt lgkmcnt(2)
	v_mfma_f32_16x16x32_bf16 v[76:79], v[244:247], v[20:23], v[76:79]
	ds_read_b64 v[244:245], v128
	ds_read_b64 v[246:247], v129
	s_waitcnt lgkmcnt(2)
	v_mfma_f32_16x16x32_bf16 v[72:75], v[240:243], v[20:23], v[72:75]
	ds_read_b64 v[240:241], v130
	ds_read_b64 v[242:243], v131
	s_waitcnt lgkmcnt(2)
	v_mfma_f32_16x16x32_bf16 v[88:91], v[244:247], v[20:23], v[68:71]
	ds_read_b64 v[244:245], v132
	ds_read_b64 v[246:247], v133
	s_waitcnt lgkmcnt(2)
	v_mfma_f32_16x16x32_bf16 v[170:173], v[240:243], v[20:23], v[64:67]
	s_waitcnt lgkmcnt(0)
	v_mfma_f32_16x16x32_bf16 v[174:177], v[244:247], v[20:23], v[24:27]
	ds_read_b64 v[20:21], v134
	ds_read_b64 v[22:23], v135
	s_nop 0
	ds_read_b64 v[24:25], v136
	ds_read_b64 v[26:27], v137
	s_waitcnt lgkmcnt(2)
	v_mfma_f32_16x16x32_bf16 v[20:23], v[20:23], v[16:19], v[52:55]
	s_nop 2
	ds_read_b64 v[52:53], v138
	ds_read_b64 v[54:55], v139
	ds_read_b64 v[64:65], v140
	ds_read_b64 v[66:67], v141
	ds_read_b64 v[68:69], v142
	ds_read_b64 v[70:71], v143
	s_waitcnt lgkmcnt(4)
	v_mfma_f32_16x16x32_bf16 v[52:55], v[52:55], v[16:19], v[80:83]
	s_waitcnt lgkmcnt(2)
	v_mfma_f32_16x16x32_bf16 v[64:67], v[64:67], v[16:19], v[76:79]
	s_waitcnt lgkmcnt(0)
	v_mfma_f32_16x16x32_bf16 v[68:71], v[68:71], v[16:19], v[72:75]
	s_nop 2
	ds_read_b64 v[72:73], v146
	ds_read_b64 v[74:75], v147
	ds_read_b64 v[76:77], v148
	ds_read_b64 v[78:79], v149
	ds_read_b64 v[80:81], v150
	ds_read_b64 v[82:83], v151
	v_mfma_f32_16x16x32_bf16 v[24:27], v[24:27], v[16:19], v[84:87]
	s_waitcnt lgkmcnt(4)
	v_mfma_f32_16x16x32_bf16 v[72:75], v[72:75], v[16:19], v[88:91]
	s_waitcnt lgkmcnt(2)
	v_mfma_f32_16x16x32_bf16 v[76:79], v[76:79], v[16:19], v[170:173]
	s_waitcnt lgkmcnt(0)
	v_mfma_f32_16x16x32_bf16 v[16:19], v[80:83], v[16:19], v[174:177]
	s_and_b64 vcc, exec, s[38:39]
	s_cbranch_vccnz .LBB0_220
	s_waitcnt vmcnt(7)
	ds_write_b128 v154, v[32:35]
	s_waitcnt vmcnt(6)
	ds_write_b128 v154, v[28:31] offset:4352
	s_waitcnt vmcnt(5)
	ds_write_b128 v154, v[40:43] offset:8704
	s_waitcnt vmcnt(4)
	ds_write_b128 v154, v[36:39] offset:13056
	s_waitcnt vmcnt(3)
	ds_write_b128 v154, v[48:51] offset:17408
	s_waitcnt vmcnt(2)
	ds_write_b128 v154, v[44:47] offset:21760
	s_waitcnt vmcnt(1)
	ds_write_b128 v154, v[56:59] offset:26112
	s_waitcnt vmcnt(0)
	ds_write_b128 v154, v[60:63] offset:30464
	s_branch .LBB0_220

; #define LAS __attribute__((address_space(3)))
; #define SCHED_FENCE() __builtin_amdgcn_sched_barrier(0)
; __device__ __forceinline__ f32x4 mfma16(bf16x8 a, bf16x8 b, f32x4 c) { return __builtin_amdgcn_mfma_f32_16x16x32_bf16(a, b, c, 0, 0, 0); }
; #define A2_LOADK(hp_, s_) do { const char* _g = (const char*)(kg0 + (size_t)(s_) * kstep + (hp_) * 256); _Pragma("unroll") for (int j = 0; j < 8; ++j) t8[j] = *(const u32x4*)(_g + (size_t)j * (16 * kld * 2) + kgo); } while (0)
; #define A2_LOADV(hp_, s_) do { const char* _g = (const char*)(vg0 + (size_t)(hp_) * 256 * vld + (size_t)(s_) * vstep); _Pragma("unroll") for (int j = 0; j < 8; ++j) t8[j] = *(const u32x4*)(_g + (size_t)j * (32 * vld * 2) + vgo); } while (0)
; #define A2_WRITEK(buf_) do { _Pragma("unroll") for (int j = 0; j < 8; ++j) *(LAS u32x4*)((buf_) + klo + j * (16 * 272)) = t8[j]; } while (0)
; template <bool NA> ...
;     ...
;         for (int ks = 0; ks < NSTEP; ++ks) {
;             LAS unsigned char* cur = lds + cb * ABUF2; LAS unsigned char* nxt = lds + (cb ^ 1) * ABUF2;
;             if (ks < NSTEP - 1) A2_LOADK(hp, ks + 1); else A2_LOADV(hp, 0);
;             SCHED_FENCE();
; #pragma unroll
;             for (int g = 0; g < NGRP; ++g) {
;                 const int gi = ks * NGRP + g, koff = NA ? g * 64 + w0 : g * 32;
;                 const LAS unsigned char* kp = cur + (hh * 128 + koff + fr) * 272 + fq * 16;
;                 bf16x8 kf[2][4];
; #pragma unroll
;                 for (int a = 0; a < 2; ++a)
; #pragma unroll
;                     for (int dc = 0; dc < 4; ++dc) kf[a][dc] = *(const LAS bf16x8*)(kp + a * 16 * 272 + dc * 64);
;                 f32x4 s0 = (f32x4){0.f, 0.f, 0.f, 0.f}, s1 = (f32x4){0.f, 0.f, 0.f, 0.f};
; #pragma unroll
;                 for (int dc = 0; dc < 4; ++dc) { s0 = mfma16(kf[0][dc], qf[dc], s0); s1 = mfma16(kf[1][dc], qf[dc], s1); }
;                 if (NA) { const LAS float* br = rpb + ((hp * 2 + hh) * 15 + brow0 + 2 * ks + g) * 32;
; #pragma unroll
;                     for (int e = 0; e < 4; ++e) { s0[e] += br[bidx[e]]; s1[e] += br[bidx[4 + e]]; } }
;                 sc[gi][0] = s0; sc[gi][1] = s1;
;             }
;             SCHED_FENCE();
;             if (ks < NSTEP - 1) A2_WRITEK(nxt); else A2_WRITEV(nxt);
;             __syncthreads(); cb ^= 1;
.LBB0_229:
	s_lshl_b32 s74, s10, 19
	v_lshl_add_u64 v[136:137], v[116:117], 0, s[74:75]
	s_lshl_b32 s74, s10, 9
	v_lshl_add_u64 v[16:17], v[118:119], 0, s[74:75]
	v_add_co_u32_e32 v18, vcc, 0x4000, v16
	s_xor_b64 s[6:7], s[8:9], -1
	s_nop 0
	v_addc_co_u32_e32 v19, vcc, 0, v17, vcc
	global_load_dwordx4 v[48:51], v[16:17], off
	global_load_dwordx4 v[52:55], v[18:19], off
	v_add_co_u32_e32 v18, vcc, 0x8000, v16
	s_nop 1
	v_addc_co_u32_e32 v19, vcc, 0, v17, vcc
	v_add_co_u32_e32 v20, vcc, 0xc000, v16
	s_nop 1
	v_addc_co_u32_e32 v21, vcc, 0, v17, vcc
	global_load_dwordx4 v[56:59], v[18:19], off
	global_load_dwordx4 v[60:63], v[20:21], off
	v_add_co_u32_e32 v18, vcc, 0x10000, v16
	s_nop 1
	v_addc_co_u32_e32 v19, vcc, 0, v17, vcc
	v_add_co_u32_e32 v20, vcc, 0x14000, v16
	s_nop 1
	v_addc_co_u32_e32 v21, vcc, 0, v17, vcc
	global_load_dwordx4 v[64:67], v[18:19], off
	global_load_dwordx4 v[68:71], v[20:21], off
	v_add_co_u32_e32 v18, vcc, 0x18000, v16
	s_nop 1
	v_addc_co_u32_e32 v19, vcc, 0, v17, vcc
	v_add_co_u32_e32 v16, vcc, 0x1c000, v16
	s_nop 1
	v_addc_co_u32_e32 v17, vcc, 0, v17, vcc
	global_load_dwordx4 v[72:75], v[18:19], off
	global_load_dwordx4 v[76:79], v[16:17], off
	v_add_u32_e32 v84, v155, v158
	ds_read_b128 v[16:19], v84
	ds_read_b128 v[24:27], v84 offset:64
	ds_read_b128 v[20:23], v84 offset:4352
	s_waitcnt lgkmcnt(2)
	v_mfma_f32_16x16x32_bf16 v[16:19], v[16:19], v[4:7], 0
	ds_read_b128 v[32:35], v84 offset:8768
	ds_read_b128 v[40:43], v84 offset:17472
	ds_read_b128 v[28:31], v84 offset:13056
	s_waitcnt lgkmcnt(4)
	v_mfma_f32_16x16x32_bf16 v[16:19], v[24:27], v[0:3], v[16:19]
	ds_read_b128 v[24:27], v84 offset:4416
	ds_read_b128 v[36:39], v84 offset:21760
	ds_read_b128 v[80:83], v84 offset:26176
	s_waitcnt lgkmcnt(6)
	v_mfma_f32_16x16x32_bf16 v[20:23], v[20:23], v[4:7], 0
	ds_read_b128 v[44:47], v84 offset:30464
	s_waitcnt lgkmcnt(3)
	v_mfma_f32_16x16x32_bf16 v[20:23], v[24:27], v[0:3], v[20:23]
	ds_read_b128 v[240:243], v84 offset:128
	ds_read_b128 v[244:247], v84 offset:4480
	s_waitcnt lgkmcnt(1)
	v_mfma_f32_16x16x32_bf16 v[16:19], v[240:243], v[8:11], v[16:19]
	ds_read_b128 v[240:243], v84 offset:192
	s_waitcnt lgkmcnt(1)
	v_mfma_f32_16x16x32_bf16 v[20:23], v[244:247], v[8:11], v[20:23]
	ds_read_b128 v[244:247], v84 offset:4544
	s_waitcnt lgkmcnt(1)
	v_mfma_f32_16x16x32_bf16 v[16:19], v[240:243], v[12:15], v[16:19]
	ds_read_b128 v[240:243], v84 offset:8704
	s_waitcnt lgkmcnt(1)
	v_mfma_f32_16x16x32_bf16 v[20:23], v[244:247], v[12:15], v[20:23]
	s_waitcnt lgkmcnt(0)
	v_mfma_f32_16x16x32_bf16 v[24:27], v[240:243], v[4:7], 0
	v_mfma_f32_16x16x32_bf16 v[24:27], v[32:35], v[0:3], v[24:27]
	ds_read_b128 v[32:35], v84 offset:13120
	v_mfma_f32_16x16x32_bf16 v[28:31], v[28:31], v[4:7], 0
	s_waitcnt lgkmcnt(0)
	v_mfma_f32_16x16x32_bf16 v[28:31], v[32:35], v[0:3], v[28:31]
	ds_read_b128 v[240:243], v84 offset:8832
	ds_read_b128 v[244:247], v84 offset:13184
	s_waitcnt lgkmcnt(1)
	v_mfma_f32_16x16x32_bf16 v[24:27], v[240:243], v[8:11], v[24:27]
	ds_read_b128 v[240:243], v84 offset:8896
	s_waitcnt lgkmcnt(1)
	v_mfma_f32_16x16x32_bf16 v[28:31], v[244:247], v[8:11], v[28:31]
	ds_read_b128 v[244:247], v84 offset:13248
	s_waitcnt lgkmcnt(1)
	v_mfma_f32_16x16x32_bf16 v[24:27], v[240:243], v[12:15], v[24:27]
	ds_read_b128 v[240:243], v84 offset:17408
	s_waitcnt lgkmcnt(1)
	v_mfma_f32_16x16x32_bf16 v[28:31], v[244:247], v[12:15], v[28:31]
	s_waitcnt lgkmcnt(0)
	v_mfma_f32_16x16x32_bf16 v[32:35], v[240:243], v[4:7], 0
	v_mfma_f32_16x16x32_bf16 v[32:35], v[40:43], v[0:3], v[32:35]
	ds_read_b128 v[40:43], v84 offset:21824
	v_mfma_f32_16x16x32_bf16 v[36:39], v[36:39], v[4:7], 0
	s_waitcnt lgkmcnt(0)
	v_mfma_f32_16x16x32_bf16 v[36:39], v[40:43], v[0:3], v[36:39]
	ds_read_b128 v[240:243], v84 offset:17536
	ds_read_b128 v[244:247], v84 offset:21888
	s_waitcnt lgkmcnt(1)
	v_mfma_f32_16x16x32_bf16 v[32:35], v[240:243], v[8:11], v[32:35]
	ds_read_b128 v[240:243], v84 offset:17600
	s_waitcnt lgkmcnt(1)
	v_mfma_f32_16x16x32_bf16 v[36:39], v[244:247], v[8:11], v[36:39]
	ds_read_b128 v[244:247], v84 offset:21952
	s_waitcnt lgkmcnt(1)
	v_mfma_f32_16x16x32_bf16 v[32:35], v[240:243], v[12:15], v[32:35]
	ds_read_b128 v[240:243], v84 offset:26112
	s_waitcnt lgkmcnt(1)
	v_mfma_f32_16x16x32_bf16 v[36:39], v[244:247], v[12:15], v[36:39]
	s_waitcnt lgkmcnt(0)
	v_mfma_f32_16x16x32_bf16 v[40:43], v[240:243], v[4:7], 0
	v_mfma_f32_16x16x32_bf16 v[40:43], v[80:83], v[0:3], v[40:43]
	ds_read_b128 v[80:83], v84 offset:30528
	v_mfma_f32_16x16x32_bf16 v[44:47], v[44:47], v[4:7], 0
	s_waitcnt lgkmcnt(0)
	v_mfma_f32_16x16x32_bf16 v[44:47], v[80:83], v[0:3], v[44:47]
	ds_read_b128 v[240:243], v84 offset:26240
	ds_read_b128 v[244:247], v84 offset:30592
	s_waitcnt lgkmcnt(1)
	v_mfma_f32_16x16x32_bf16 v[40:43], v[240:243], v[8:11], v[40:43]
	ds_read_b128 v[240:243], v84 offset:26304
	s_waitcnt lgkmcnt(1)
	v_mfma_f32_16x16x32_bf16 v[44:47], v[244:247], v[8:11], v[44:47]
	ds_read_b128 v[244:247], v84 offset:30656
	s_waitcnt lgkmcnt(1)
	v_mfma_f32_16x16x32_bf16 v[40:43], v[240:243], v[12:15], v[40:43]
	s_waitcnt lgkmcnt(0)
	v_mfma_f32_16x16x32_bf16 v[44:47], v[244:247], v[12:15], v[44:47]
	v_add_co_u32_e32 v138, vcc, s47, v136
	s_mov_b32 s11, 0x20000
	s_nop 0
	v_addc_co_u32_e32 v139, vcc, 0, v137, vcc
	v_add_co_u32_e32 v140, vcc, s11, v136
	s_waitcnt vmcnt(7)
	ds_write_b128 v160, v[48:51]
	s_waitcnt vmcnt(6)
	ds_write_b128 v160, v[52:55] offset:4352
	s_waitcnt vmcnt(5)
	ds_write_b128 v160, v[56:59] offset:8704
	s_waitcnt vmcnt(4)
	ds_write_b128 v160, v[60:63] offset:13056
	s_waitcnt vmcnt(3)
	ds_write_b128 v160, v[64:67] offset:17408
	s_waitcnt vmcnt(2)
	ds_write_b128 v160, v[68:71] offset:21760
	s_waitcnt vmcnt(1)
	ds_write_b128 v160, v[72:75] offset:26112
	s_waitcnt vmcnt(0)
	ds_write_b128 v160, v[76:79] offset:30464
	v_addc_co_u32_e32 v141, vcc, 0, v137, vcc
	v_add_co_u32_e32 v142, vcc, s3, v136
	s_waitcnt lgkmcnt(0)
	s_nop 0
	v_addc_co_u32_e32 v143, vcc, 0, v137, vcc
	v_add_co_u32_e32 v146, vcc, s21, v136
	s_barrier
; #define LAS __attribute__((address_space(3)))
; #define SCHED_FENCE() __builtin_amdgcn_sched_barrier(0)
; __device__ __forceinline__ f32x4 mfma16(bf16x8 a, bf16x8 b, f32x4 c) { return __builtin_amdgcn_mfma_f32_16x16x32_bf16(a, b, c, 0, 0, 0); }
; #define A2_LOADK(hp_, s_) do { const char* _g = (const char*)(kg0 + (size_t)(s_) * kstep + (hp_) * 256); _Pragma("unroll") for (int j = 0; j < 8; ++j) t8[j] = *(const u32x4*)(_g + (size_t)j * (16 * kld * 2) + kgo); } while (0)
; #define A2_LOADV(hp_, s_) do { const char* _g = (const char*)(vg0 + (size_t)(hp_) * 256 * vld + (size_t)(s_) * vstep); _Pragma("unroll") for (int j = 0; j < 8; ++j) t8[j] = *(const u32x4*)(_g + (size_t)j * (32 * vld * 2) + vgo); } while (0)
; #define A2_WRITEK(buf_) do { _Pragma("unroll") for (int j = 0; j < 8; ++j) *(LAS u32x4*)((buf_) + klo + j * (16 * 272)) = t8[j]; } while (0)
; template <bool NA> ...
;     ...
;         for (int ks = 0; ks < NSTEP; ++ks) {
;             LAS unsigned char* cur = lds + cb * ABUF2; LAS unsigned char* nxt = lds + (cb ^ 1) * ABUF2;
;             if (ks < NSTEP - 1) A2_LOADK(hp, ks + 1); else A2_LOADV(hp, 0);
;             SCHED_FENCE();
; #pragma unroll
;             for (int g = 0; g < NGRP; ++g) {
;                 const int gi = ks * NGRP + g, koff = NA ? g * 64 + w0 : g * 32;
;                 const LAS unsigned char* kp = cur + (hh * 128 + koff + fr) * 272 + fq * 16;
;                 bf16x8 kf[2][4];
; #pragma unroll
;                 for (int a = 0; a < 2; ++a)
; #pragma unroll
;                     for (int dc = 0; dc < 4; ++dc) kf[a][dc] = *(const LAS bf16x8*)(kp + a * 16 * 272 + dc * 64);
;                 f32x4 s0 = (f32x4){0.f, 0.f, 0.f, 0.f}, s1 = (f32x4){0.f, 0.f, 0.f, 0.f};
; #pragma unroll
;                 for (int dc = 0; dc < 4; ++dc) { s0 = mfma16(kf[0][dc], qf[dc], s0); s1 = mfma16(kf[1][dc], qf[dc], s1); }
;                 if (NA) { const LAS float* br = rpb + ((hp * 2 + hh) * 15 + brow0 + 2 * ks + g) * 32;
; #pragma unroll
;                     for (int e = 0; e < 4; ++e) { s0[e] += br[bidx[e]]; s1[e] += br[bidx[4 + e]]; } }
;                 sc[gi][0] = s0; sc[gi][1] = s1;
;             }
;             SCHED_FENCE();
;             if (ks < NSTEP - 1) A2_WRITEK(nxt); else A2_WRITEV(nxt);
;             __syncthreads(); cb ^= 1;
	s_nop 0
	v_addc_co_u32_e32 v147, vcc, 0, v137, vcc
	v_add_co_u32_e32 v148, vcc, s20, v136
	s_nop 1
	v_addc_co_u32_e32 v149, vcc, 0, v137, vcc
	v_add_co_u32_e32 v150, vcc, s26, v136
	global_load_dwordx4 v[100:103], v[136:137], off
	global_load_dwordx4 v[104:107], v[138:139], off
	v_addc_co_u32_e32 v151, vcc, 0, v137, vcc
	v_add_co_u32_e32 v152, vcc, s48, v136
	global_load_dwordx4 v[108:111], v[140:141], off
	global_load_dwordx4 v[64:67], v[142:143], off
	global_load_dwordx4 v[72:75], v[146:147], off
	global_load_dwordx4 v[84:87], v[148:149], off
	v_addc_co_u32_e32 v153, vcc, 0, v137, vcc
	global_load_dwordx4 v[96:99], v[150:151], off
	global_load_dwordx4 v[92:95], v[152:153], off
	v_add_u32_e32 v233, v159, v158
	ds_read_b128 v[48:51], v233
	ds_read_b128 v[56:59], v233 offset:64
	ds_read_b128 v[52:55], v233 offset:4352
	s_waitcnt lgkmcnt(2)
	v_mfma_f32_16x16x32_bf16 v[48:51], v[48:51], v[4:7], 0
	ds_read_b128 v[68:71], v233 offset:8768
	ds_read_b128 v[76:79], v233 offset:21760
	ds_read_b128 v[80:83], v233 offset:17472
	s_waitcnt lgkmcnt(4)
	v_mfma_f32_16x16x32_bf16 v[48:51], v[56:59], v[0:3], v[48:51]
	ds_read_b128 v[56:59], v233 offset:4416
	ds_read_b128 v[234:237], v233 offset:26176
	ds_read_b128 v[88:91], v233 offset:30464
	s_waitcnt lgkmcnt(6)
	v_mfma_f32_16x16x32_bf16 v[52:55], v[52:55], v[4:7], 0
	s_waitcnt lgkmcnt(2)
	v_mfma_f32_16x16x32_bf16 v[52:55], v[56:59], v[0:3], v[52:55]
	ds_read_b128 v[240:243], v233 offset:128
	ds_read_b128 v[244:247], v233 offset:4480
	s_waitcnt lgkmcnt(1)
	v_mfma_f32_16x16x32_bf16 v[48:51], v[240:243], v[8:11], v[48:51]
	ds_read_b128 v[240:243], v233 offset:192
	s_waitcnt lgkmcnt(1)
	v_mfma_f32_16x16x32_bf16 v[52:55], v[244:247], v[8:11], v[52:55]
	ds_read_b128 v[244:247], v233 offset:4544
	s_waitcnt lgkmcnt(1)
	v_mfma_f32_16x16x32_bf16 v[56:59], v[240:243], v[12:15], v[48:51]
	s_waitcnt lgkmcnt(0)
	v_mfma_f32_16x16x32_bf16 v[60:63], v[244:247], v[12:15], v[52:55]
	ds_read_b128 v[48:51], v233 offset:8704
	s_nop 1
	ds_read_b128 v[52:55], v233 offset:13056
	s_waitcnt lgkmcnt(1)
	v_mfma_f32_16x16x32_bf16 v[48:51], v[48:51], v[4:7], 0
	v_mfma_f32_16x16x32_bf16 v[48:51], v[68:71], v[0:3], v[48:51]
	ds_read_b128 v[68:71], v233 offset:13120
	s_waitcnt lgkmcnt(1)
	v_mfma_f32_16x16x32_bf16 v[52:55], v[52:55], v[4:7], 0
	s_waitcnt lgkmcnt(0)
	v_mfma_f32_16x16x32_bf16 v[52:55], v[68:71], v[0:3], v[52:55]
	ds_read_b128 v[240:243], v233 offset:8832
	ds_read_b128 v[244:247], v233 offset:13184
	s_waitcnt lgkmcnt(1)
	v_mfma_f32_16x16x32_bf16 v[48:51], v[240:243], v[8:11], v[48:51]
	ds_read_b128 v[240:243], v233 offset:8896
	s_waitcnt lgkmcnt(1)
	v_mfma_f32_16x16x32_bf16 v[52:55], v[244:247], v[8:11], v[52:55]
	ds_read_b128 v[244:247], v233 offset:13248
	s_waitcnt lgkmcnt(1)
	v_mfma_f32_16x16x32_bf16 v[48:51], v[240:243], v[12:15], v[48:51]
	ds_read_b128 v[240:243], v233 offset:17408
	s_waitcnt lgkmcnt(1)
	v_mfma_f32_16x16x32_bf16 v[52:55], v[244:247], v[12:15], v[52:55]
	s_waitcnt lgkmcnt(0)
	v_mfma_f32_16x16x32_bf16 v[68:71], v[240:243], v[4:7], 0
	v_mfma_f32_16x16x32_bf16 v[68:71], v[80:83], v[0:3], v[68:71]
	ds_read_b128 v[80:83], v233 offset:21824
	v_mfma_f32_16x16x32_bf16 v[76:79], v[76:79], v[4:7], 0
	s_waitcnt lgkmcnt(0)
	v_mfma_f32_16x16x32_bf16 v[76:79], v[80:83], v[0:3], v[76:79]
	ds_read_b128 v[240:243], v233 offset:17536
	ds_read_b128 v[244:247], v233 offset:21888
	s_waitcnt lgkmcnt(1)
	v_mfma_f32_16x16x32_bf16 v[68:71], v[240:243], v[8:11], v[68:71]
	ds_read_b128 v[240:243], v233 offset:17600
	s_waitcnt lgkmcnt(1)
	v_mfma_f32_16x16x32_bf16 v[76:79], v[244:247], v[8:11], v[76:79]
	ds_read_b128 v[244:247], v233 offset:21952
	s_waitcnt lgkmcnt(1)
	v_mfma_f32_16x16x32_bf16 v[68:71], v[240:243], v[12:15], v[68:71]
	ds_read_b128 v[240:243], v233 offset:26112
	s_waitcnt lgkmcnt(1)
	v_mfma_f32_16x16x32_bf16 v[76:79], v[244:247], v[12:15], v[76:79]
	s_waitcnt lgkmcnt(0)
	v_mfma_f32_16x16x32_bf16 v[80:83], v[240:243], v[4:7], 0
	v_mfma_f32_16x16x32_bf16 v[80:83], v[234:237], v[0:3], v[80:83]
	ds_read_b128 v[234:237], v233 offset:30528
	v_mfma_f32_16x16x32_bf16 v[88:91], v[88:91], v[4:7], 0
	s_waitcnt lgkmcnt(0)
	v_mfma_f32_16x16x32_bf16 v[88:91], v[234:237], v[0:3], v[88:91]
	ds_read_b128 v[240:243], v233 offset:26240
	ds_read_b128 v[244:247], v233 offset:30592
	s_waitcnt lgkmcnt(1)
	v_mfma_f32_16x16x32_bf16 v[80:83], v[240:243], v[8:11], v[80:83]
	ds_read_b128 v[240:243], v233 offset:26304
	s_waitcnt lgkmcnt(1)
	v_mfma_f32_16x16x32_bf16 v[88:91], v[244:247], v[8:11], v[88:91]
	s_waitcnt lgkmcnt(0)
	v_mfma_f32_16x16x32_bf16 v[80:83], v[240:243], v[12:15], v[80:83]
	ds_read_b128 v[234:237], v233 offset:30656
	s_waitcnt lgkmcnt(0)
	v_mfma_f32_16x16x32_bf16 v[88:91], v[234:237], v[12:15], v[88:91]
	s_waitcnt vmcnt(7)
	ds_write_b128 v161, v[100:103]
	s_waitcnt vmcnt(6)
	ds_write_b128 v161, v[104:107] offset:8704
	s_waitcnt vmcnt(5)
; __device__ __forceinline__ unsigned pk2(float lo, float hi) { unsigned r; asm("v_cvt_pk_bf16_f32 %0, %1, %2" : "=v"(r) : "v"(lo), "v"(hi)); return r; }
; __device__ __forceinline__ float shfl_xor_l(float v, int lane, int mask) { return __int_as_float(__builtin_amdgcn_ds_bpermute((lane ^ mask) << 2, __float_as_int(v))); }
; __device__ __forceinline__ float fexp2(float x) { return __builtin_amdgcn_exp2f(x); }
; #define A2_WRITEK(buf_) do { _Pragma("unroll") for (int j = 0; j < 8; ++j) *(LAS u32x4*)((buf_) + klo + j * (16 * 272)) = t8[j]; } while (0)
; #define A2_WRITEV(buf_) do { _Pragma("unroll") for (int j = 0; j < 8; ++j) *(LAS u32x4*)((buf_) + vlo + j * (32 * 272)) = t8[j]; } while (0)
; template <bool NA> ...
;     ...
;             if (ks < NSTEP - 1) A2_WRITEK(nxt); else A2_WRITEV(nxt);
;             __syncthreads(); cb ^= 1;
;         }
;         float mx = -3.0e38f;
; #pragma unroll
;         for (int gi = 0; gi < 8; ++gi)
; #pragma unroll
;             for (int a = 0; a < 2; ++a) mx = fmaxf(mx, fmaxf(fmaxf(sc[gi][a].x, sc[gi][a].y), fmaxf(sc[gi][a].z, sc[gi][a].w)));
;         mx = fmaxf(mx, shfl_xor_l(mx, lane, 16)); mx = fmaxf(mx, shfl_xor_l(mx, lane, 32));
;         float l = 0.f; bf16x8 pb[8];
; #pragma unroll
;         for (int gi = 0; gi < 8; ++gi) {
;             f32x4 p0 = sc[gi][0], p1 = sc[gi][1];
; #pragma unroll
;             for (int e = 0; e < 4; ++e) { p0[e] = fexp2(p0[e] - mx); p1[e] = fexp2(p1[e] - mx); }
;             l += ((p0.x + p0.y) + (p0.z + p0.w)) + ((p1.x + p1.y) + (p1.z + p1.w));
;             u32x4 pw; pw.x = pk2(p0.x, p0.y); pw.y = pk2(p0.z, p0.w); pw.z = pk2(p1.x, p1.y); pw.w = pk2(p1.z, p1.w);
;             pb[gi] = __builtin_bit_cast(bf16x8, pw);
;         }
	ds_write_b128 v161, v[108:111] offset:17408
	v_max_f32_e32 v100, v19, v19
	v_max_f32_e32 v101, v18, v18
	v_max_f32_e32 v100, v101, v100
	v_max_f32_e32 v101, v23, v23
	v_max_f32_e32 v102, v22, v22
	v_max_f32_e32 v101, v102, v101
	v_max3_f32 v100, v16, v17, v100
	v_max3_f32 v101, v20, v21, v101
	v_max3_f32 v100, v100, s27, v101
	v_max_f32_e32 v101, v27, v27
	v_max_f32_e32 v102, v26, v26
	v_max_f32_e32 v101, v102, v101
	v_max_f32_e32 v102, v31, v31
	v_max_f32_e32 v103, v30, v30
	v_max_f32_e32 v102, v103, v102
	v_max3_f32 v101, v24, v25, v101
	v_max3_f32 v102, v28, v29, v102
	v_max3_f32 v100, v100, v101, v102
	v_max_f32_e32 v101, v35, v35
	v_max_f32_e32 v102, v34, v34
	v_max_f32_e32 v101, v102, v101
	v_max_f32_e32 v102, v39, v39
	v_max_f32_e32 v103, v38, v38
	v_max_f32_e32 v102, v103, v102
	v_max3_f32 v101, v32, v33, v101
	v_max3_f32 v102, v36, v37, v102
	v_max3_f32 v100, v100, v101, v102
	v_max_f32_e32 v101, v43, v43
	v_max_f32_e32 v102, v42, v42
	v_max_f32_e32 v101, v102, v101
	v_max_f32_e32 v102, v47, v47
	v_max_f32_e32 v103, v46, v46
	v_max_f32_e32 v102, v103, v102
	v_max3_f32 v101, v40, v41, v101
	v_max3_f32 v102, v44, v45, v102
	v_max3_f32 v100, v100, v101, v102
	v_max_f32_e32 v101, v59, v59
	v_max_f32_e32 v102, v58, v58
	v_max_f32_e32 v101, v102, v101
	v_max_f32_e32 v102, v63, v63
	v_max_f32_e32 v103, v62, v62
	v_max_f32_e32 v102, v103, v102
	v_max3_f32 v101, v56, v57, v101
	v_max3_f32 v102, v60, v61, v102
	v_max3_f32 v100, v100, v101, v102
	v_max_f32_e32 v101, v51, v51
	v_max_f32_e32 v102, v50, v50
	v_max_f32_e32 v101, v102, v101
	v_max_f32_e32 v102, v55, v55
	v_max_f32_e32 v103, v54, v54
	v_max_f32_e32 v102, v103, v102
	v_max3_f32 v101, v48, v49, v101
	v_max3_f32 v102, v52, v53, v102
	v_max3_f32 v100, v100, v101, v102
	v_max_f32_e32 v101, v71, v71
	v_max_f32_e32 v102, v70, v70
	v_max_f32_e32 v101, v102, v101
	v_max_f32_e32 v102, v79, v79
	v_max_f32_e32 v103, v78, v78
	v_max_f32_e32 v102, v103, v102
	v_max3_f32 v101, v68, v69, v101
	v_max3_f32 v102, v76, v77, v102
	v_max3_f32 v100, v100, v101, v102
	v_max_f32_e32 v101, v83, v83
	v_max_f32_e32 v102, v82, v82
	v_max_f32_e32 v101, v102, v101
	v_max_f32_e32 v102, v91, v91
	v_max_f32_e32 v103, v90, v90
	v_max_f32_e32 v102, v103, v102
	v_max3_f32 v101, v80, v81, v101
	v_max3_f32 v102, v88, v89, v102
	v_max3_f32 v100, v100, v101, v102
	ds_bpermute_b32 v101, v156, v100
	s_waitcnt vmcnt(4)
	ds_write_b128 v161, v[64:67] offset:26112
	s_waitcnt vmcnt(3)
	ds_write_b128 v161, v[72:75] offset:34816
	s_waitcnt vmcnt(2)
	ds_write_b128 v161, v[84:87] offset:43520
	s_waitcnt vmcnt(1)
	ds_write_b128 v161, v[96:99] offset:52224
	s_waitcnt vmcnt(0)
	ds_write_b128 v161, v[92:95] offset:60928
	s_waitcnt lgkmcnt(0)
	s_barrier
	v_max_f32_e32 v64, v101, v101
	v_max_f32_e32 v64, v100, v64
	ds_bpermute_b32 v65, v157, v64
	s_waitcnt lgkmcnt(0)
	v_max_f32_e32 v65, v65, v65
	v_max_f32_e32 v96, v64, v65
	v_sub_f32_e32 v16, v16, v96
	v_sub_f32_e32 v17, v17, v96
	v_sub_f32_e32 v18, v18, v96
	v_sub_f32_e32 v19, v19, v96
	v_exp_f32_e32 v16, v16
	v_sub_f32_e32 v20, v20, v96
	v_exp_f32_e32 v17, v17
	v_sub_f32_e32 v21, v21, v96
	v_exp_f32_e32 v18, v18
	v_sub_f32_e32 v22, v22, v96
	v_exp_f32_e32 v19, v19
	v_sub_f32_e32 v23, v23, v96
	v_exp_f32_e32 v20, v20
	v_exp_f32_e32 v21, v21
	v_exp_f32_e32 v22, v22
	v_exp_f32_e32 v23, v23
	v_add_f32_e32 v64, v16, v17
	v_add_f32_e32 v65, v18, v19
	v_add_f32_e32 v64, v64, v65
	v_add_f32_e32 v65, v20, v21
	v_add_f32_e32 v66, v22, v23
	v_cvt_pk_bf16_f32 v92, v16, v17
	v_cvt_pk_bf16_f32 v93, v18, v19
	v_cvt_pk_bf16_f32 v94, v20, v21
	v_cvt_pk_bf16_f32 v95, v22, v23
	v_sub_f32_e32 v16, v24, v96
	v_sub_f32_e32 v18, v25, v96
	v_sub_f32_e32 v20, v26, v96
	v_sub_f32_e32 v22, v27, v96
	v_exp_f32_e32 v16, v16
	v_sub_f32_e32 v17, v28, v96
	v_exp_f32_e32 v18, v18
	v_sub_f32_e32 v19, v29, v96
	v_exp_f32_e32 v20, v20
	v_sub_f32_e32 v21, v30, v96
	v_exp_f32_e32 v22, v22
	v_sub_f32_e32 v23, v31, v96
	v_exp_f32_e32 v17, v17
	v_exp_f32_e32 v19, v19
	v_exp_f32_e32 v21, v21
	v_exp_f32_e32 v23, v23
	v_add_f32_e32 v24, v16, v18
	v_add_f32_e32 v25, v20, v22
	v_cvt_pk_bf16_f32 v84, v16, v18
	v_cvt_pk_bf16_f32 v85, v20, v22
	v_sub_f32_e32 v16, v32, v96
	v_sub_f32_e32 v18, v33, v96
	v_sub_f32_e32 v20, v34, v96
	v_sub_f32_e32 v22, v35, v96
	v_add_f32_e32 v24, v24, v25
	v_add_f32_e32 v25, v17, v19
	v_add_f32_e32 v26, v21, v23
	v_cvt_pk_bf16_f32 v86, v17, v19
	v_cvt_pk_bf16_f32 v87, v21, v23
	v_exp_f32_e32 v16, v16
	v_sub_f32_e32 v17, v36, v96
	v_exp_f32_e32 v18, v18
	v_sub_f32_e32 v19, v37, v96
	v_exp_f32_e32 v20, v20
	v_sub_f32_e32 v21, v38, v96
	v_exp_f32_e32 v22, v22
	v_sub_f32_e32 v23, v39, v96
	v_exp_f32_e32 v17, v17
	v_exp_f32_e32 v19, v19
	v_exp_f32_e32 v21, v21
	v_exp_f32_e32 v23, v23
	v_add_f32_e32 v25, v25, v26
	v_add_f32_e32 v24, v24, v25
	v_add_f32_e32 v25, v16, v18
	v_add_f32_e32 v26, v20, v22
	v_cvt_pk_bf16_f32 v72, v16, v18
	v_cvt_pk_bf16_f32 v73, v20, v22
	v_sub_f32_e32 v16, v40, v96
	v_sub_f32_e32 v18, v41, v96
	v_sub_f32_e32 v20, v42, v96
	v_sub_f32_e32 v22, v43, v96
	v_add_f32_e32 v65, v65, v66
	v_add_f32_e32 v25, v25, v26
	v_add_f32_e32 v26, v17, v19
	v_add_f32_e32 v27, v21, v23
	v_cvt_pk_bf16_f32 v74, v17, v19
	v_cvt_pk_bf16_f32 v75, v21, v23
	v_exp_f32_e32 v16, v16
	v_sub_f32_e32 v17, v44, v96
	v_exp_f32_e32 v18, v18
	v_sub_f32_e32 v19, v45, v96
	v_exp_f32_e32 v20, v20
	v_sub_f32_e32 v21, v46, v96
	v_exp_f32_e32 v22, v22
	v_sub_f32_e32 v23, v47, v96
	v_add_f32_e32 v64, v64, v65
	v_exp_f32_e32 v17, v17
	v_exp_f32_e32 v19, v19
	v_exp_f32_e32 v21, v21
	v_exp_f32_e32 v23, v23
	v_add_f32_e32 v64, 0, v64
	v_add_f32_e32 v26, v26, v27
	v_add_f32_e32 v24, v24, v64
	v_add_f32_e32 v25, v25, v26
; #define LAS __attribute__((address_space(3)))
; #define SCHED_FENCE() __builtin_amdgcn_sched_barrier(0)
; __device__ __forceinline__ unsigned pk2(float lo, float hi) { unsigned r; asm("v_cvt_pk_bf16_f32 %0, %1, %2" : "=v"(r) : "v"(lo), "v"(hi)); return r; }
; __device__ __forceinline__ float shfl_xor_l(float v, int lane, int mask) { return __int_as_float(__builtin_amdgcn_ds_bpermute((lane ^ mask) << 2, __float_as_int(v))); }
; __device__ __forceinline__ float fexp2(float x) { return __builtin_amdgcn_exp2f(x); }
; template <bool NA> ...
;     ...
; #pragma unroll
;         for (int gi = 0; gi < 8; ++gi) {
;             f32x4 p0 = sc[gi][0], p1 = sc[gi][1];
; #pragma unroll
;             for (int e = 0; e < 4; ++e) { p0[e] = fexp2(p0[e] - mx); p1[e] = fexp2(p1[e] - mx); }
;             l += ((p0.x + p0.y) + (p0.z + p0.w)) + ((p1.x + p1.y) + (p1.z + p1.w));
;             u32x4 pw; pw.x = pk2(p0.x, p0.y); pw.y = pk2(p0.z, p0.w); pw.z = pk2(p1.x, p1.y); pw.w = pk2(p1.z, p1.w);
;             pb[gi] = __builtin_bit_cast(bf16x8, pw);
;         }
;         l += shfl_xor_l(l, lane, 16); l += shfl_xor_l(l, lane, 32);
;         f32x4 o[8];
; #pragma unroll
;         for (int d = 0; d < 8; ++d) o[d] = (f32x4){0.f, 0.f, 0.f, 0.f};
; #pragma unroll
;         for (int vs = 0; vs < NSTEP; ++vs) {
;             LAS unsigned char* cur = lds + cb * ABUF2; LAS unsigned char* nxt = lds + (cb ^ 1) * ABUF2;
;             if (vs == NSTEP - 1 && hp < NHP - 1) {
;                 const bf16_t* qa = qbase + ((hp + 1) * 2 + hh) * 128;
; #pragma unroll
;                 for (int dc = 0; dc < 4; ++dc) qfn[dc] = *(const bf16x8*)(qa + dc * 32);
;             }
;             if (vs < NSTEP - 1) A2_LOADV(hp, vs + 1); else if (hp < NHP - 1) A2_LOADK(hp + 1, 0);
;             SCHED_FENCE();
; #pragma unroll
;             for (int g = 0; g < NGRP; ++g) {
;                 const int gi = vs * NGRP + g, voff = NA ? g * 64 + w0 : g * 32;
;                 const LAS unsigned char* vp = cur + (hh * 128 + fr) * 272 + (voff + fq * 4) * 2;
; #pragma unroll
;                 for (int d = 0; d < 8; ++d) {
;                     const u32x2 lo = *(const LAS u32x2*)(vp + d * 16 * 272), hi = *(const LAS u32x2*)(vp + d * 16 * 272 + 32);
	v_add_f32_e32 v24, v25, v24
	v_add_f32_e32 v25, v16, v18
	v_add_f32_e32 v26, v20, v22
	v_cvt_pk_bf16_f32 v64, v16, v18
	v_cvt_pk_bf16_f32 v65, v20, v22
	v_sub_f32_e32 v16, v56, v96
	v_sub_f32_e32 v18, v57, v96
	v_sub_f32_e32 v20, v58, v96
	v_sub_f32_e32 v22, v59, v96
	v_add_f32_e32 v25, v25, v26
	v_add_f32_e32 v26, v17, v19
	v_add_f32_e32 v27, v21, v23
	v_cvt_pk_bf16_f32 v66, v17, v19
	v_cvt_pk_bf16_f32 v67, v21, v23
	v_exp_f32_e32 v16, v16
	v_sub_f32_e32 v17, v60, v96
	v_exp_f32_e32 v18, v18
	v_sub_f32_e32 v19, v61, v96
	v_exp_f32_e32 v20, v20
	v_sub_f32_e32 v21, v62, v96
	v_exp_f32_e32 v22, v22
	v_sub_f32_e32 v23, v63, v96
	v_exp_f32_e32 v17, v17
	v_exp_f32_e32 v19, v19
	v_exp_f32_e32 v21, v21
	v_exp_f32_e32 v23, v23
	v_add_f32_e32 v26, v26, v27
	v_add_f32_e32 v25, v25, v26
	v_add_f32_e32 v24, v25, v24
	v_add_f32_e32 v25, v16, v18
	v_add_f32_e32 v26, v20, v22
	v_cvt_pk_bf16_f32 v56, v16, v18
	v_sub_f32_e32 v16, v48, v96
	v_add_f32_e32 v25, v25, v26
	v_add_f32_e32 v26, v17, v19
	v_add_f32_e32 v27, v21, v23
	v_exp_f32_e32 v48, v16
	v_sub_f32_e32 v16, v52, v96
	v_add_f32_e32 v26, v26, v27
	v_exp_f32_e32 v52, v16
	v_sub_f32_e32 v16, v49, v96
	v_add_f32_e32 v25, v25, v26
	v_exp_f32_e32 v49, v16
	v_sub_f32_e32 v16, v53, v96
	v_add_f32_e32 v60, v25, v24
	v_cvt_pk_bf16_f32 v57, v20, v22
	v_cvt_pk_bf16_f32 v58, v17, v19
	v_cvt_pk_bf16_f32 v59, v21, v23
	v_exp_f32_e32 v53, v16
	global_load_dwordx4 v[44:47], v[136:137], off offset:256
	global_load_dwordx4 v[40:43], v[138:139], off offset:256
	global_load_dwordx4 v[36:39], v[140:141], off offset:256
	global_load_dwordx4 v[32:35], v[142:143], off offset:256
	global_load_dwordx4 v[28:31], v[146:147], off offset:256
	global_load_dwordx4 v[24:27], v[148:149], off offset:256
	global_load_dwordx4 v[16:19], v[150:151], off offset:256
	global_load_dwordx4 v[20:23], v[152:153], off offset:256
	v_sub_f32_e32 v50, v50, v96
	v_sub_f32_e32 v51, v51, v96
	v_exp_f32_e32 v50, v50
	v_sub_f32_e32 v54, v54, v96
	v_exp_f32_e32 v51, v51
	v_sub_f32_e32 v55, v55, v96
	v_exp_f32_e32 v54, v54
	v_exp_f32_e32 v55, v55
	v_add_f32_e32 v61, v48, v49
	v_add_f32_e32 v62, v50, v51
	v_add_f32_e32 v61, v61, v62
	v_add_f32_e32 v62, v52, v53
	v_add_f32_e32 v63, v54, v55
	v_add_f32_e32 v62, v62, v63
	v_add_f32_e32 v61, v61, v62
	v_cvt_pk_bf16_f32 v62, v52, v53
	v_sub_f32_e32 v52, v70, v96
	v_exp_f32_e32 v53, v52
	v_sub_f32_e32 v52, v78, v96
	v_add_f32_e32 v97, v61, v60
	v_cvt_pk_bf16_f32 v60, v48, v49
	v_cvt_pk_bf16_f32 v61, v50, v51
	v_cvt_pk_bf16_f32 v63, v54, v55
	v_sub_f32_e32 v48, v68, v96
	v_sub_f32_e32 v50, v69, v96
	v_exp_f32_e32 v55, v52
	v_sub_f32_e32 v52, v71, v96
	v_exp_f32_e32 v48, v48
	v_sub_f32_e32 v49, v76, v96
	v_exp_f32_e32 v50, v50
	v_sub_f32_e32 v51, v77, v96
	v_exp_f32_e32 v54, v52
	v_sub_f32_e32 v52, v79, v96
	v_exp_f32_e32 v49, v49
	v_exp_f32_e32 v51, v51
	v_exp_f32_e32 v68, v52
	v_add_f32_e32 v52, v48, v50
	v_add_f32_e32 v69, v53, v54
	v_add_f32_e32 v52, v52, v69
	v_add_f32_e32 v69, v49, v51
	v_add_f32_e32 v70, v55, v68
	v_add_f32_e32 v69, v69, v70
	v_add_f32_e32 v52, v52, v69
	v_sub_f32_e32 v69, v80, v96
	v_sub_f32_e32 v71, v81, v96
	v_sub_f32_e32 v77, v82, v96
	v_sub_f32_e32 v79, v83, v96
	v_exp_f32_e32 v69, v69
	v_sub_f32_e32 v70, v88, v96
	v_exp_f32_e32 v71, v71
	v_sub_f32_e32 v76, v89, v96
	v_exp_f32_e32 v77, v77
	v_sub_f32_e32 v78, v90, v96
	v_exp_f32_e32 v79, v79
	v_sub_f32_e32 v80, v91, v96
	v_exp_f32_e32 v70, v70
	v_exp_f32_e32 v76, v76
	v_exp_f32_e32 v78, v78
	v_exp_f32_e32 v80, v80
	v_add_f32_e32 v81, v69, v71
	v_add_f32_e32 v82, v77, v79
	v_add_f32_e32 v81, v81, v82
	v_add_f32_e32 v82, v70, v76
	v_add_f32_e32 v83, v78, v80
	v_add_f32_e32 v82, v82, v83
	v_add_f32_e32 v52, v52, v97
	v_add_f32_e32 v81, v81, v82
	v_add_f32_e32 v81, v81, v52
	ds_bpermute_b32 v82, v156, v81
	v_cvt_pk_bf16_f32 v52, v48, v50
	v_cvt_pk_bf16_f32 v53, v53, v54
	v_cvt_pk_bf16_f32 v54, v49, v51
	v_cvt_pk_bf16_f32 v55, v55, v68
	s_waitcnt lgkmcnt(0)
	v_add_f32_e32 v96, v81, v82
	ds_bpermute_b32 v97, v157, v96
	v_cvt_pk_bf16_f32 v48, v69, v71
	v_cvt_pk_bf16_f32 v49, v77, v79
	v_cvt_pk_bf16_f32 v50, v70, v76
	v_cvt_pk_bf16_f32 v51, v78, v80
	v_add_u32_e32 v110, 0x1000, v144
	v_add_u32_e32 v111, 0x2000, v144
	v_add_u32_e32 v146, 0x3000, v144
	v_add_u32_e32 v147, 0x4000, v144
	v_add_u32_e32 v148, 0x5000, v144
	v_add_u32_e32 v149, 0x6000, v144
	v_add_u32_e32 v150, 0x7000, v144
	ds_read2_b64 v[68:71], v144 offset1:4
	ds_read2_b64 v[76:79], v110 offset0:32 offset1:36
	ds_read2_b64 v[80:83], v111 offset0:64 offset1:68
	ds_read2_b64 v[88:91], v146 offset0:96 offset1:100
	ds_read2_b64 v[98:101], v147 offset0:128 offset1:132
	ds_read2_b64 v[102:105], v148 offset0:160 offset1:164
	ds_read2_b64 v[106:109], v149 offset0:192 offset1:196
	ds_read2_b64 v[136:139], v150 offset0:224 offset1:228
	s_waitcnt lgkmcnt(7)
; #define LAS __attribute__((address_space(3)))
; #define SCHED_FENCE() __builtin_amdgcn_sched_barrier(0)
; __device__ __forceinline__ f32x4 mfma16(bf16x8 a, bf16x8 b, f32x4 c) { return __builtin_amdgcn_mfma_f32_16x16x32_bf16(a, b, c, 0, 0, 0); }
; #define A2_LOADK(hp_, s_) do { const char* _g = (const char*)(kg0 + (size_t)(s_) * kstep + (hp_) * 256); _Pragma("unroll") for (int j = 0; j < 8; ++j) t8[j] = *(const u32x4*)(_g + (size_t)j * (16 * kld * 2) + kgo); } while (0)
; #define A2_LOADV(hp_, s_) do { const char* _g = (const char*)(vg0 + (size_t)(hp_) * 256 * vld + (size_t)(s_) * vstep); _Pragma("unroll") for (int j = 0; j < 8; ++j) t8[j] = *(const u32x4*)(_g + (size_t)j * (32 * vld * 2) + vgo); } while (0)
; #define A2_WRITEK(buf_) do { _Pragma("unroll") for (int j = 0; j < 8; ++j) *(LAS u32x4*)((buf_) + klo + j * (16 * 272)) = t8[j]; } while (0)
; #define A2_WRITEV(buf_) do { _Pragma("unroll") for (int j = 0; j < 8; ++j) *(LAS u32x4*)((buf_) + vlo + j * (32 * 272)) = t8[j]; } while (0)
; template <bool NA> ...
;     ...
;         for (int vs = 0; vs < NSTEP; ++vs) {
;             LAS unsigned char* cur = lds + cb * ABUF2; LAS unsigned char* nxt = lds + (cb ^ 1) * ABUF2;
;             if (vs == NSTEP - 1 && hp < NHP - 1) {
;                 const bf16_t* qa = qbase + ((hp + 1) * 2 + hh) * 128;
; #pragma unroll
;                 for (int dc = 0; dc < 4; ++dc) qfn[dc] = *(const bf16x8*)(qa + dc * 32);
;             }
;             if (vs < NSTEP - 1) A2_LOADV(hp, vs + 1); else if (hp < NHP - 1) A2_LOADK(hp + 1, 0);
;             SCHED_FENCE();
; #pragma unroll
;             for (int g = 0; g < NGRP; ++g) {
;                 const int gi = vs * NGRP + g, voff = NA ? g * 64 + w0 : g * 32;
;                 const LAS unsigned char* vp = cur + (hh * 128 + fr) * 272 + (voff + fq * 4) * 2;
; #pragma unroll
;                 for (int d = 0; d < 8; ++d) {
;                     const u32x2 lo = *(const LAS u32x2*)(vp + d * 16 * 272), hi = *(const LAS u32x2*)(vp + d * 16 * 272 + 32);
;                     u32x4 vw; vw.x = lo.x; vw.y = lo.y; vw.z = hi.x; vw.w = hi.y;
;                     o[d] = mfma16(__builtin_bit_cast(bf16x8, vw), pb[gi], o[d]);
;                 }
;             }
;             SCHED_FENCE();
;             if (vs < NSTEP - 1) A2_WRITEV(nxt); else if (hp < NHP - 1) A2_WRITEK(nxt);
;             __syncthreads(); cb ^= 1;
	v_mfma_f32_16x16x32_bf16 v[68:71], v[68:71], v[92:95], 0
	s_waitcnt lgkmcnt(6)
	v_mfma_f32_16x16x32_bf16 v[76:79], v[76:79], v[92:95], 0
	s_waitcnt lgkmcnt(5)
	v_mfma_f32_16x16x32_bf16 v[80:83], v[80:83], v[92:95], 0
	s_waitcnt lgkmcnt(4)
	v_mfma_f32_16x16x32_bf16 v[88:91], v[88:91], v[92:95], 0
	s_waitcnt lgkmcnt(3)
	v_mfma_f32_16x16x32_bf16 v[98:101], v[98:101], v[92:95], 0
	s_waitcnt lgkmcnt(2)
	v_mfma_f32_16x16x32_bf16 v[102:105], v[102:105], v[92:95], 0
	s_waitcnt lgkmcnt(1)
	v_mfma_f32_16x16x32_bf16 v[106:109], v[106:109], v[92:95], 0
	s_waitcnt lgkmcnt(0)
	v_mfma_f32_16x16x32_bf16 v[92:95], v[136:139], v[92:95], 0
	ds_read2_b64 v[136:139], v144 offset0:8 offset1:12
	s_waitcnt lgkmcnt(0)
	v_mfma_f32_16x16x32_bf16 v[68:71], v[136:139], v[84:87], v[68:71]
	ds_read2_b64 v[136:139], v110 offset0:40 offset1:44
	s_waitcnt lgkmcnt(0)
	v_mfma_f32_16x16x32_bf16 v[76:79], v[136:139], v[84:87], v[76:79]
	ds_read2_b64 v[136:139], v111 offset0:72 offset1:76
	s_waitcnt lgkmcnt(0)
	v_mfma_f32_16x16x32_bf16 v[80:83], v[136:139], v[84:87], v[80:83]
	ds_read2_b64 v[136:139], v146 offset0:104 offset1:108
	s_waitcnt lgkmcnt(0)
	v_mfma_f32_16x16x32_bf16 v[88:91], v[136:139], v[84:87], v[88:91]
	ds_read2_b64 v[136:139], v147 offset0:136 offset1:140
	s_waitcnt lgkmcnt(0)
	v_mfma_f32_16x16x32_bf16 v[98:101], v[136:139], v[84:87], v[98:101]
	ds_read2_b64 v[136:139], v148 offset0:168 offset1:172
	s_waitcnt lgkmcnt(0)
	v_mfma_f32_16x16x32_bf16 v[102:105], v[136:139], v[84:87], v[102:105]
	ds_read2_b64 v[136:139], v149 offset0:200 offset1:204
	s_waitcnt lgkmcnt(0)
	v_mfma_f32_16x16x32_bf16 v[106:109], v[136:139], v[84:87], v[106:109]
	ds_read2_b64 v[136:139], v150 offset0:232 offset1:236
	s_waitcnt lgkmcnt(0)
	v_mfma_f32_16x16x32_bf16 v[84:87], v[136:139], v[84:87], v[92:95]
	s_nop 2
	ds_read2_b64 v[92:95], v144 offset0:16 offset1:20
	s_waitcnt lgkmcnt(0)
	v_mfma_f32_16x16x32_bf16 v[68:71], v[92:95], v[72:75], v[68:71]
	ds_read2_b64 v[92:95], v110 offset0:48 offset1:52
	s_waitcnt lgkmcnt(0)
	v_mfma_f32_16x16x32_bf16 v[76:79], v[92:95], v[72:75], v[76:79]
	ds_read2_b64 v[92:95], v111 offset0:80 offset1:84
	s_waitcnt lgkmcnt(0)
	v_mfma_f32_16x16x32_bf16 v[80:83], v[92:95], v[72:75], v[80:83]
	ds_read2_b64 v[92:95], v146 offset0:112 offset1:116
	s_waitcnt lgkmcnt(0)
	v_mfma_f32_16x16x32_bf16 v[136:139], v[92:95], v[72:75], v[88:91]
	s_nop 2
	ds_read2_b64 v[88:91], v147 offset0:144 offset1:148
	s_waitcnt lgkmcnt(0)
	v_mfma_f32_16x16x32_bf16 v[98:101], v[88:91], v[72:75], v[98:101]
	ds_read2_b64 v[88:91], v148 offset0:176 offset1:180
	s_waitcnt lgkmcnt(0)
	v_mfma_f32_16x16x32_bf16 v[102:105], v[88:91], v[72:75], v[102:105]
	ds_read2_b64 v[88:91], v149 offset0:208 offset1:212
	s_waitcnt lgkmcnt(0)
	v_mfma_f32_16x16x32_bf16 v[106:109], v[88:91], v[72:75], v[106:109]
	ds_read2_b64 v[88:91], v150 offset0:240 offset1:244
	s_waitcnt lgkmcnt(0)
	v_mfma_f32_16x16x32_bf16 v[140:143], v[88:91], v[72:75], v[84:87]
	ds_read2_b64 v[72:75], v144 offset0:24 offset1:28
	s_waitcnt lgkmcnt(0)
	v_mfma_f32_16x16x32_bf16 v[92:95], v[72:75], v[64:67], v[68:71]
	s_nop 2
	ds_read2_b64 v[68:71], v110 offset0:56 offset1:60
	s_waitcnt lgkmcnt(0)
	v_mfma_f32_16x16x32_bf16 v[88:91], v[68:71], v[64:67], v[76:79]
	ds_read2_b64 v[68:71], v111 offset0:88 offset1:92
	s_waitcnt lgkmcnt(0)
	v_mfma_f32_16x16x32_bf16 v[84:87], v[68:71], v[64:67], v[80:83]
	ds_read2_b64 v[68:71], v146 offset0:120 offset1:124
	s_waitcnt lgkmcnt(0)
	v_mfma_f32_16x16x32_bf16 v[80:83], v[68:71], v[64:67], v[136:139]
	ds_read2_b64 v[68:71], v147 offset0:152 offset1:156
	s_waitcnt lgkmcnt(0)
	v_mfma_f32_16x16x32_bf16 v[76:79], v[68:71], v[64:67], v[98:101]
	ds_read2_b64 v[68:71], v148 offset0:184 offset1:188
	s_nop 1
	ds_read2_b64 v[98:101], v150 offset0:248 offset1:252
	s_waitcnt lgkmcnt(1)
	v_mfma_f32_16x16x32_bf16 v[72:75], v[68:71], v[64:67], v[102:105]
	ds_read2_b64 v[68:71], v149 offset0:216 offset1:220
	s_waitcnt lgkmcnt(0)
	v_mfma_f32_16x16x32_bf16 v[68:71], v[68:71], v[64:67], v[106:109]
	v_mfma_f32_16x16x32_bf16 v[64:67], v[98:101], v[64:67], v[140:143]
	s_and_b64 vcc, exec, s[6:7]
	s_waitcnt vmcnt(7)
	ds_write_b128 v162, v[44:47]
	s_waitcnt vmcnt(6)
	ds_write_b128 v162, v[40:43] offset:8704
	s_waitcnt vmcnt(5)
	ds_write_b128 v162, v[36:39] offset:17408
	s_waitcnt vmcnt(4)
	ds_write_b128 v162, v[32:35] offset:26112
	s_waitcnt vmcnt(3)
	ds_write_b128 v162, v[28:31] offset:34816
	s_waitcnt vmcnt(2)
	ds_write_b128 v162, v[24:27] offset:43520
	s_waitcnt vmcnt(1)
	ds_write_b128 v162, v[16:19] offset:52224
	s_waitcnt vmcnt(0)
	ds_write_b128 v162, v[20:23] offset:60928
	s_waitcnt lgkmcnt(0)
	s_barrier
	s_cbranch_vccnz .LBB0_231
	global_load_dwordx4 v[4:7], v[114:115], off offset:512
	global_load_dwordx4 v[0:3], v[114:115], off offset:576
	global_load_dwordx4 v[8:11], v[114:115], off offset:640
	global_load_dwordx4 v[12:15], v[114:115], off offset:704

; #define LAS __attribute__((address_space(3)))
; #define SCHED_FENCE() __builtin_amdgcn_sched_barrier(0)
; __device__ __forceinline__ f32x4 mfma16(bf16x8 a, bf16x8 b, f32x4 c) { return __builtin_amdgcn_mfma_f32_16x16x32_bf16(a, b, c, 0, 0, 0); }
; #define A2_WRITEK(buf_) do { _Pragma("unroll") for (int j = 0; j < 8; ++j) *(LAS u32x4*)((buf_) + klo + j * (16 * 272)) = t8[j]; } while (0)
; #define A2_WRITEV(buf_) do { _Pragma("unroll") for (int j = 0; j < 8; ++j) *(LAS u32x4*)((buf_) + vlo + j * (32 * 272)) = t8[j]; } while (0)
; template <bool NA> ...
;     ...
;             for (int g = 0; g < NGRP; ++g) {
;                 const int gi = vs * NGRP + g, voff = NA ? g * 64 + w0 : g * 32;
;                 const LAS unsigned char* vp = cur + (hh * 128 + fr) * 272 + (voff + fq * 4) * 2;
; #pragma unroll
;                 for (int d = 0; d < 8; ++d) {
;                     const u32x2 lo = *(const LAS u32x2*)(vp + d * 16 * 272), hi = *(const LAS u32x2*)(vp + d * 16 * 272 + 32);
;                     u32x4 vw; vw.x = lo.x; vw.y = lo.y; vw.z = hi.x; vw.w = hi.y;
;                     o[d] = mfma16(__builtin_bit_cast(bf16x8, vw), pb[gi], o[d]);
;                 }
;             }
;             SCHED_FENCE();
;             if (vs < NSTEP - 1) A2_WRITEV(nxt); else if (hp < NHP - 1) A2_WRITEK(nxt);
.LBB0_233:
	ds_read_b64 v[240:241], v163
	ds_read_b64 v[242:243], v164
	ds_read_b64 v[244:245], v165
	ds_read_b64 v[246:247], v166
	s_waitcnt lgkmcnt(2)
	v_mfma_f32_16x16x32_bf16 v[92:95], v[240:243], v[56:59], v[92:95]
	ds_read_b64 v[240:241], v167
	ds_read_b64 v[242:243], v168
	s_waitcnt lgkmcnt(2)
	v_mfma_f32_16x16x32_bf16 v[88:91], v[244:247], v[56:59], v[88:91]
	ds_read_b64 v[244:245], v169
	ds_read_b64 v[246:247], v170
	s_waitcnt lgkmcnt(2)
	v_mfma_f32_16x16x32_bf16 v[84:87], v[240:243], v[56:59], v[84:87]
	ds_read_b64 v[240:241], v171
	ds_read_b64 v[242:243], v172
	s_waitcnt lgkmcnt(2)
	v_mfma_f32_16x16x32_bf16 v[80:83], v[244:247], v[56:59], v[80:83]
	ds_read_b64 v[244:245], v173
	ds_read_b64 v[246:247], v174
	s_waitcnt lgkmcnt(2)
	v_mfma_f32_16x16x32_bf16 v[76:79], v[240:243], v[56:59], v[76:79]
	ds_read_b64 v[240:241], v175
	ds_read_b64 v[242:243], v176
	s_waitcnt lgkmcnt(2)
	v_mfma_f32_16x16x32_bf16 v[72:75], v[244:247], v[56:59], v[72:75]
	s_waitcnt lgkmcnt(0)
	v_mfma_f32_16x16x32_bf16 v[68:71], v[240:243], v[56:59], v[68:71]
	ds_read_b64 v[98:99], v177
	ds_read_b64 v[100:101], v178
	s_waitcnt lgkmcnt(0)
	v_mfma_f32_16x16x32_bf16 v[56:59], v[98:101], v[56:59], v[64:67]
	s_nop 2
	ds_read_b64 v[240:241], v179
	ds_read_b64 v[242:243], v180
	ds_read_b64 v[244:245], v181
	ds_read_b64 v[246:247], v182
	s_waitcnt lgkmcnt(2)
	v_mfma_f32_16x16x32_bf16 v[64:67], v[240:243], v[60:63], v[92:95]
	ds_read_b64 v[240:241], v183
	ds_read_b64 v[242:243], v184
	s_waitcnt lgkmcnt(2)
	v_mfma_f32_16x16x32_bf16 v[88:91], v[244:247], v[60:63], v[88:91]
	ds_read_b64 v[244:245], v185
	ds_read_b64 v[246:247], v186
	s_waitcnt lgkmcnt(2)
	v_mfma_f32_16x16x32_bf16 v[84:87], v[240:243], v[60:63], v[84:87]
	ds_read_b64 v[240:241], v187
	ds_read_b64 v[242:243], v188
	s_waitcnt lgkmcnt(2)
	v_mfma_f32_16x16x32_bf16 v[80:83], v[244:247], v[60:63], v[80:83]
	ds_read_b64 v[244:245], v189
	ds_read_b64 v[246:247], v190
	s_waitcnt lgkmcnt(2)
	v_mfma_f32_16x16x32_bf16 v[76:79], v[240:243], v[60:63], v[76:79]
	ds_read_b64 v[240:241], v191
	ds_read_b64 v[242:243], v192
	s_waitcnt lgkmcnt(2)
	v_mfma_f32_16x16x32_bf16 v[72:75], v[244:247], v[60:63], v[72:75]
	ds_read_b64 v[244:245], v193
	ds_read_b64 v[246:247], v194
	s_waitcnt lgkmcnt(2)
	v_mfma_f32_16x16x32_bf16 v[68:71], v[240:243], v[60:63], v[68:71]
	ds_read_b64 v[240:241], v195
	ds_read_b64 v[242:243], v196
	s_waitcnt lgkmcnt(2)
	v_mfma_f32_16x16x32_bf16 v[56:59], v[244:247], v[60:63], v[56:59]
	ds_read_b64 v[244:245], v197
	ds_read_b64 v[246:247], v198
	s_waitcnt lgkmcnt(2)
	v_mfma_f32_16x16x32_bf16 v[60:63], v[240:243], v[52:55], v[64:67]
	ds_read_b64 v[240:241], v199
	ds_read_b64 v[242:243], v200
	s_waitcnt lgkmcnt(2)
	v_mfma_f32_16x16x32_bf16 v[64:67], v[244:247], v[52:55], v[88:91]
	ds_read_b64 v[244:245], v201
	ds_read_b64 v[246:247], v202
	s_waitcnt lgkmcnt(2)
	v_mfma_f32_16x16x32_bf16 v[84:87], v[240:243], v[52:55], v[84:87]
	ds_read_b64 v[240:241], v203
	ds_read_b64 v[242:243], v204
	s_waitcnt lgkmcnt(2)
	v_mfma_f32_16x16x32_bf16 v[80:83], v[244:247], v[52:55], v[80:83]
	ds_read_b64 v[244:245], v205
	ds_read_b64 v[246:247], v206
	s_waitcnt lgkmcnt(2)
	v_mfma_f32_16x16x32_bf16 v[76:79], v[240:243], v[52:55], v[76:79]
	ds_read_b64 v[240:241], v207
	ds_read_b64 v[242:243], v208
	s_waitcnt lgkmcnt(2)
	v_mfma_f32_16x16x32_bf16 v[72:75], v[244:247], v[52:55], v[72:75]
	ds_read_b64 v[244:245], v209
	ds_read_b64 v[246:247], v210
	s_waitcnt lgkmcnt(2)
	v_mfma_f32_16x16x32_bf16 v[88:91], v[240:243], v[52:55], v[68:71]
	s_waitcnt lgkmcnt(0)
	v_mfma_f32_16x16x32_bf16 v[92:95], v[244:247], v[52:55], v[56:59]
	ds_read_b64 v[52:53], v211
	ds_read_b64 v[54:55], v218
	s_nop 0
	ds_read_b64 v[56:57], v219
	ds_read_b64 v[58:59], v220
	s_waitcnt lgkmcnt(2)
	v_mfma_f32_16x16x32_bf16 v[52:55], v[52:55], v[48:51], v[60:63]
	s_nop 2
	ds_read_b64 v[60:61], v221
	ds_read_b64 v[62:63], v222
	s_waitcnt lgkmcnt(2)
	v_mfma_f32_16x16x32_bf16 v[56:59], v[56:59], v[48:51], v[64:67]
	s_nop 2
	ds_read_b64 v[64:65], v223
	ds_read_b64 v[66:67], v224
	ds_read_b64 v[68:69], v225
	ds_read_b64 v[70:71], v226
	s_waitcnt lgkmcnt(0)
	v_mfma_f32_16x16x32_bf16 v[68:71], v[68:71], v[48:51], v[76:79]
	s_nop 2
	ds_read_b64 v[76:77], v227
	ds_read_b64 v[78:79], v228
	v_mfma_f32_16x16x32_bf16 v[64:67], v[64:67], v[48:51], v[80:83]
	s_waitcnt lgkmcnt(0)
	v_mfma_f32_16x16x32_bf16 v[72:75], v[76:79], v[48:51], v[72:75]
	ds_read_b64 v[76:77], v229
	ds_read_b64 v[78:79], v230
	ds_read_b64 v[80:81], v231
	ds_read_b64 v[82:83], v232
	v_mfma_f32_16x16x32_bf16 v[60:63], v[60:63], v[48:51], v[84:87]
	s_waitcnt lgkmcnt(2)
	v_mfma_f32_16x16x32_bf16 v[76:79], v[76:79], v[48:51], v[88:91]
	s_waitcnt lgkmcnt(0)
	v_mfma_f32_16x16x32_bf16 v[48:51], v[80:83], v[48:51], v[92:95]
	s_and_b64 vcc, exec, s[38:39]
	s_cbranch_vccnz .LBB0_228
	s_waitcnt vmcnt(7)
	ds_write_b128 v154, v[44:47]
	s_waitcnt vmcnt(6)
	ds_write_b128 v154, v[40:43] offset:4352
	s_waitcnt vmcnt(5)
	ds_write_b128 v154, v[36:39] offset:8704
	s_waitcnt vmcnt(4)
	ds_write_b128 v154, v[32:35] offset:13056
	s_waitcnt vmcnt(3)
	ds_write_b128 v154, v[28:31] offset:17408
	s_waitcnt vmcnt(2)
	ds_write_b128 v154, v[24:27] offset:21760
	s_waitcnt vmcnt(1)
	ds_write_b128 v154, v[16:19] offset:26112
	s_waitcnt vmcnt(0)
	ds_write_b128 v154, v[20:23] offset:30464
	s_branch .LBB0_228
